# EpiWin epilogue: after the matching per-column-class block, branch directly past the chain of skip tests (144 sites)
# speedup vs baseline: 1.0042x; 1.0042x over previous
.LBB0_536:
	v_mov_b32_e32 v96, v189
	v_mov_b32_e32 v145, v188
	v_and_b32_e32 v171, 64, v225
	v_add_u32_e32 v96, s67, v96
	v_lshlrev_b32_e32 v144, 4, v145
	s_add_i32 s1, 0, 0x21000
	v_lshlrev_b32_e32 v146, 6, v96
	v_xor_b32_e32 v170, 16, v225
	v_add_u32_e32 v172, 64, v171
	s_waitcnt vmcnt(16)
	s_barrier
	v_add3_u32 v144, s1, v144, v146
	v_cmp_lt_i32_e32 vcc, v170, v172
	ds_read_b128 v[146:149], v144
	ds_read_b128 v[150:153], v144 offset:1024
	ds_read_b128 v[154:157], v144 offset:2048
	ds_read_b128 v[158:161], v144 offset:3072
	ds_read_b128 v[162:165], v144 offset:8192
	ds_read_b128 v[166:169], v144 offset:9216
	v_cndmask_b32_e32 v170, v225, v170, vcc
	v_lshlrev_b32_e32 v192, 2, v170
	s_waitcnt lgkmcnt(0)
	v_mov_b32_e32 v170, v147
	v_mov_b32_e32 v171, v148
	v_mov_b32_e32 v147, v149
	v_pk_add_f32 v[146:147], v[170:171], v[146:147]
	v_xor_b32_e32 v148, 32, v225
	v_add_f32_e32 v146, v146, v147
	ds_bpermute_b32 v147, v192, v146
	v_cmp_lt_i32_e32 vcc, v148, v172
	s_lshl_b32 s94, s93, 1
	v_readlane_b32 s1, v249, 47
	v_cndmask_b32_e32 v148, v225, v148, vcc
	v_lshlrev_b32_e32 v193, 2, v148
	s_waitcnt lgkmcnt(0)
	v_add_f32_e32 v170, v146, v147
	ds_bpermute_b32 v171, v193, v170
	v_add_f32_e32 v146, v150, v151
	v_add_f32_e32 v147, v152, v153
	v_add_f32_e32 v172, v146, v147
	ds_read_b128 v[146:149], v144 offset:10240
	ds_read_b128 v[150:153], v144 offset:11264
	s_waitcnt lgkmcnt(0)
	v_add_f32_e32 v144, v170, v171
	v_fmamk_f32 v144, v144, 0x3a800000, v226
	v_rsq_f32_e32 v170, v144
	v_add_f32_e32 v144, v154, v155
	v_add_f32_e32 v154, v156, v157
	v_add_f32_e32 v144, v144, v154
	ds_bpermute_b32 v154, v192, v144
	v_add_f32_e32 v155, v158, v159
	v_add_f32_e32 v156, v160, v161
	v_add_f32_e32 v157, v162, v163
	v_add_f32_e32 v158, v164, v165
	s_waitcnt lgkmcnt(0)
	v_add_f32_e32 v206, v144, v154
	v_add_f32_e32 v144, v166, v167
	v_add_f32_e32 v154, v168, v169
	v_add_f32_e32 v146, v146, v147
	v_add_f32_e32 v147, v148, v149
	v_add_f32_e32 v148, v150, v151
	v_add_f32_e32 v149, v152, v153
	v_add_f32_e32 v155, v155, v156
	v_add_f32_e32 v157, v157, v158
	v_add_f32_e32 v144, v144, v154
	v_add_f32_e32 v146, v146, v147
	v_add_f32_e32 v148, v148, v149
	ds_bpermute_b32 v173, v192, v172
	ds_bpermute_b32 v156, v192, v155
	ds_bpermute_b32 v158, v192, v157
	ds_bpermute_b32 v154, v192, v144
	ds_bpermute_b32 v147, v192, v146
	ds_bpermute_b32 v149, v192, v148
	s_waitcnt lgkmcnt(0)
	v_add_f32_e32 v208, v172, v173
	v_add_f32_e32 v204, v155, v156
	v_add_f32_e32 v202, v157, v158
	v_add_f32_e32 v200, v144, v154
	v_add_f32_e32 v198, v146, v147
	v_add_f32_e32 v196, v148, v149
	ds_bpermute_b32 v209, v193, v208
	ds_bpermute_b32 v207, v193, v206
	ds_bpermute_b32 v205, v193, v204
	ds_bpermute_b32 v203, v193, v202
	ds_bpermute_b32 v201, v193, v200
	ds_bpermute_b32 v199, v193, v198
	ds_bpermute_b32 v197, v193, v196
	v_lshl_add_u32 v148, s10, 8, v96
	v_lshlrev_b32_e32 v144, 3, v145
	v_ashrrev_i32_e32 v149, 31, v148
	s_cmp_gt_i32 s93, 2
	v_add_u32_e32 v146, s1, v144
	v_lshlrev_b64 v[152:153], 11, v[148:149]
	v_lshlrev_b64 v[156:157], 10, v[148:149]
	s_cselect_b64 s[12:13], -1, 0
	v_add_u32_e32 v195, 0xfffff300, v146
	v_ashrrev_i32_e32 v147, 31, v146
	v_add_u32_e32 v194, 0xfffffb00, v146
	v_cmp_eq_u32_e64 s[8:9], 0, v145
	v_lshl_add_u64 v[172:173], s[50:51], 0, v[152:153]
	v_lshl_add_u64 v[150:151], s[72:73], 0, v[156:157]
	v_lshl_add_u64 v[154:155], s[52:53], 0, v[152:153]
	v_lshl_add_u64 v[152:153], s[96:97], 0, v[156:157]
	v_pk_mul_f32 v[164:165], v[126:127], v[170:171] op_sel_hi:[1,0]
	v_pk_mul_f32 v[166:167], v[128:129], v[170:171] op_sel_hi:[1,0]
	v_pk_mul_f32 v[168:169], v[122:123], v[170:171] op_sel_hi:[1,0]
	v_pk_mul_f32 v[176:177], v[124:125], v[170:171] op_sel_hi:[1,0]
	s_mov_b64 s[10:11], -1
	s_and_b64 vcc, exec, s[12:13]
	s_cbranch_vccz .LBB0_558
	s_cmp_gt_u32 s94, 9
	s_cbranch_scc0 .LBB0_555
	s_cmp_gt_u32 s94, 13
	s_cbranch_scc0 .LBB0_552
	s_cmp_gt_u32 s94, 17
	s_cbranch_scc0 .LBB0_549
	s_cmp_gt_u32 s94, 21
	s_cbranch_scc0 .LBB0_546
	s_cmp_gt_u32 s94, 25
	s_cbranch_scc0 .LBB0_543
	v_mul_f32_e32 v122, 0xbfb8aa3b, v164
	v_mul_f32_e32 v123, 0xbfb8aa3b, v165
	v_mul_f32_e32 v124, 0xbfb8aa3b, v166
	v_mul_f32_e32 v125, 0xbfb8aa3b, v167
	v_mul_f32_e32 v127, 0xbfb8aa3b, v168
	v_mul_f32_e32 v128, 0xbfb8aa3b, v169
	v_exp_f32_e32 v122, v122
	v_exp_f32_e32 v123, v123
	v_exp_f32_e32 v124, v124
	v_exp_f32_e32 v125, v125
	v_exp_f32_e32 v127, v127
	v_exp_f32_e32 v128, v128
	v_mul_f32_e32 v129, 0xbfb8aa3b, v176
	v_mul_f32_e32 v156, 0xbfb8aa3b, v177
	v_exp_f32_e32 v129, v129
	v_exp_f32_e32 v156, v156
	v_add_f32_e32 v122, 1.0, v122
	v_add_f32_e32 v123, 1.0, v123
	v_add_f32_e32 v124, 1.0, v124
	v_add_f32_e32 v125, 1.0, v125
	v_add_f32_e32 v127, 1.0, v127
	v_add_f32_e32 v128, 1.0, v128
	v_rcp_f32_e32 v122, v122
	v_rcp_f32_e32 v123, v123
	v_rcp_f32_e32 v124, v124
	v_rcp_f32_e32 v125, v125
	v_rcp_f32_e32 v127, v127
	v_rcp_f32_e32 v128, v128
	v_lshl_add_u32 v96, s93, 8, v195
	v_add_f32_e32 v129, 1.0, v129
	v_add_f32_e32 v156, 1.0, v156
	v_ashrrev_i32_e32 v126, 10, v96
	v_rcp_f32_e32 v129, v129
	v_rcp_f32_e32 v156, v156
	v_cvt_pk_bf16_f32 v122, v122, v123
	v_cvt_pk_bf16_f32 v123, v124, v125
	v_cvt_pk_bf16_f32 v124, v127, v128
	v_ashrrev_i32_e32 v127, 31, v126
	v_and_b32_e32 v96, 0x3f8, v96
	v_lshlrev_b64 v[126:127], 25, v[126:127]
	v_lshl_add_u64 v[126:127], v[172:173], 0, v[126:127]
	v_lshlrev_b32_e32 v96, 1, v96
	v_cvt_pk_bf16_f32 v125, v129, v156
	v_lshl_add_u64 v[126:127], v[126:127], 0, v[96:97]
	global_store_dwordx4 v[126:127], v[122:125], off
	s_mov_b64 s[10:11], 0
	s_mov_b64 s[10:11], 0
	s_branch .LBB0_558
.LBB0_543:
	s_andn2_b64 vcc, exec, s[10:11]
	s_cbranch_vccnz .LBB0_545
	s_mov_b32 s10, 0x3e0293ee
	v_pk_mul_f32 v[122:123], v[164:165], s[10:11] op_sel_hi:[1,0]
	v_pk_mul_f32 v[124:125], v[166:167], s[10:11] op_sel_hi:[1,0]
	v_pk_mul_f32 v[126:127], v[168:169], s[10:11] op_sel_hi:[1,0]
	s_lshl_b32 s48, s93, 8
	v_cvt_pk_bf16_f32 v122, v122, v123
	v_cvt_pk_bf16_f32 v123, v124, v125
	v_cvt_pk_bf16_f32 v124, v126, v127
	v_lshl_add_u64 v[126:127], s[48:49], 1, v[150:151]
	v_lshl_add_u64 v[126:127], v[146:147], 1, v[126:127]
	v_pk_mul_f32 v[128:129], v[176:177], s[10:11] op_sel_hi:[1,0]
	v_add_co_u32_e32 v126, vcc, 0xe11e000, v126
	v_cvt_pk_bf16_f32 v125, v128, v129
	s_nop 0
	v_addc_co_u32_e32 v127, vcc, 0, v127, vcc
	global_store_dwordx4 v[126:127], v[122:125], off offset:2560
	s_mov_b64 s[10:11], 0
	s_branch .LBB0_558
.LBB0_545:
	s_mov_b64 s[10:11], 0
	s_mov_b64 s[10:11], 0
	s_branch .LBB0_558
.LBB0_546:
	s_andn2_b64 vcc, exec, s[10:11]
	s_cbranch_vccnz .LBB0_548
	v_mul_f32_e32 v96, 0xbfb8aa3b, v164
	v_exp_f32_e32 v96, v96
	v_mul_f32_e32 v122, 0xbfb8aa3b, v165
	v_exp_f32_e32 v122, v122
	v_mul_f32_e32 v124, 0xbfb8aa3b, v167
	v_add_f32_e32 v96, 1.0, v96
	v_exp_f32_e32 v125, v124
	v_add_f32_e32 v123, 1.0, v122
	v_rcp_f32_e32 v122, v96
	v_mul_f32_e32 v96, 0xbfb8aa3b, v166
	v_exp_f32_e32 v96, v96
	v_rcp_f32_e32 v123, v123
	s_lshl_b32 s48, s93, 8
	v_add_f32_e32 v96, 1.0, v96
	v_rcp_f32_e32 v124, v96
	v_add_f32_e32 v96, 1.0, v125
	v_mul_f32_e32 v125, 0xbfb8aa3b, v168
	v_exp_f32_e32 v126, v125
	v_mul_f32_e32 v125, 0xbfb8aa3b, v169
	v_exp_f32_e32 v127, v125
	v_rcp_f32_e32 v125, v96
	v_add_f32_e32 v96, 1.0, v126
	v_rcp_f32_e32 v126, v96
	v_add_f32_e32 v96, 1.0, v127
	v_mul_f32_e32 v127, 0xbfb8aa3b, v176
	v_exp_f32_e32 v128, v127
	v_mul_f32_e32 v127, 0xbfb8aa3b, v177
	v_exp_f32_e32 v129, v127
	v_rcp_f32_e32 v127, v96
	v_add_f32_e32 v96, 1.0, v128
	v_rcp_f32_e32 v128, v96
	v_add_f32_e32 v96, 1.0, v129
	v_rcp_f32_e32 v129, v96
	v_pk_mul_f32 v[122:123], v[164:165], v[122:123]
	v_pk_mul_f32 v[124:125], v[166:167], v[124:125]
	v_pk_mul_f32 v[126:127], v[168:169], v[126:127]
	v_cvt_pk_bf16_f32 v122, v122, v123
	v_cvt_pk_bf16_f32 v123, v124, v125
	v_cvt_pk_bf16_f32 v124, v126, v127
	v_lshl_add_u64 v[126:127], s[48:49], 1, v[150:151]
	v_lshl_add_u64 v[126:127], v[146:147], 1, v[126:127]
	v_pk_mul_f32 v[128:129], v[176:177], v[128:129]
	v_add_co_u32_e32 v126, vcc, 0xd11e000, v126
	v_cvt_pk_bf16_f32 v125, v128, v129
	s_nop 0
	v_addc_co_u32_e32 v127, vcc, 0, v127, vcc
	global_store_dwordx4 v[126:127], v[122:125], off offset:3584
	s_mov_b64 s[10:11], 0
	s_branch .LBB0_558

.LBB0_549:
	s_andn2_b64 vcc, exec, s[10:11]
	s_cbranch_vccnz .LBB0_551
	s_lshl_b32 s48, s93, 8
	v_lshl_add_u64 v[126:127], s[48:49], 1, v[150:151]
	v_lshl_add_u64 v[126:127], v[146:147], 1, v[126:127]
	v_add_co_u32_e32 v126, vcc, 0xc11f000, v126
	v_cvt_pk_bf16_f32 v122, v164, v165
	v_cvt_pk_bf16_f32 v123, v166, v167
	v_cvt_pk_bf16_f32 v124, v168, v169
	v_cvt_pk_bf16_f32 v125, v176, v177
	v_addc_co_u32_e32 v127, vcc, 0, v127, vcc
	global_store_dwordx4 v[126:127], v[122:125], off offset:512
	s_mov_b64 s[10:11], 0
	s_branch .LBB0_558

.LBB0_567:
	v_lshlrev_b32_e32 v122, 2, v145
	v_ashrrev_i32_e32 v123, 31, v122
	v_readlane_b32 s10, v249, 62
	v_lshlrev_b64 v[122:123], 2, v[122:123]
	v_readlane_b32 s11, v249, 63
	s_or_b32 s95, s94, 1
	v_mov_b32_e32 v171, v170
	v_lshl_add_u64 v[124:125], s[10:11], 0, v[122:123]
	v_readlane_b32 s10, v248, 0
	v_readlane_b32 s11, v248, 1
	s_cmp_gt_i32 s95, 4
	v_ashrrev_i32_e32 v145, 31, v144
	v_lshl_add_u64 v[122:123], s[10:11], 0, v[122:123]
	v_pk_mul_f32 v[164:165], v[118:119], v[170:171]
	v_pk_mul_f32 v[166:167], v[120:121], v[170:171]
	v_pk_mul_f32 v[168:169], v[114:115], v[170:171]
	v_pk_mul_f32 v[170:171], v[116:117], v[170:171]
	s_cselect_b64 s[14:15], -1, 0
	s_cmp_lt_i32 s95, 5
	s_mov_b64 s[10:11], -1
	s_cbranch_scc1 .LBB0_594
	s_cmp_eq_u32 s93, 2
	s_cbranch_scc1 .LBB0_590
	s_cmp_lt_u32 s94, 10
	s_cbranch_scc1 .LBB0_587
	s_cmp_lt_u32 s94, 14
	s_cbranch_scc1 .LBB0_584
	s_cmp_lt_u32 s94, 18
	s_cbranch_scc1 .LBB0_581
	s_cmp_lt_u32 s94, 22
	s_cbranch_scc1 .LBB0_578
	s_cmp_lt_u32 s94, 26
	s_cbranch_scc1 .LBB0_575
	v_mul_f32_e32 v114, 0xbfb8aa3b, v164
	v_mul_f32_e32 v115, 0xbfb8aa3b, v165
	v_mul_f32_e32 v116, 0xbfb8aa3b, v166
	v_mul_f32_e32 v117, 0xbfb8aa3b, v167
	v_mul_f32_e32 v119, 0xbfb8aa3b, v168
	v_mul_f32_e32 v120, 0xbfb8aa3b, v169
	v_exp_f32_e32 v114, v114
	v_exp_f32_e32 v115, v115
	v_exp_f32_e32 v116, v116
	v_exp_f32_e32 v117, v117
	v_exp_f32_e32 v119, v119
	v_exp_f32_e32 v120, v120
	v_mul_f32_e32 v121, 0xbfb8aa3b, v170
	v_mul_f32_e32 v149, 0xbfb8aa3b, v171
	v_exp_f32_e32 v121, v121
	v_exp_f32_e32 v149, v149
	v_add_f32_e32 v114, 1.0, v114
	v_add_f32_e32 v115, 1.0, v115
	v_add_f32_e32 v116, 1.0, v116
	v_add_f32_e32 v117, 1.0, v117
	v_add_f32_e32 v119, 1.0, v119
	v_add_f32_e32 v120, 1.0, v120
	v_rcp_f32_e32 v114, v114
	v_rcp_f32_e32 v115, v115
	v_rcp_f32_e32 v116, v116
	v_rcp_f32_e32 v117, v117
	v_rcp_f32_e32 v119, v119
	v_rcp_f32_e32 v120, v120
	v_lshl_add_u32 v96, s95, 7, v195
	v_add_f32_e32 v121, 1.0, v121
	v_add_f32_e32 v149, 1.0, v149
	v_ashrrev_i32_e32 v118, 10, v96
	v_rcp_f32_e32 v121, v121
	v_rcp_f32_e32 v149, v149
	v_cvt_pk_bf16_f32 v114, v114, v115
	v_cvt_pk_bf16_f32 v115, v116, v117
	v_cvt_pk_bf16_f32 v116, v119, v120
	v_ashrrev_i32_e32 v119, 31, v118
	v_and_b32_e32 v96, 0x3f8, v96
	v_lshlrev_b64 v[118:119], 25, v[118:119]
	v_lshl_add_u64 v[118:119], v[172:173], 0, v[118:119]
	v_lshlrev_b32_e32 v96, 1, v96
	v_cvt_pk_bf16_f32 v117, v121, v149
	v_lshl_add_u64 v[118:119], v[118:119], 0, v[96:97]
	s_mov_b64 s[10:11], 0
	global_store_dwordx4 v[118:119], v[114:117], off
	s_mov_b64 s[10:11], 0
	s_branch .LBB0_603
.LBB0_575:
	s_andn2_b64 vcc, exec, s[10:11]
	s_cbranch_vccnz .LBB0_577
	s_mov_b32 s10, 0x3e0293ee
	v_pk_mul_f32 v[114:115], v[164:165], s[10:11] op_sel_hi:[1,0]
	v_pk_mul_f32 v[116:117], v[166:167], s[10:11] op_sel_hi:[1,0]
	v_pk_mul_f32 v[118:119], v[168:169], s[10:11] op_sel_hi:[1,0]
	s_lshl_b32 s48, s95, 8
	v_cvt_pk_bf16_f32 v114, v114, v115
	v_cvt_pk_bf16_f32 v115, v116, v117
	v_cvt_pk_bf16_f32 v116, v118, v119
	v_lshl_add_u64 v[118:119], v[150:151], 0, s[48:49]
	v_lshl_add_u64 v[118:119], v[146:147], 1, v[118:119]
	v_pk_mul_f32 v[120:121], v[170:171], s[10:11] op_sel_hi:[1,0]
	v_add_co_u32_e32 v118, vcc, 0xe11e000, v118
	v_cvt_pk_bf16_f32 v117, v120, v121
	s_nop 0
	v_addc_co_u32_e32 v119, vcc, 0, v119, vcc
	global_store_dwordx4 v[118:119], v[114:117], off offset:2560
	s_mov_b64 s[10:11], 0
	s_branch .LBB0_603

.LBB0_578:
	s_andn2_b64 vcc, exec, s[10:11]
	s_cbranch_vccnz .LBB0_580
	v_mul_f32_e32 v96, 0xbfb8aa3b, v164
	v_exp_f32_e32 v96, v96
	v_mul_f32_e32 v114, 0xbfb8aa3b, v165
	v_exp_f32_e32 v114, v114
	v_mul_f32_e32 v116, 0xbfb8aa3b, v167
	v_add_f32_e32 v96, 1.0, v96
	v_exp_f32_e32 v117, v116
	v_add_f32_e32 v115, 1.0, v114
	v_rcp_f32_e32 v114, v96
	v_mul_f32_e32 v96, 0xbfb8aa3b, v166
	v_exp_f32_e32 v96, v96
	v_rcp_f32_e32 v115, v115
	s_lshl_b32 s48, s95, 8
	v_add_f32_e32 v96, 1.0, v96
	v_rcp_f32_e32 v116, v96
	v_add_f32_e32 v96, 1.0, v117
	v_mul_f32_e32 v117, 0xbfb8aa3b, v168
	v_exp_f32_e32 v118, v117
	v_mul_f32_e32 v117, 0xbfb8aa3b, v169
	v_exp_f32_e32 v119, v117
	v_rcp_f32_e32 v117, v96
	v_add_f32_e32 v96, 1.0, v118
	v_rcp_f32_e32 v118, v96
	v_add_f32_e32 v96, 1.0, v119
	v_mul_f32_e32 v119, 0xbfb8aa3b, v170
	v_exp_f32_e32 v120, v119
	v_mul_f32_e32 v119, 0xbfb8aa3b, v171
	v_exp_f32_e32 v121, v119
	v_rcp_f32_e32 v119, v96
	v_add_f32_e32 v96, 1.0, v120
	v_rcp_f32_e32 v120, v96
	v_add_f32_e32 v96, 1.0, v121
	v_rcp_f32_e32 v121, v96
	v_pk_mul_f32 v[114:115], v[164:165], v[114:115]
	v_pk_mul_f32 v[116:117], v[166:167], v[116:117]
	v_pk_mul_f32 v[118:119], v[168:169], v[118:119]
	v_cvt_pk_bf16_f32 v114, v114, v115
	v_cvt_pk_bf16_f32 v115, v116, v117
	v_cvt_pk_bf16_f32 v116, v118, v119
	v_lshl_add_u64 v[118:119], v[150:151], 0, s[48:49]
	v_lshl_add_u64 v[118:119], v[146:147], 1, v[118:119]
	v_pk_mul_f32 v[120:121], v[170:171], v[120:121]
	v_add_co_u32_e32 v118, vcc, 0xd11e000, v118
	v_cvt_pk_bf16_f32 v117, v120, v121
	s_nop 0
	v_addc_co_u32_e32 v119, vcc, 0, v119, vcc
	global_store_dwordx4 v[118:119], v[114:117], off offset:3584
	s_mov_b64 s[10:11], 0
	s_branch .LBB0_603

.LBB0_581:
	s_andn2_b64 vcc, exec, s[10:11]
	s_cbranch_vccnz .LBB0_583
	s_lshl_b32 s48, s95, 8
	v_lshl_add_u64 v[118:119], v[150:151], 0, s[48:49]
	v_lshl_add_u64 v[118:119], v[146:147], 1, v[118:119]
	v_add_co_u32_e32 v118, vcc, 0xc11f000, v118
	v_cvt_pk_bf16_f32 v114, v164, v165
	v_cvt_pk_bf16_f32 v115, v166, v167
	v_cvt_pk_bf16_f32 v116, v168, v169
	v_cvt_pk_bf16_f32 v117, v170, v171
	v_addc_co_u32_e32 v119, vcc, 0, v119, vcc
	global_store_dwordx4 v[118:119], v[114:117], off offset:512
	s_mov_b64 s[10:11], 0
	s_branch .LBB0_603

.LBB0_584:
	s_andn2_b64 vcc, exec, s[10:11]
	s_cbranch_vccnz .LBB0_586
	v_lshl_add_u32 v172, s95, 7, v194
	v_ashrrev_i32_e32 v173, 31, v172
	v_lshlrev_b64 v[176:177], 2, v[172:173]
	v_lshl_add_u64 v[118:119], s[80:81], 0, v[176:177]
	global_load_dwordx4 v[114:117], v[118:119], off offset:16
	s_nop 0
	global_load_dwordx4 v[118:121], v[118:119], off
	v_max_f32_e32 v96, v164, v164
	s_mov_b32 s17, 0xc2700000
	v_med3_f32 v96, v96, s17, v231
	v_mul_f32_e32 v96, 0xbfb8aa3b, v96
	v_exp_f32_e32 v178, v96
	s_mov_b32 s1, 0x3f317217
	v_lshl_add_u64 v[154:155], v[154:155], 0, v[176:177]
	v_add_f32_e32 v96, 1.0, v178
	v_rcp_f32_e32 v180, v96
	v_max_f32_e32 v96, v165, v165
	v_med3_f32 v96, v96, s17, v231
	v_mul_f32_e32 v96, 0xbfb8aa3b, v96
	v_exp_f32_e32 v179, v96
	s_waitcnt vmcnt(0)
	v_pk_add_f32 v[186:187], v[114:115], 1.0 op_sel_hi:[1,0] neg_lo:[1,0] neg_hi:[1,0]
	v_add_f32_e32 v96, 1.0, v179
	v_pk_add_f32 v[182:183], v[118:119], 1.0 op_sel_hi:[1,0] neg_lo:[1,0] neg_hi:[1,0]
	v_rcp_f32_e32 v181, v96
	v_fma_f32 v96, v180, v182, v118
	v_cmp_gt_f32_e32 vcc, s16, v96
	v_pk_add_f32 v[184:185], v[120:121], 1.0 op_sel_hi:[1,0] neg_lo:[1,0] neg_hi:[1,0]
	v_pk_mul_f32 v[178:179], v[178:179], v[180:181]
	v_cndmask_b32_e64 v118, 0, 32, vcc
	v_ldexp_f32 v96, v96, v118
	v_log_f32_e32 v96, v96
	v_pk_mul_f32 v[178:179], v[178:179], v[182:183]
	v_pk_add_f32 v[210:211], v[116:117], 1.0 op_sel_hi:[1,0] neg_lo:[1,0] neg_hi:[1,0]
	v_mul_f32_e32 v118, 0x3f317217, v96
	v_fma_f32 v118, v96, s1, -v118
	v_fmac_f32_e32 v118, 0x3377d1cf, v96
	v_fmac_f32_e32 v118, 0x3f317217, v96
	v_cmp_lt_f32_e64 s[10:11], |v96|, s4
	s_nop 1
	v_cndmask_b32_e64 v96, v96, v118, s[10:11]
	v_cndmask_b32_e32 v118, 0, v232, vcc
	v_sub_f32_e32 v118, v96, v118
	v_fma_f32 v96, v181, v183, v119
	v_cmp_gt_f32_e32 vcc, s16, v96
	s_nop 1
	v_cndmask_b32_e64 v119, 0, 32, vcc
	v_ldexp_f32 v96, v96, v119
	v_log_f32_e32 v96, v96
	s_nop 0
	v_mul_f32_e32 v119, 0x3f317217, v96
	v_fma_f32 v119, v96, s1, -v119
	v_fmac_f32_e32 v119, 0x3377d1cf, v96
	v_fmac_f32_e32 v119, 0x3f317217, v96
	v_cmp_lt_f32_e64 s[10:11], |v96|, s4
	s_nop 1
	v_cndmask_b32_e64 v96, v96, v119, s[10:11]
	v_cndmask_b32_e32 v119, 0, v232, vcc
	v_sub_f32_e32 v119, v96, v119
	v_max_f32_e32 v96, v166, v166
	v_med3_f32 v96, v96, s17, v231
	v_mul_f32_e32 v96, 0xbfb8aa3b, v96
	v_exp_f32_e32 v180, v96
	s_nop 0
	v_add_f32_e32 v96, 1.0, v180
	v_rcp_f32_e32 v182, v96
	v_max_f32_e32 v96, v167, v167
	v_med3_f32 v96, v96, s17, v231
	v_mul_f32_e32 v96, 0xbfb8aa3b, v96
	v_exp_f32_e32 v181, v96
	s_nop 0
	v_add_f32_e32 v96, 1.0, v181
	v_rcp_f32_e32 v183, v96
	v_fma_f32 v96, v182, v184, v120
	v_cmp_gt_f32_e32 vcc, s16, v96
	v_fmac_f32_e32 v121, v183, v185
	s_nop 0
	v_cndmask_b32_e64 v120, 0, 32, vcc
	v_ldexp_f32 v96, v96, v120
	v_log_f32_e32 v96, v96
	v_pk_mul_f32 v[180:181], v[180:181], v[182:183]
	v_mul_f32_e32 v120, 0x3f317217, v96
	v_fma_f32 v120, v96, s1, -v120
	v_fmac_f32_e32 v120, 0x3377d1cf, v96
	v_fmac_f32_e32 v120, 0x3f317217, v96
	v_cmp_lt_f32_e64 s[10:11], |v96|, s4
	v_pk_mul_f32 v[180:181], v[180:181], v[184:185]
	s_nop 0
	v_cndmask_b32_e64 v96, v96, v120, s[10:11]
	v_cndmask_b32_e32 v120, 0, v232, vcc
	v_cmp_gt_f32_e32 vcc, s16, v121
	v_sub_f32_e32 v120, v96, v120
	s_nop 0
	v_cndmask_b32_e64 v96, 0, 32, vcc
	v_ldexp_f32 v96, v121, v96
	v_log_f32_e32 v96, v96
	s_nop 0
	v_mul_f32_e32 v121, 0x3f317217, v96
	v_fma_f32 v121, v96, s1, -v121
	v_fmac_f32_e32 v121, 0x3377d1cf, v96
	v_fmac_f32_e32 v121, 0x3f317217, v96
	v_cmp_lt_f32_e64 s[10:11], |v96|, s4
	s_nop 1
	v_cndmask_b32_e64 v96, v96, v121, s[10:11]
	v_cndmask_b32_e32 v121, 0, v232, vcc
	v_sub_f32_e32 v121, v96, v121
	v_max_f32_e32 v96, v168, v168
	v_med3_f32 v96, v96, s17, v231
	v_mul_f32_e32 v96, 0xbfb8aa3b, v96
	v_exp_f32_e32 v184, v96
	s_nop 0
	v_add_f32_e32 v96, 1.0, v184
	v_rcp_f32_e32 v182, v96
	v_max_f32_e32 v96, v169, v169
	v_med3_f32 v96, v96, s17, v231
	v_mul_f32_e32 v96, 0xbfb8aa3b, v96
	v_exp_f32_e32 v185, v96
	s_nop 0
	v_add_f32_e32 v96, 1.0, v185
	v_rcp_f32_e32 v183, v96
	v_fma_f32 v96, v182, v186, v114
	v_cmp_gt_f32_e32 vcc, s16, v96
	v_pk_mul_f32 v[184:185], v[184:185], v[182:183]
	s_nop 0
	v_cndmask_b32_e64 v114, 0, 32, vcc
	v_ldexp_f32 v96, v96, v114
	v_log_f32_e32 v96, v96
	v_pk_mul_f32 v[184:185], v[184:185], v[186:187]
	v_mul_f32_e32 v114, 0x3f317217, v96
	v_fma_f32 v114, v96, s1, -v114
	v_fmac_f32_e32 v114, 0x3377d1cf, v96
	v_fmac_f32_e32 v114, 0x3f317217, v96
	v_cmp_lt_f32_e64 s[10:11], |v96|, s4
	s_nop 1
	v_cndmask_b32_e64 v96, v96, v114, s[10:11]
	v_cndmask_b32_e32 v114, 0, v232, vcc
	v_sub_f32_e32 v114, v96, v114
	v_fma_f32 v96, v183, v187, v115
	v_cmp_gt_f32_e32 vcc, s16, v96
	s_nop 1
	v_cndmask_b32_e64 v115, 0, 32, vcc
	v_ldexp_f32 v96, v96, v115
	v_log_f32_e32 v96, v96
	s_nop 0
	v_mul_f32_e32 v115, 0x3f317217, v96
	v_fma_f32 v115, v96, s1, -v115
	v_fmac_f32_e32 v115, 0x3377d1cf, v96
	v_fmac_f32_e32 v115, 0x3f317217, v96
	v_cmp_lt_f32_e64 s[10:11], |v96|, s4
	s_nop 1
	v_cndmask_b32_e64 v96, v96, v115, s[10:11]
	v_cndmask_b32_e32 v115, 0, v232, vcc
	v_sub_f32_e32 v115, v96, v115
	v_max_f32_e32 v96, v170, v170
	v_med3_f32 v96, v96, s17, v231
	v_mul_f32_e32 v96, 0xbfb8aa3b, v96
	v_exp_f32_e32 v182, v96
	s_nop 0
	v_add_f32_e32 v96, 1.0, v182
	v_rcp_f32_e32 v186, v96
	v_max_f32_e32 v96, v171, v171
	v_med3_f32 v96, v96, s17, v231
	v_mul_f32_e32 v96, 0xbfb8aa3b, v96
	v_exp_f32_e32 v183, v96
	s_nop 0
	v_add_f32_e32 v96, 1.0, v183
	v_rcp_f32_e32 v187, v96
	v_fma_f32 v96, v186, v210, v116
	v_cmp_gt_f32_e32 vcc, s16, v96
	v_fmac_f32_e32 v117, v187, v211
	s_nop 0
	v_cndmask_b32_e64 v116, 0, 32, vcc
	v_ldexp_f32 v96, v96, v116
	v_log_f32_e32 v96, v96
	v_pk_mul_f32 v[182:183], v[182:183], v[186:187]
	v_mul_f32_e32 v116, 0x3f317217, v96
	v_fma_f32 v116, v96, s1, -v116
	v_fmac_f32_e32 v116, 0x3377d1cf, v96
	v_fmac_f32_e32 v116, 0x3f317217, v96
	v_cmp_lt_f32_e64 s[10:11], |v96|, s4
	v_pk_mul_f32 v[182:183], v[182:183], v[210:211]
	s_nop 0
	v_cndmask_b32_e64 v96, v96, v116, s[10:11]
	v_cndmask_b32_e32 v116, 0, v232, vcc
	v_cmp_gt_f32_e32 vcc, s16, v117
	v_sub_f32_e32 v116, v96, v116
	s_nop 0
	v_cndmask_b32_e64 v96, 0, 32, vcc
	v_ldexp_f32 v96, v117, v96
	v_log_f32_e32 v96, v96
	s_nop 0
	v_mul_f32_e32 v117, 0x3f317217, v96
	v_fma_f32 v117, v96, s1, -v117
	v_fmac_f32_e32 v117, 0x3377d1cf, v96
	v_fmac_f32_e32 v117, 0x3f317217, v96
	v_cmp_lt_f32_e64 s[10:11], |v96|, s4
	s_nop 1
	v_cndmask_b32_e64 v96, v96, v117, s[10:11]
	v_cndmask_b32_e32 v117, 0, v232, vcc
	v_sub_f32_e32 v117, v96, v117
	global_store_dwordx4 v[154:155], v[118:121], off
	global_store_dwordx4 v[154:155], v[114:117], off offset:16
	s_nop 0
	v_lshl_add_u64 v[118:119], v[172:173], 1, v[152:153]
	v_cvt_pk_bf16_f32 v114, v178, v179
	v_cvt_pk_bf16_f32 v115, v180, v181
	v_cvt_pk_bf16_f32 v116, v184, v185
	v_cvt_pk_bf16_f32 v117, v182, v183
	global_store_dwordx4 v[118:119], v[114:117], off
	s_mov_b64 s[10:11], 0
	s_branch .LBB0_603

.LBB0_587:
	s_andn2_b64 vcc, exec, s[10:11]
	s_cbranch_vccnz .LBB0_589
	v_mul_f32_e32 v96, 0xbfb8aa3b, v164
	v_exp_f32_e32 v96, v96
	v_mul_f32_e32 v114, 0xbfb8aa3b, v165
	v_exp_f32_e32 v114, v114
	v_mul_f32_e32 v116, 0xbfb8aa3b, v167
	v_add_f32_e32 v96, 1.0, v96
	v_exp_f32_e32 v117, v116
	v_add_f32_e32 v115, 1.0, v114
	v_rcp_f32_e32 v114, v96
	v_mul_f32_e32 v96, 0xbfb8aa3b, v166
	v_exp_f32_e32 v96, v96
	v_rcp_f32_e32 v115, v115
	s_lshl_b32 s48, s95, 8
	v_add_f32_e32 v96, 1.0, v96
	v_rcp_f32_e32 v116, v96
	v_add_f32_e32 v96, 1.0, v117
	v_mul_f32_e32 v117, 0xbfb8aa3b, v168
	v_exp_f32_e32 v118, v117
	v_mul_f32_e32 v117, 0xbfb8aa3b, v169
	v_exp_f32_e32 v119, v117
	v_rcp_f32_e32 v117, v96
	v_add_f32_e32 v96, 1.0, v118
	v_rcp_f32_e32 v118, v96
	v_add_f32_e32 v96, 1.0, v119
	v_mul_f32_e32 v119, 0xbfb8aa3b, v170
	v_exp_f32_e32 v120, v119
	v_mul_f32_e32 v119, 0xbfb8aa3b, v171
	v_exp_f32_e32 v121, v119
	v_rcp_f32_e32 v119, v96
	v_add_f32_e32 v96, 1.0, v120
	v_rcp_f32_e32 v120, v96
	v_add_f32_e32 v96, 1.0, v121
	v_rcp_f32_e32 v121, v96
	v_pk_mul_f32 v[114:115], v[164:165], v[114:115]
	v_pk_mul_f32 v[116:117], v[166:167], v[116:117]
	v_pk_mul_f32 v[118:119], v[168:169], v[118:119]
	v_cvt_pk_bf16_f32 v114, v114, v115
	v_cvt_pk_bf16_f32 v115, v116, v117
	v_cvt_pk_bf16_f32 v116, v118, v119
	v_lshl_add_u64 v[118:119], v[150:151], 0, s[48:49]
	v_lshl_add_u64 v[118:119], v[146:147], 1, v[118:119]
	v_pk_mul_f32 v[120:121], v[170:171], v[120:121]
	v_add_co_u32_e32 v118, vcc, 0x811f000, v118
	v_cvt_pk_bf16_f32 v117, v120, v121
	s_nop 0
	v_addc_co_u32_e32 v119, vcc, 0, v119, vcc
	global_store_dwordx4 v[118:119], v[114:117], off offset:2560
	s_mov_b64 s[10:11], 0
	s_branch .LBB0_603

.LBB0_603:
	s_waitcnt lgkmcnt(0)
	v_add_f32_e32 v96, v208, v209
	v_fmamk_f32 v96, v96, 0x3a800000, v226
	v_rsq_f32_e32 v156, v96
	v_add_u32_e32 v114, 16, v148
	v_ashrrev_i32_e32 v115, 31, v114
	v_lshlrev_b64 v[118:119], 11, v[114:115]
	v_lshlrev_b64 v[150:151], 10, v[114:115]
	v_cndmask_b32_e64 v96, 0, 1, s[12:13]
	v_lshl_add_u64 v[158:159], s[50:51], 0, v[118:119]
	v_lshl_add_u64 v[116:117], s[72:73], 0, v[150:151]
	v_lshl_add_u64 v[120:121], s[52:53], 0, v[118:119]
	v_lshl_add_u64 v[118:119], s[96:97], 0, v[150:151]
	v_pk_mul_f32 v[154:155], v[110:111], v[156:157] op_sel_hi:[1,0]
	v_pk_mul_f32 v[162:163], v[112:113], v[156:157] op_sel_hi:[1,0]
	v_pk_mul_f32 v[164:165], v[106:107], v[156:157] op_sel_hi:[1,0]
	v_pk_mul_f32 v[166:167], v[108:109], v[156:157] op_sel_hi:[1,0]
	v_cmp_ne_u32_e64 s[10:11], 1, v96
	s_andn2_b64 vcc, exec, s[12:13]
	s_mov_b64 s[12:13], -1
	s_cbranch_vccnz .LBB0_625
	s_cmp_lt_u32 s94, 10
	s_cbranch_scc1 .LBB0_622
	s_cmp_lt_u32 s94, 14
	s_cbranch_scc1 .LBB0_619
	s_cmp_lt_u32 s94, 18
	s_cbranch_scc1 .LBB0_616
	s_cmp_lt_u32 s94, 22
	s_cbranch_scc1 .LBB0_613
	s_cmp_lt_u32 s94, 26
	s_cbranch_scc1 .LBB0_610
	v_mul_f32_e32 v106, 0xbfb8aa3b, v154
	v_mul_f32_e32 v107, 0xbfb8aa3b, v155
	v_mul_f32_e32 v108, 0xbfb8aa3b, v162
	v_mul_f32_e32 v109, 0xbfb8aa3b, v163
	v_mul_f32_e32 v111, 0xbfb8aa3b, v164
	v_mul_f32_e32 v112, 0xbfb8aa3b, v165
	v_exp_f32_e32 v106, v106
	v_exp_f32_e32 v107, v107
	v_exp_f32_e32 v108, v108
	v_exp_f32_e32 v109, v109
	v_exp_f32_e32 v111, v111
	v_exp_f32_e32 v112, v112
	v_mul_f32_e32 v113, 0xbfb8aa3b, v166
	v_mul_f32_e32 v149, 0xbfb8aa3b, v167
	v_exp_f32_e32 v113, v113
	v_exp_f32_e32 v149, v149
	v_add_f32_e32 v106, 1.0, v106
	v_add_f32_e32 v107, 1.0, v107
	v_add_f32_e32 v108, 1.0, v108
	v_add_f32_e32 v109, 1.0, v109
	v_add_f32_e32 v111, 1.0, v111
	v_add_f32_e32 v112, 1.0, v112
	v_rcp_f32_e32 v106, v106
	v_rcp_f32_e32 v107, v107
	v_rcp_f32_e32 v108, v108
	v_rcp_f32_e32 v109, v109
	v_rcp_f32_e32 v111, v111
	v_rcp_f32_e32 v112, v112
	v_lshl_add_u32 v96, s93, 8, v195
	v_add_f32_e32 v113, 1.0, v113
	v_add_f32_e32 v149, 1.0, v149
	v_ashrrev_i32_e32 v110, 10, v96
	v_rcp_f32_e32 v113, v113
	v_rcp_f32_e32 v149, v149
	v_cvt_pk_bf16_f32 v106, v106, v107
	v_cvt_pk_bf16_f32 v107, v108, v109
	v_cvt_pk_bf16_f32 v108, v111, v112
	v_ashrrev_i32_e32 v111, 31, v110
	v_and_b32_e32 v96, 0x3f8, v96
	v_lshlrev_b64 v[110:111], 25, v[110:111]
	v_lshl_add_u64 v[110:111], v[158:159], 0, v[110:111]
	v_lshlrev_b32_e32 v96, 1, v96
	v_cvt_pk_bf16_f32 v109, v113, v149
	v_lshl_add_u64 v[110:111], v[110:111], 0, v[96:97]
	s_mov_b64 s[12:13], 0
	global_store_dwordx4 v[110:111], v[106:109], off
	s_mov_b64 s[12:13], 0
	s_branch .LBB0_625
.LBB0_610:
	s_andn2_b64 vcc, exec, s[12:13]
	s_cbranch_vccnz .LBB0_612
	s_mov_b32 s12, 0x3e0293ee
	v_pk_mul_f32 v[106:107], v[154:155], s[12:13] op_sel_hi:[1,0]
	v_pk_mul_f32 v[108:109], v[162:163], s[12:13] op_sel_hi:[1,0]
	v_pk_mul_f32 v[110:111], v[164:165], s[12:13] op_sel_hi:[1,0]
	s_lshl_b32 s48, s93, 8
	v_cvt_pk_bf16_f32 v106, v106, v107
	v_cvt_pk_bf16_f32 v107, v108, v109
	v_cvt_pk_bf16_f32 v108, v110, v111
	v_lshl_add_u64 v[110:111], s[48:49], 1, v[116:117]
	v_lshl_add_u64 v[110:111], v[146:147], 1, v[110:111]
	v_pk_mul_f32 v[112:113], v[166:167], s[12:13] op_sel_hi:[1,0]
	v_add_co_u32_e32 v110, vcc, 0xe11e000, v110
	v_cvt_pk_bf16_f32 v109, v112, v113
	s_nop 0
	v_addc_co_u32_e32 v111, vcc, 0, v111, vcc
	global_store_dwordx4 v[110:111], v[106:109], off offset:2560
	s_mov_b64 s[12:13], 0
	s_branch .LBB0_625
.LBB0_612:
	s_mov_b64 s[12:13], 0
	s_mov_b64 s[12:13], 0
	s_branch .LBB0_625
.LBB0_613:
	s_andn2_b64 vcc, exec, s[12:13]
	s_cbranch_vccnz .LBB0_615
	v_mul_f32_e32 v96, 0xbfb8aa3b, v154
	v_exp_f32_e32 v96, v96
	v_mul_f32_e32 v106, 0xbfb8aa3b, v155
	v_exp_f32_e32 v106, v106
	v_mul_f32_e32 v108, 0xbfb8aa3b, v163
	v_add_f32_e32 v96, 1.0, v96
	v_exp_f32_e32 v109, v108
	v_add_f32_e32 v107, 1.0, v106
	v_rcp_f32_e32 v106, v96
	v_mul_f32_e32 v96, 0xbfb8aa3b, v162
	v_exp_f32_e32 v96, v96
	v_rcp_f32_e32 v107, v107
	s_lshl_b32 s48, s93, 8
	v_add_f32_e32 v96, 1.0, v96
	v_rcp_f32_e32 v108, v96
	v_add_f32_e32 v96, 1.0, v109
	v_mul_f32_e32 v109, 0xbfb8aa3b, v164
	v_exp_f32_e32 v110, v109
	v_mul_f32_e32 v109, 0xbfb8aa3b, v165
	v_exp_f32_e32 v111, v109
	v_rcp_f32_e32 v109, v96
	v_add_f32_e32 v96, 1.0, v110
	v_rcp_f32_e32 v110, v96
	v_add_f32_e32 v96, 1.0, v111
	v_mul_f32_e32 v111, 0xbfb8aa3b, v166
	v_exp_f32_e32 v112, v111
	v_mul_f32_e32 v111, 0xbfb8aa3b, v167
	v_exp_f32_e32 v113, v111
	v_rcp_f32_e32 v111, v96
	v_add_f32_e32 v96, 1.0, v112
	v_rcp_f32_e32 v112, v96
	v_add_f32_e32 v96, 1.0, v113
	v_rcp_f32_e32 v113, v96
	v_pk_mul_f32 v[106:107], v[154:155], v[106:107]
	v_pk_mul_f32 v[108:109], v[162:163], v[108:109]
	v_pk_mul_f32 v[110:111], v[164:165], v[110:111]
	v_cvt_pk_bf16_f32 v106, v106, v107
	v_cvt_pk_bf16_f32 v107, v108, v109
	v_cvt_pk_bf16_f32 v108, v110, v111
	v_lshl_add_u64 v[110:111], s[48:49], 1, v[116:117]
	v_lshl_add_u64 v[110:111], v[146:147], 1, v[110:111]
	v_pk_mul_f32 v[112:113], v[166:167], v[112:113]
	v_add_co_u32_e32 v110, vcc, 0xd11e000, v110
	v_cvt_pk_bf16_f32 v109, v112, v113
	s_nop 0
	v_addc_co_u32_e32 v111, vcc, 0, v111, vcc
	global_store_dwordx4 v[110:111], v[106:109], off offset:3584
	s_mov_b64 s[12:13], 0
	s_branch .LBB0_625

.LBB0_616:
	s_andn2_b64 vcc, exec, s[12:13]
	s_cbranch_vccnz .LBB0_618
	s_lshl_b32 s48, s93, 8
	v_lshl_add_u64 v[110:111], s[48:49], 1, v[116:117]
	v_lshl_add_u64 v[110:111], v[146:147], 1, v[110:111]
	v_add_co_u32_e32 v110, vcc, 0xc11f000, v110
	v_cvt_pk_bf16_f32 v106, v154, v155
	v_cvt_pk_bf16_f32 v107, v162, v163
	v_cvt_pk_bf16_f32 v108, v164, v165
	v_cvt_pk_bf16_f32 v109, v166, v167
	v_addc_co_u32_e32 v111, vcc, 0, v111, vcc
	global_store_dwordx4 v[110:111], v[106:109], off offset:512
	s_mov_b64 s[12:13], 0
	s_branch .LBB0_625

.LBB0_634:
	v_mov_b32_e32 v157, v156
	v_cndmask_b32_e64 v96, 0, 1, s[14:15]
	v_pk_mul_f32 v[106:107], v[102:103], v[156:157]
	v_pk_mul_f32 v[108:109], v[104:105], v[156:157]
	v_pk_mul_f32 v[154:155], v[98:99], v[156:157]
	v_pk_mul_f32 v[156:157], v[100:101], v[156:157]
	v_cmp_ne_u32_e64 s[12:13], 1, v96
	s_andn2_b64 vcc, exec, s[14:15]
	s_mov_b64 s[14:15], -1
	s_cbranch_vccnz .LBB0_661
	s_cmp_eq_u32 s93, 2
	s_cbranch_scc1 .LBB0_657
	s_cmp_lt_u32 s94, 10
	s_cbranch_scc1 .LBB0_654
	s_cmp_lt_u32 s94, 14
	s_cbranch_scc1 .LBB0_651
	s_cmp_lt_u32 s94, 18
	s_cbranch_scc1 .LBB0_648
	s_cmp_lt_u32 s94, 22
	s_cbranch_scc1 .LBB0_645
	s_cmp_lt_u32 s94, 26
	s_cbranch_scc1 .LBB0_642
	v_mul_f32_e32 v98, 0xbfb8aa3b, v106
	v_mul_f32_e32 v99, 0xbfb8aa3b, v107
	v_mul_f32_e32 v100, 0xbfb8aa3b, v108
	v_mul_f32_e32 v101, 0xbfb8aa3b, v109
	v_mul_f32_e32 v103, 0xbfb8aa3b, v154
	v_mul_f32_e32 v104, 0xbfb8aa3b, v155
	v_exp_f32_e32 v98, v98
	v_exp_f32_e32 v99, v99
	v_exp_f32_e32 v100, v100
	v_exp_f32_e32 v101, v101
	v_exp_f32_e32 v103, v103
	v_exp_f32_e32 v104, v104
	v_mul_f32_e32 v105, 0xbfb8aa3b, v156
	v_mul_f32_e32 v115, 0xbfb8aa3b, v157
	v_exp_f32_e32 v105, v105
	v_exp_f32_e32 v115, v115
	v_add_f32_e32 v98, 1.0, v98
	v_add_f32_e32 v99, 1.0, v99
	v_add_f32_e32 v100, 1.0, v100
	v_add_f32_e32 v101, 1.0, v101
	v_add_f32_e32 v103, 1.0, v103
	v_add_f32_e32 v104, 1.0, v104
	v_rcp_f32_e32 v98, v98
	v_rcp_f32_e32 v99, v99
	v_rcp_f32_e32 v100, v100
	v_rcp_f32_e32 v101, v101
	v_rcp_f32_e32 v103, v103
	v_rcp_f32_e32 v104, v104
	v_lshl_add_u32 v96, s95, 7, v195
	v_add_f32_e32 v105, 1.0, v105
	v_add_f32_e32 v115, 1.0, v115
	v_ashrrev_i32_e32 v102, 10, v96
	v_rcp_f32_e32 v105, v105
	v_rcp_f32_e32 v115, v115
	v_cvt_pk_bf16_f32 v98, v98, v99
	v_cvt_pk_bf16_f32 v99, v100, v101
	v_cvt_pk_bf16_f32 v100, v103, v104
	v_ashrrev_i32_e32 v103, 31, v102
	v_and_b32_e32 v96, 0x3f8, v96
	v_lshlrev_b64 v[102:103], 25, v[102:103]
	v_lshl_add_u64 v[102:103], v[158:159], 0, v[102:103]
	v_lshlrev_b32_e32 v96, 1, v96
	v_cvt_pk_bf16_f32 v101, v105, v115
	v_lshl_add_u64 v[102:103], v[102:103], 0, v[96:97]
	s_mov_b64 s[14:15], 0
	global_store_dwordx4 v[102:103], v[98:101], off
	s_mov_b64 s[14:15], 0
	s_branch .LBB0_670
.LBB0_642:
	s_andn2_b64 vcc, exec, s[14:15]
	s_cbranch_vccnz .LBB0_644
	s_mov_b32 s14, 0x3e0293ee
	v_pk_mul_f32 v[98:99], v[106:107], s[14:15] op_sel_hi:[1,0]
	v_pk_mul_f32 v[100:101], v[108:109], s[14:15] op_sel_hi:[1,0]
	v_pk_mul_f32 v[102:103], v[154:155], s[14:15] op_sel_hi:[1,0]
	s_lshl_b32 s48, s95, 8
	v_cvt_pk_bf16_f32 v98, v98, v99
	v_cvt_pk_bf16_f32 v99, v100, v101
	v_cvt_pk_bf16_f32 v100, v102, v103
	v_lshl_add_u64 v[102:103], v[116:117], 0, s[48:49]
	v_lshl_add_u64 v[102:103], v[146:147], 1, v[102:103]
	v_pk_mul_f32 v[104:105], v[156:157], s[14:15] op_sel_hi:[1,0]
	v_add_co_u32_e32 v102, vcc, 0xe11e000, v102
	v_cvt_pk_bf16_f32 v101, v104, v105
	s_nop 0
	v_addc_co_u32_e32 v103, vcc, 0, v103, vcc
	global_store_dwordx4 v[102:103], v[98:101], off offset:2560
	s_mov_b64 s[14:15], 0
	s_branch .LBB0_670
.LBB0_644:
	s_mov_b64 s[14:15], 0
	s_mov_b64 s[14:15], 0
	s_branch .LBB0_670
.LBB0_645:
	s_andn2_b64 vcc, exec, s[14:15]
	s_cbranch_vccnz .LBB0_647
	v_mul_f32_e32 v96, 0xbfb8aa3b, v106
	v_exp_f32_e32 v96, v96
	v_mul_f32_e32 v98, 0xbfb8aa3b, v107
	v_exp_f32_e32 v98, v98
	v_mul_f32_e32 v100, 0xbfb8aa3b, v109
	v_add_f32_e32 v96, 1.0, v96
	v_exp_f32_e32 v101, v100
	v_add_f32_e32 v99, 1.0, v98
	v_rcp_f32_e32 v98, v96
	v_mul_f32_e32 v96, 0xbfb8aa3b, v108
	v_exp_f32_e32 v96, v96
	v_rcp_f32_e32 v99, v99
	s_lshl_b32 s48, s95, 8
	v_add_f32_e32 v96, 1.0, v96
	v_rcp_f32_e32 v100, v96
	v_add_f32_e32 v96, 1.0, v101
	v_mul_f32_e32 v101, 0xbfb8aa3b, v154
	v_exp_f32_e32 v102, v101
	v_mul_f32_e32 v101, 0xbfb8aa3b, v155
	v_exp_f32_e32 v103, v101
	v_rcp_f32_e32 v101, v96
	v_add_f32_e32 v96, 1.0, v102
	v_rcp_f32_e32 v102, v96
	v_add_f32_e32 v96, 1.0, v103
	v_mul_f32_e32 v103, 0xbfb8aa3b, v156
	v_exp_f32_e32 v104, v103
	v_mul_f32_e32 v103, 0xbfb8aa3b, v157
	v_exp_f32_e32 v105, v103
	v_rcp_f32_e32 v103, v96
	v_add_f32_e32 v96, 1.0, v104
	v_rcp_f32_e32 v104, v96
	v_add_f32_e32 v96, 1.0, v105
	v_rcp_f32_e32 v105, v96
	v_pk_mul_f32 v[98:99], v[106:107], v[98:99]
	v_pk_mul_f32 v[100:101], v[108:109], v[100:101]
	v_pk_mul_f32 v[102:103], v[154:155], v[102:103]
	v_cvt_pk_bf16_f32 v98, v98, v99
	v_cvt_pk_bf16_f32 v99, v100, v101
	v_cvt_pk_bf16_f32 v100, v102, v103
	v_lshl_add_u64 v[102:103], v[116:117], 0, s[48:49]
	v_lshl_add_u64 v[102:103], v[146:147], 1, v[102:103]
	v_pk_mul_f32 v[104:105], v[156:157], v[104:105]
	v_add_co_u32_e32 v102, vcc, 0xd11e000, v102
	v_cvt_pk_bf16_f32 v101, v104, v105
	s_nop 0
	v_addc_co_u32_e32 v103, vcc, 0, v103, vcc
	global_store_dwordx4 v[102:103], v[98:101], off offset:3584
	s_mov_b64 s[14:15], 0
	s_branch .LBB0_670

.LBB0_648:
	s_andn2_b64 vcc, exec, s[14:15]
	s_cbranch_vccnz .LBB0_650
	s_lshl_b32 s48, s95, 8
	v_lshl_add_u64 v[102:103], v[116:117], 0, s[48:49]
	v_lshl_add_u64 v[102:103], v[146:147], 1, v[102:103]
	v_add_co_u32_e32 v102, vcc, 0xc11f000, v102
	v_cvt_pk_bf16_f32 v98, v106, v107
	v_cvt_pk_bf16_f32 v99, v108, v109
	v_cvt_pk_bf16_f32 v100, v154, v155
	v_cvt_pk_bf16_f32 v101, v156, v157
	v_addc_co_u32_e32 v103, vcc, 0, v103, vcc
	global_store_dwordx4 v[102:103], v[98:101], off offset:512
	s_mov_b64 s[14:15], 0
	s_branch .LBB0_670

.LBB0_651:
	s_andn2_b64 vcc, exec, s[14:15]
	s_cbranch_vccnz .LBB0_653
	v_lshl_add_u32 v158, s95, 7, v194
	v_ashrrev_i32_e32 v159, 31, v158
	v_lshlrev_b64 v[162:163], 2, v[158:159]
	v_lshl_add_u64 v[102:103], s[80:81], 0, v[162:163]
	global_load_dwordx4 v[98:101], v[102:103], off offset:16
	s_nop 0
	global_load_dwordx4 v[102:105], v[102:103], off
	v_max_f32_e32 v96, v106, v106
	s_mov_b32 s17, 0xc2700000
	v_med3_f32 v96, v96, s17, v231
	v_mul_f32_e32 v96, 0xbfb8aa3b, v96
	v_exp_f32_e32 v164, v96
	s_mov_b32 s1, 0x3f317217
	v_lshl_add_u64 v[120:121], v[120:121], 0, v[162:163]
	v_add_f32_e32 v96, 1.0, v164
	v_rcp_f32_e32 v166, v96
	v_max_f32_e32 v96, v107, v107
	v_med3_f32 v96, v96, s17, v231
	v_mul_f32_e32 v96, 0xbfb8aa3b, v96
	v_exp_f32_e32 v165, v96
	s_waitcnt vmcnt(0)
	v_pk_add_f32 v[172:173], v[98:99], 1.0 op_sel_hi:[1,0] neg_lo:[1,0] neg_hi:[1,0]
	v_add_f32_e32 v96, 1.0, v165
	v_pk_add_f32 v[168:169], v[102:103], 1.0 op_sel_hi:[1,0] neg_lo:[1,0] neg_hi:[1,0]
	v_rcp_f32_e32 v167, v96
	v_fma_f32 v96, v166, v168, v102
	v_cmp_gt_f32_e32 vcc, s16, v96
	v_pk_add_f32 v[170:171], v[104:105], 1.0 op_sel_hi:[1,0] neg_lo:[1,0] neg_hi:[1,0]
	v_pk_mul_f32 v[164:165], v[164:165], v[166:167]
	v_cndmask_b32_e64 v102, 0, 32, vcc
	v_ldexp_f32 v96, v96, v102
	v_log_f32_e32 v96, v96
	v_pk_mul_f32 v[164:165], v[164:165], v[168:169]
	v_pk_add_f32 v[174:175], v[100:101], 1.0 op_sel_hi:[1,0] neg_lo:[1,0] neg_hi:[1,0]
	v_mul_f32_e32 v102, 0x3f317217, v96
	v_fma_f32 v102, v96, s1, -v102
	v_fmac_f32_e32 v102, 0x3377d1cf, v96
	v_fmac_f32_e32 v102, 0x3f317217, v96
	v_cmp_lt_f32_e64 s[14:15], |v96|, s4
	s_nop 1
	v_cndmask_b32_e64 v96, v96, v102, s[14:15]
	v_cndmask_b32_e32 v102, 0, v232, vcc
	v_sub_f32_e32 v102, v96, v102
	v_fma_f32 v96, v167, v169, v103
	v_cmp_gt_f32_e32 vcc, s16, v96
	s_nop 1
	v_cndmask_b32_e64 v103, 0, 32, vcc
	v_ldexp_f32 v96, v96, v103
	v_log_f32_e32 v96, v96
	s_nop 0
	v_mul_f32_e32 v103, 0x3f317217, v96
	v_fma_f32 v103, v96, s1, -v103
	v_fmac_f32_e32 v103, 0x3377d1cf, v96
	v_fmac_f32_e32 v103, 0x3f317217, v96
	v_cmp_lt_f32_e64 s[14:15], |v96|, s4
	s_nop 1
	v_cndmask_b32_e64 v96, v96, v103, s[14:15]
	v_cndmask_b32_e32 v103, 0, v232, vcc
	v_sub_f32_e32 v103, v96, v103
	v_max_f32_e32 v96, v108, v108
	v_med3_f32 v96, v96, s17, v231
	v_mul_f32_e32 v96, 0xbfb8aa3b, v96
	v_exp_f32_e32 v166, v96
	s_nop 0
	v_add_f32_e32 v96, 1.0, v166
	v_rcp_f32_e32 v168, v96
	v_max_f32_e32 v96, v109, v109
	v_med3_f32 v96, v96, s17, v231
	v_mul_f32_e32 v96, 0xbfb8aa3b, v96
	v_exp_f32_e32 v167, v96
	s_nop 0
	v_add_f32_e32 v96, 1.0, v167
	v_rcp_f32_e32 v169, v96
	v_fma_f32 v96, v168, v170, v104
	v_cmp_gt_f32_e32 vcc, s16, v96
	v_fmac_f32_e32 v105, v169, v171
	s_nop 0
	v_cndmask_b32_e64 v104, 0, 32, vcc
	v_ldexp_f32 v96, v96, v104
	v_log_f32_e32 v96, v96
	v_pk_mul_f32 v[166:167], v[166:167], v[168:169]
	v_mul_f32_e32 v104, 0x3f317217, v96
	v_fma_f32 v104, v96, s1, -v104
	v_fmac_f32_e32 v104, 0x3377d1cf, v96
	v_fmac_f32_e32 v104, 0x3f317217, v96
	v_cmp_lt_f32_e64 s[14:15], |v96|, s4
	v_pk_mul_f32 v[166:167], v[166:167], v[170:171]
	s_nop 0
	v_cndmask_b32_e64 v96, v96, v104, s[14:15]
	v_cndmask_b32_e32 v104, 0, v232, vcc
	v_cmp_gt_f32_e32 vcc, s16, v105
	v_sub_f32_e32 v104, v96, v104
	s_nop 0
	v_cndmask_b32_e64 v96, 0, 32, vcc
	v_ldexp_f32 v96, v105, v96
	v_log_f32_e32 v96, v96
	s_nop 0
	v_mul_f32_e32 v105, 0x3f317217, v96
	v_fma_f32 v105, v96, s1, -v105
	v_fmac_f32_e32 v105, 0x3377d1cf, v96
	v_fmac_f32_e32 v105, 0x3f317217, v96
	v_cmp_lt_f32_e64 s[14:15], |v96|, s4
	s_nop 1
	v_cndmask_b32_e64 v96, v96, v105, s[14:15]
	v_cndmask_b32_e32 v105, 0, v232, vcc
	v_sub_f32_e32 v105, v96, v105
	v_max_f32_e32 v96, v154, v154
	v_med3_f32 v96, v96, s17, v231
	v_mul_f32_e32 v96, 0xbfb8aa3b, v96
	v_exp_f32_e32 v170, v96
	s_nop 0
	v_add_f32_e32 v96, 1.0, v170
	v_rcp_f32_e32 v168, v96
	v_max_f32_e32 v96, v155, v155
	v_med3_f32 v96, v96, s17, v231
	v_mul_f32_e32 v96, 0xbfb8aa3b, v96
	v_exp_f32_e32 v171, v96
	s_nop 0
	v_add_f32_e32 v96, 1.0, v171
	v_rcp_f32_e32 v169, v96
	v_fma_f32 v96, v168, v172, v98
	v_cmp_gt_f32_e32 vcc, s16, v96
	v_pk_mul_f32 v[170:171], v[170:171], v[168:169]
	s_nop 0
	v_cndmask_b32_e64 v98, 0, 32, vcc
	v_ldexp_f32 v96, v96, v98
	v_log_f32_e32 v96, v96
	v_pk_mul_f32 v[170:171], v[170:171], v[172:173]
	v_mul_f32_e32 v98, 0x3f317217, v96
	v_fma_f32 v98, v96, s1, -v98
	v_fmac_f32_e32 v98, 0x3377d1cf, v96
	v_fmac_f32_e32 v98, 0x3f317217, v96
	v_cmp_lt_f32_e64 s[14:15], |v96|, s4
	s_nop 1
	v_cndmask_b32_e64 v96, v96, v98, s[14:15]
	v_cndmask_b32_e32 v98, 0, v232, vcc
	v_sub_f32_e32 v98, v96, v98
	v_fma_f32 v96, v169, v173, v99
	v_cmp_gt_f32_e32 vcc, s16, v96
	s_nop 1
	v_cndmask_b32_e64 v99, 0, 32, vcc
	v_ldexp_f32 v96, v96, v99
	v_log_f32_e32 v96, v96
	s_nop 0
	v_mul_f32_e32 v99, 0x3f317217, v96
	v_fma_f32 v99, v96, s1, -v99
	v_fmac_f32_e32 v99, 0x3377d1cf, v96
	v_fmac_f32_e32 v99, 0x3f317217, v96
	v_cmp_lt_f32_e64 s[14:15], |v96|, s4
	s_nop 1
	v_cndmask_b32_e64 v96, v96, v99, s[14:15]
	v_cndmask_b32_e32 v99, 0, v232, vcc
	v_sub_f32_e32 v99, v96, v99
	v_max_f32_e32 v96, v156, v156
	v_med3_f32 v96, v96, s17, v231
	v_mul_f32_e32 v96, 0xbfb8aa3b, v96
	v_exp_f32_e32 v168, v96
	s_nop 0
	v_add_f32_e32 v96, 1.0, v168
	v_rcp_f32_e32 v172, v96
	v_max_f32_e32 v96, v157, v157
	v_med3_f32 v96, v96, s17, v231
	v_mul_f32_e32 v96, 0xbfb8aa3b, v96
	v_exp_f32_e32 v169, v96
	s_nop 0
	v_add_f32_e32 v96, 1.0, v169
	v_rcp_f32_e32 v173, v96
	v_fma_f32 v96, v172, v174, v100
	v_cmp_gt_f32_e32 vcc, s16, v96
	v_fmac_f32_e32 v101, v173, v175
	s_nop 0
	v_cndmask_b32_e64 v100, 0, 32, vcc
	v_ldexp_f32 v96, v96, v100
	v_log_f32_e32 v96, v96
	v_pk_mul_f32 v[168:169], v[168:169], v[172:173]
	v_mul_f32_e32 v100, 0x3f317217, v96
	v_fma_f32 v100, v96, s1, -v100
	v_fmac_f32_e32 v100, 0x3377d1cf, v96
	v_fmac_f32_e32 v100, 0x3f317217, v96
	v_cmp_lt_f32_e64 s[14:15], |v96|, s4
	v_pk_mul_f32 v[168:169], v[168:169], v[174:175]
	s_nop 0
	v_cndmask_b32_e64 v96, v96, v100, s[14:15]
	v_cndmask_b32_e32 v100, 0, v232, vcc
	v_cmp_gt_f32_e32 vcc, s16, v101
	v_sub_f32_e32 v100, v96, v100
	s_nop 0
	v_cndmask_b32_e64 v96, 0, 32, vcc
	v_ldexp_f32 v96, v101, v96
	v_log_f32_e32 v96, v96
	s_nop 0
	v_mul_f32_e32 v101, 0x3f317217, v96
	v_fma_f32 v101, v96, s1, -v101
	v_fmac_f32_e32 v101, 0x3377d1cf, v96
	v_fmac_f32_e32 v101, 0x3f317217, v96
	v_cmp_lt_f32_e64 s[14:15], |v96|, s4
	s_nop 1
	v_cndmask_b32_e64 v96, v96, v101, s[14:15]
	v_cndmask_b32_e32 v101, 0, v232, vcc
	v_sub_f32_e32 v101, v96, v101
	global_store_dwordx4 v[120:121], v[102:105], off
	global_store_dwordx4 v[120:121], v[98:101], off offset:16
	s_nop 0
	v_lshl_add_u64 v[102:103], v[158:159], 1, v[118:119]
	v_cvt_pk_bf16_f32 v98, v164, v165
	v_cvt_pk_bf16_f32 v99, v166, v167
	v_cvt_pk_bf16_f32 v100, v170, v171
	v_cvt_pk_bf16_f32 v101, v168, v169
	global_store_dwordx4 v[102:103], v[98:101], off
	s_mov_b64 s[14:15], 0
	s_branch .LBB0_670

.LBB0_654:
	s_andn2_b64 vcc, exec, s[14:15]
	s_cbranch_vccnz .LBB0_656
	v_mul_f32_e32 v96, 0xbfb8aa3b, v106
	v_exp_f32_e32 v96, v96
	v_mul_f32_e32 v98, 0xbfb8aa3b, v107
	v_exp_f32_e32 v98, v98
	v_mul_f32_e32 v100, 0xbfb8aa3b, v109
	v_add_f32_e32 v96, 1.0, v96
	v_exp_f32_e32 v101, v100
	v_add_f32_e32 v99, 1.0, v98
	v_rcp_f32_e32 v98, v96
	v_mul_f32_e32 v96, 0xbfb8aa3b, v108
	v_exp_f32_e32 v96, v96
	v_rcp_f32_e32 v99, v99
	s_lshl_b32 s48, s95, 8
	v_add_f32_e32 v96, 1.0, v96
	v_rcp_f32_e32 v100, v96
	v_add_f32_e32 v96, 1.0, v101
	v_mul_f32_e32 v101, 0xbfb8aa3b, v154
	v_exp_f32_e32 v102, v101
	v_mul_f32_e32 v101, 0xbfb8aa3b, v155
	v_exp_f32_e32 v103, v101
	v_rcp_f32_e32 v101, v96
	v_add_f32_e32 v96, 1.0, v102
	v_rcp_f32_e32 v102, v96
	v_add_f32_e32 v96, 1.0, v103
	v_mul_f32_e32 v103, 0xbfb8aa3b, v156
	v_exp_f32_e32 v104, v103
	v_mul_f32_e32 v103, 0xbfb8aa3b, v157
	v_exp_f32_e32 v105, v103
	v_rcp_f32_e32 v103, v96
	v_add_f32_e32 v96, 1.0, v104
	v_rcp_f32_e32 v104, v96
	v_add_f32_e32 v96, 1.0, v105
	v_rcp_f32_e32 v105, v96
	v_pk_mul_f32 v[98:99], v[106:107], v[98:99]
	v_pk_mul_f32 v[100:101], v[108:109], v[100:101]
	v_pk_mul_f32 v[102:103], v[154:155], v[102:103]
	v_cvt_pk_bf16_f32 v98, v98, v99
	v_cvt_pk_bf16_f32 v99, v100, v101
	v_cvt_pk_bf16_f32 v100, v102, v103
	v_lshl_add_u64 v[102:103], v[116:117], 0, s[48:49]
	v_lshl_add_u64 v[102:103], v[146:147], 1, v[102:103]
	v_pk_mul_f32 v[104:105], v[156:157], v[104:105]
	v_add_co_u32_e32 v102, vcc, 0x811f000, v102
	v_cvt_pk_bf16_f32 v101, v104, v105
	s_nop 0
	v_addc_co_u32_e32 v103, vcc, 0, v103, vcc
	global_store_dwordx4 v[102:103], v[98:101], off offset:2560
	s_mov_b64 s[14:15], 0
	s_branch .LBB0_670

.LBB0_670:
	v_add_f32_e32 v96, v206, v207
	v_fmamk_f32 v96, v96, 0x3a800000, v226
	v_rsq_f32_e32 v112, v96
	v_add_u32_e32 v98, 32, v148
	v_ashrrev_i32_e32 v99, 31, v98
	v_lshlrev_b64 v[102:103], 11, v[98:99]
	v_lshlrev_b64 v[106:107], 10, v[98:99]
	v_lshl_add_u64 v[114:115], s[50:51], 0, v[102:103]
	v_lshl_add_u64 v[100:101], s[72:73], 0, v[106:107]
	v_lshl_add_u64 v[104:105], s[52:53], 0, v[102:103]
	v_lshl_add_u64 v[102:103], s[96:97], 0, v[106:107]
	v_pk_mul_f32 v[110:111], v[92:93], v[112:113] op_sel_hi:[1,0]
	v_pk_mul_f32 v[118:119], v[94:95], v[112:113] op_sel_hi:[1,0]
	v_pk_mul_f32 v[120:121], v[88:89], v[112:113] op_sel_hi:[1,0]
	v_pk_mul_f32 v[150:151], v[90:91], v[112:113] op_sel_hi:[1,0]
	s_and_b64 vcc, exec, s[10:11]
	s_mov_b64 s[14:15], -1
	s_cbranch_vccnz .LBB0_692
	s_cmp_lt_u32 s94, 10
	s_cbranch_scc1 .LBB0_689
	s_cmp_lt_u32 s94, 14
	s_cbranch_scc1 .LBB0_686
	s_cmp_lt_u32 s94, 18
	s_cbranch_scc1 .LBB0_683
	s_cmp_lt_u32 s94, 22
	s_cbranch_scc1 .LBB0_680
	s_cmp_lt_u32 s94, 26
	s_cbranch_scc1 .LBB0_677
	v_mul_f32_e32 v89, 0xbfb8aa3b, v110
	v_mul_f32_e32 v90, 0xbfb8aa3b, v111
	v_mul_f32_e32 v91, 0xbfb8aa3b, v118
	v_mul_f32_e32 v93, 0xbfb8aa3b, v119
	v_exp_f32_e32 v89, v89
	v_exp_f32_e32 v90, v90
	v_exp_f32_e32 v91, v91
	v_exp_f32_e32 v93, v93
	v_mul_f32_e32 v96, 0xbfb8aa3b, v150
	v_mul_f32_e32 v106, 0xbfb8aa3b, v151
	v_mul_f32_e32 v94, 0xbfb8aa3b, v120
	v_mul_f32_e32 v95, 0xbfb8aa3b, v121
	v_exp_f32_e32 v96, v96
	v_exp_f32_e32 v106, v106
	v_exp_f32_e32 v94, v94
	v_exp_f32_e32 v95, v95
	v_add_f32_e32 v89, 1.0, v89
	v_add_f32_e32 v90, 1.0, v90
	v_add_f32_e32 v91, 1.0, v91
	v_add_f32_e32 v93, 1.0, v93
	v_rcp_f32_e32 v89, v89
	v_rcp_f32_e32 v90, v90
	v_rcp_f32_e32 v91, v91
	v_rcp_f32_e32 v93, v93
	v_add_f32_e32 v96, 1.0, v96
	v_add_f32_e32 v106, 1.0, v106
	v_lshl_add_u32 v88, s93, 8, v195
	v_add_f32_e32 v94, 1.0, v94
	v_add_f32_e32 v95, 1.0, v95
	v_rcp_f32_e32 v96, v96
	v_rcp_f32_e32 v106, v106
	v_ashrrev_i32_e32 v92, 10, v88
	v_rcp_f32_e32 v94, v94
	v_rcp_f32_e32 v95, v95
	v_and_b32_e32 v107, 0x3f8, v88
	v_cvt_pk_bf16_f32 v88, v89, v90
	v_cvt_pk_bf16_f32 v89, v91, v93
	v_ashrrev_i32_e32 v93, 31, v92
	v_lshlrev_b64 v[92:93], 25, v[92:93]
	v_cvt_pk_bf16_f32 v91, v96, v106
	v_lshl_add_u64 v[92:93], v[114:115], 0, v[92:93]
	v_lshlrev_b32_e32 v96, 1, v107
	v_cvt_pk_bf16_f32 v90, v94, v95
	v_lshl_add_u64 v[92:93], v[92:93], 0, v[96:97]
	s_mov_b64 s[14:15], 0
	global_store_dwordx4 v[92:93], v[88:91], off
	s_mov_b64 s[14:15], 0
	s_branch .LBB0_692
.LBB0_677:
	s_andn2_b64 vcc, exec, s[14:15]
	s_cbranch_vccnz .LBB0_679
	s_mov_b32 s14, 0x3e0293ee
	v_pk_mul_f32 v[88:89], v[110:111], s[14:15] op_sel_hi:[1,0]
	v_pk_mul_f32 v[90:91], v[118:119], s[14:15] op_sel_hi:[1,0]
	v_pk_mul_f32 v[92:93], v[120:121], s[14:15] op_sel_hi:[1,0]
	s_lshl_b32 s48, s93, 8
	v_cvt_pk_bf16_f32 v88, v88, v89
	v_cvt_pk_bf16_f32 v89, v90, v91
	v_cvt_pk_bf16_f32 v90, v92, v93
	v_lshl_add_u64 v[92:93], s[48:49], 1, v[100:101]
	v_lshl_add_u64 v[92:93], v[146:147], 1, v[92:93]
	v_pk_mul_f32 v[94:95], v[150:151], s[14:15] op_sel_hi:[1,0]
	v_add_co_u32_e32 v92, vcc, 0xe11e000, v92
	v_cvt_pk_bf16_f32 v91, v94, v95
	s_nop 0
	v_addc_co_u32_e32 v93, vcc, 0, v93, vcc
	global_store_dwordx4 v[92:93], v[88:91], off offset:2560
	s_mov_b64 s[14:15], 0
	s_branch .LBB0_692

.LBB0_680:
	s_andn2_b64 vcc, exec, s[14:15]
	s_cbranch_vccnz .LBB0_682
	v_mul_f32_e32 v88, 0xbfb8aa3b, v110
	v_mul_f32_e32 v89, 0xbfb8aa3b, v111
	v_mul_f32_e32 v90, 0xbfb8aa3b, v118
	v_mul_f32_e32 v91, 0xbfb8aa3b, v119
	v_mul_f32_e32 v92, 0xbfb8aa3b, v120
	v_mul_f32_e32 v93, 0xbfb8aa3b, v121
	v_exp_f32_e32 v88, v88
	v_exp_f32_e32 v89, v89
	v_exp_f32_e32 v90, v90
	v_exp_f32_e32 v91, v91
	v_exp_f32_e32 v92, v92
	v_exp_f32_e32 v93, v93
	v_mul_f32_e32 v94, 0xbfb8aa3b, v150
	v_mul_f32_e32 v95, 0xbfb8aa3b, v151
	v_exp_f32_e32 v94, v94
	v_exp_f32_e32 v95, v95
	v_add_f32_e32 v88, 1.0, v88
	v_add_f32_e32 v89, 1.0, v89
	v_add_f32_e32 v90, 1.0, v90
	v_add_f32_e32 v91, 1.0, v91
	v_add_f32_e32 v92, 1.0, v92
	v_add_f32_e32 v93, 1.0, v93
	v_rcp_f32_e32 v88, v88
	v_rcp_f32_e32 v89, v89
	v_rcp_f32_e32 v90, v90
	v_rcp_f32_e32 v91, v91
	v_rcp_f32_e32 v92, v92
	v_rcp_f32_e32 v93, v93
	v_add_f32_e32 v94, 1.0, v94
	v_add_f32_e32 v95, 1.0, v95
	v_rcp_f32_e32 v94, v94
	v_rcp_f32_e32 v95, v95
	v_pk_mul_f32 v[88:89], v[110:111], v[88:89]
	v_pk_mul_f32 v[90:91], v[118:119], v[90:91]
	v_pk_mul_f32 v[92:93], v[120:121], v[92:93]
	s_lshl_b32 s48, s93, 8
	v_cvt_pk_bf16_f32 v88, v88, v89
	v_cvt_pk_bf16_f32 v89, v90, v91
	v_cvt_pk_bf16_f32 v90, v92, v93
	v_lshl_add_u64 v[92:93], s[48:49], 1, v[100:101]
	v_lshl_add_u64 v[92:93], v[146:147], 1, v[92:93]
	v_pk_mul_f32 v[94:95], v[150:151], v[94:95]
	v_add_co_u32_e32 v92, vcc, 0xd11e000, v92
	v_cvt_pk_bf16_f32 v91, v94, v95
	s_nop 0
	v_addc_co_u32_e32 v93, vcc, 0, v93, vcc
	global_store_dwordx4 v[92:93], v[88:91], off offset:3584
	s_mov_b64 s[14:15], 0
	s_branch .LBB0_692

.LBB0_683:
	s_andn2_b64 vcc, exec, s[14:15]
	s_cbranch_vccnz .LBB0_685
	s_lshl_b32 s48, s93, 8
	v_lshl_add_u64 v[92:93], s[48:49], 1, v[100:101]
	v_lshl_add_u64 v[92:93], v[146:147], 1, v[92:93]
	v_add_co_u32_e32 v92, vcc, 0xc11f000, v92
	v_cvt_pk_bf16_f32 v88, v110, v111
	v_cvt_pk_bf16_f32 v89, v118, v119
	v_cvt_pk_bf16_f32 v90, v120, v121
	v_cvt_pk_bf16_f32 v91, v150, v151
	v_addc_co_u32_e32 v93, vcc, 0, v93, vcc
	global_store_dwordx4 v[92:93], v[88:91], off offset:512
	s_mov_b64 s[14:15], 0
	s_branch .LBB0_692

.LBB0_701:
	v_mov_b32_e32 v113, v112
	v_pk_mul_f32 v[88:89], v[84:85], v[112:113]
	v_pk_mul_f32 v[90:91], v[86:87], v[112:113]
	v_pk_mul_f32 v[110:111], v[80:81], v[112:113]
	v_pk_mul_f32 v[112:113], v[82:83], v[112:113]
	s_and_b64 vcc, exec, s[12:13]
	s_mov_b64 s[14:15], -1
	s_cbranch_vccnz .LBB0_728
	s_cmp_eq_u32 s93, 2
	s_cbranch_scc1 .LBB0_724
	s_cmp_lt_u32 s94, 10
	s_cbranch_scc1 .LBB0_721
	s_cmp_lt_u32 s94, 14
	s_cbranch_scc1 .LBB0_718
	s_cmp_lt_u32 s94, 18
	s_cbranch_scc1 .LBB0_715
	s_cmp_lt_u32 s94, 22
	s_cbranch_scc1 .LBB0_712
	s_cmp_lt_u32 s94, 26
	s_cbranch_scc1 .LBB0_709
	v_mul_f32_e32 v81, 0xbfb8aa3b, v88
	v_mul_f32_e32 v82, 0xbfb8aa3b, v89
	v_mul_f32_e32 v83, 0xbfb8aa3b, v90
	v_mul_f32_e32 v85, 0xbfb8aa3b, v91
	v_exp_f32_e32 v81, v81
	v_exp_f32_e32 v82, v82
	v_exp_f32_e32 v83, v83
	v_exp_f32_e32 v85, v85
	v_mul_f32_e32 v96, 0xbfb8aa3b, v112
	v_mul_f32_e32 v99, 0xbfb8aa3b, v113
	v_mul_f32_e32 v86, 0xbfb8aa3b, v110
	v_mul_f32_e32 v87, 0xbfb8aa3b, v111
	v_exp_f32_e32 v96, v96
	v_exp_f32_e32 v99, v99
	v_exp_f32_e32 v86, v86
	v_exp_f32_e32 v87, v87
	v_add_f32_e32 v81, 1.0, v81
	v_add_f32_e32 v82, 1.0, v82
	v_add_f32_e32 v83, 1.0, v83
	v_add_f32_e32 v85, 1.0, v85
	v_rcp_f32_e32 v81, v81
	v_rcp_f32_e32 v82, v82
	v_rcp_f32_e32 v83, v83
	v_rcp_f32_e32 v85, v85
	v_add_f32_e32 v96, 1.0, v96
	v_add_f32_e32 v99, 1.0, v99
	v_lshl_add_u32 v80, s95, 7, v195
	v_add_f32_e32 v86, 1.0, v86
	v_add_f32_e32 v87, 1.0, v87
	v_rcp_f32_e32 v96, v96
	v_rcp_f32_e32 v99, v99
	v_ashrrev_i32_e32 v84, 10, v80
	v_rcp_f32_e32 v86, v86
	v_rcp_f32_e32 v87, v87
	v_and_b32_e32 v118, 0x3f8, v80
	v_cvt_pk_bf16_f32 v80, v81, v82
	v_cvt_pk_bf16_f32 v81, v83, v85
	v_ashrrev_i32_e32 v85, 31, v84
	v_lshlrev_b64 v[84:85], 25, v[84:85]
	v_cvt_pk_bf16_f32 v83, v96, v99
	v_lshl_add_u64 v[84:85], v[114:115], 0, v[84:85]
	v_lshlrev_b32_e32 v96, 1, v118
	v_cvt_pk_bf16_f32 v82, v86, v87
	v_lshl_add_u64 v[84:85], v[84:85], 0, v[96:97]
	s_mov_b64 s[14:15], 0
	global_store_dwordx4 v[84:85], v[80:83], off
	s_mov_b64 s[14:15], 0
	s_branch .LBB0_737
.LBB0_709:
	s_andn2_b64 vcc, exec, s[14:15]
	s_cbranch_vccnz .LBB0_711
	s_mov_b32 s14, 0x3e0293ee
	v_pk_mul_f32 v[80:81], v[88:89], s[14:15] op_sel_hi:[1,0]
	v_pk_mul_f32 v[82:83], v[90:91], s[14:15] op_sel_hi:[1,0]
	v_pk_mul_f32 v[84:85], v[110:111], s[14:15] op_sel_hi:[1,0]
	s_lshl_b32 s48, s95, 8
	v_cvt_pk_bf16_f32 v80, v80, v81
	v_cvt_pk_bf16_f32 v81, v82, v83
	v_cvt_pk_bf16_f32 v82, v84, v85
	v_lshl_add_u64 v[84:85], v[100:101], 0, s[48:49]
	v_lshl_add_u64 v[84:85], v[146:147], 1, v[84:85]
	v_pk_mul_f32 v[86:87], v[112:113], s[14:15] op_sel_hi:[1,0]
	v_add_co_u32_e32 v84, vcc, 0xe11e000, v84
	v_cvt_pk_bf16_f32 v83, v86, v87
	s_nop 0
	v_addc_co_u32_e32 v85, vcc, 0, v85, vcc
	global_store_dwordx4 v[84:85], v[80:83], off offset:2560
	s_mov_b64 s[14:15], 0
	s_branch .LBB0_737

.LBB0_712:
	s_andn2_b64 vcc, exec, s[14:15]
	s_cbranch_vccnz .LBB0_714
	v_mul_f32_e32 v80, 0xbfb8aa3b, v88
	v_mul_f32_e32 v81, 0xbfb8aa3b, v89
	v_mul_f32_e32 v82, 0xbfb8aa3b, v90
	v_mul_f32_e32 v83, 0xbfb8aa3b, v91
	v_mul_f32_e32 v84, 0xbfb8aa3b, v110
	v_mul_f32_e32 v85, 0xbfb8aa3b, v111
	v_exp_f32_e32 v80, v80
	v_exp_f32_e32 v81, v81
	v_exp_f32_e32 v82, v82
	v_exp_f32_e32 v83, v83
	v_exp_f32_e32 v84, v84
	v_exp_f32_e32 v85, v85
	v_mul_f32_e32 v86, 0xbfb8aa3b, v112
	v_mul_f32_e32 v87, 0xbfb8aa3b, v113
	v_exp_f32_e32 v86, v86
	v_exp_f32_e32 v87, v87
	v_add_f32_e32 v80, 1.0, v80
	v_add_f32_e32 v81, 1.0, v81
	v_add_f32_e32 v82, 1.0, v82
	v_add_f32_e32 v83, 1.0, v83
	v_add_f32_e32 v84, 1.0, v84
	v_add_f32_e32 v85, 1.0, v85
	v_rcp_f32_e32 v80, v80
	v_rcp_f32_e32 v81, v81
	v_rcp_f32_e32 v82, v82
	v_rcp_f32_e32 v83, v83
	v_rcp_f32_e32 v84, v84
	v_rcp_f32_e32 v85, v85
	v_add_f32_e32 v86, 1.0, v86
	v_add_f32_e32 v87, 1.0, v87
	v_rcp_f32_e32 v86, v86
	v_rcp_f32_e32 v87, v87
	v_pk_mul_f32 v[80:81], v[88:89], v[80:81]
	v_pk_mul_f32 v[82:83], v[90:91], v[82:83]
	v_pk_mul_f32 v[84:85], v[110:111], v[84:85]
	s_lshl_b32 s48, s95, 8
	v_cvt_pk_bf16_f32 v80, v80, v81
	v_cvt_pk_bf16_f32 v81, v82, v83
	v_cvt_pk_bf16_f32 v82, v84, v85
	v_lshl_add_u64 v[84:85], v[100:101], 0, s[48:49]
	v_lshl_add_u64 v[84:85], v[146:147], 1, v[84:85]
	v_pk_mul_f32 v[86:87], v[112:113], v[86:87]
	v_add_co_u32_e32 v84, vcc, 0xd11e000, v84
	v_cvt_pk_bf16_f32 v83, v86, v87
	s_nop 0
	v_addc_co_u32_e32 v85, vcc, 0, v85, vcc
	global_store_dwordx4 v[84:85], v[80:83], off offset:3584
	s_mov_b64 s[14:15], 0
	s_branch .LBB0_737

.LBB0_715:
	s_andn2_b64 vcc, exec, s[14:15]
	s_cbranch_vccnz .LBB0_717
	s_lshl_b32 s48, s95, 8
	v_lshl_add_u64 v[84:85], v[100:101], 0, s[48:49]
	v_lshl_add_u64 v[84:85], v[146:147], 1, v[84:85]
	v_add_co_u32_e32 v84, vcc, 0xc11f000, v84
	v_cvt_pk_bf16_f32 v80, v88, v89
	v_cvt_pk_bf16_f32 v81, v90, v91
	v_cvt_pk_bf16_f32 v82, v110, v111
	v_cvt_pk_bf16_f32 v83, v112, v113
	v_addc_co_u32_e32 v85, vcc, 0, v85, vcc
	global_store_dwordx4 v[84:85], v[80:83], off offset:512
	s_mov_b64 s[14:15], 0
	s_branch .LBB0_737

.LBB0_718:
	s_andn2_b64 vcc, exec, s[14:15]
	s_cbranch_vccnz .LBB0_720
	v_lshl_add_u32 v114, s95, 7, v194
	v_ashrrev_i32_e32 v115, 31, v114
	v_lshlrev_b64 v[118:119], 2, v[114:115]
	v_lshl_add_u64 v[84:85], s[80:81], 0, v[118:119]
	global_load_dwordx4 v[80:83], v[84:85], off offset:16
	s_nop 0
	global_load_dwordx4 v[84:87], v[84:85], off
	v_max_f32_e32 v96, v88, v88
	s_mov_b32 s17, 0xc2700000
	v_med3_f32 v96, v96, s17, v231
	v_mul_f32_e32 v96, 0xbfb8aa3b, v96
	v_exp_f32_e32 v120, v96
	s_mov_b32 s1, 0x3f317217
	v_lshl_add_u64 v[104:105], v[104:105], 0, v[118:119]
	v_add_f32_e32 v96, 1.0, v120
	v_rcp_f32_e32 v150, v96
	v_max_f32_e32 v96, v89, v89
	v_med3_f32 v96, v96, s17, v231
	v_mul_f32_e32 v96, 0xbfb8aa3b, v96
	v_exp_f32_e32 v121, v96
	s_waitcnt vmcnt(0)
	v_pk_add_f32 v[156:157], v[80:81], 1.0 op_sel_hi:[1,0] neg_lo:[1,0] neg_hi:[1,0]
	v_pk_add_f32 v[152:153], v[84:85], 1.0 op_sel_hi:[1,0] neg_lo:[1,0] neg_hi:[1,0]
	v_add_f32_e32 v96, 1.0, v121
	v_fma_f32 v84, v150, v152, v84
	v_cmp_gt_f32_e32 vcc, s16, v84
	v_rcp_f32_e32 v151, v96
	v_pk_add_f32 v[154:155], v[86:87], 1.0 op_sel_hi:[1,0] neg_lo:[1,0] neg_hi:[1,0]
	v_cndmask_b32_e64 v96, 0, 32, vcc
	v_ldexp_f32 v84, v84, v96
	v_log_f32_e32 v84, v84
	v_fma_f32 v85, v151, v153, v85
	v_pk_mul_f32 v[120:121], v[120:121], v[150:151]
	v_pk_add_f32 v[158:159], v[82:83], 1.0 op_sel_hi:[1,0] neg_lo:[1,0] neg_hi:[1,0]
	v_mul_f32_e32 v96, 0x3f317217, v84
	v_fma_f32 v96, v84, s1, -v96
	v_fmac_f32_e32 v96, 0x3377d1cf, v84
	v_fmac_f32_e32 v96, 0x3f317217, v84
	v_cmp_lt_f32_e64 s[14:15], |v84|, s4
	v_pk_mul_f32 v[120:121], v[120:121], v[152:153]
	s_nop 0
	v_cndmask_b32_e64 v84, v84, v96, s[14:15]
	v_cndmask_b32_e32 v96, 0, v232, vcc
	v_cmp_gt_f32_e32 vcc, s16, v85
	v_sub_f32_e32 v84, v84, v96
	s_nop 0
	v_cndmask_b32_e64 v96, 0, 32, vcc
	v_ldexp_f32 v85, v85, v96
	v_log_f32_e32 v85, v85
	s_nop 0
	v_mul_f32_e32 v96, 0x3f317217, v85
	v_fma_f32 v96, v85, s1, -v96
	v_fmac_f32_e32 v96, 0x3377d1cf, v85
	v_fmac_f32_e32 v96, 0x3f317217, v85
	v_cmp_lt_f32_e64 s[14:15], |v85|, s4
	s_nop 1
	v_cndmask_b32_e64 v85, v85, v96, s[14:15]
	v_cndmask_b32_e32 v96, 0, v232, vcc
	v_sub_f32_e32 v85, v85, v96
	v_max_f32_e32 v96, v90, v90
	v_med3_f32 v96, v96, s17, v231
	v_mul_f32_e32 v96, 0xbfb8aa3b, v96
	v_exp_f32_e32 v150, v96
	s_nop 0
	v_add_f32_e32 v96, 1.0, v150
	v_rcp_f32_e32 v152, v96
	v_max_f32_e32 v96, v91, v91
	v_med3_f32 v96, v96, s17, v231
	v_mul_f32_e32 v96, 0xbfb8aa3b, v96
	v_exp_f32_e32 v151, v96
	v_fma_f32 v86, v152, v154, v86
	v_cmp_gt_f32_e32 vcc, s16, v86
	v_add_f32_e32 v96, 1.0, v151
	v_rcp_f32_e32 v153, v96
	v_cndmask_b32_e64 v96, 0, 32, vcc
	v_ldexp_f32 v86, v86, v96
	v_log_f32_e32 v86, v86
	v_fmac_f32_e32 v87, v153, v155
	v_pk_mul_f32 v[150:151], v[150:151], v[152:153]
	v_mul_f32_e32 v96, 0x3f317217, v86
	v_fma_f32 v96, v86, s1, -v96
	v_fmac_f32_e32 v96, 0x3377d1cf, v86
	v_fmac_f32_e32 v96, 0x3f317217, v86
	v_cmp_lt_f32_e64 s[14:15], |v86|, s4
	v_pk_mul_f32 v[150:151], v[150:151], v[154:155]
	s_nop 0
	v_cndmask_b32_e64 v86, v86, v96, s[14:15]
	v_cndmask_b32_e32 v96, 0, v232, vcc
	v_cmp_gt_f32_e32 vcc, s16, v87
	v_sub_f32_e32 v86, v86, v96
	s_nop 0
	v_cndmask_b32_e64 v96, 0, 32, vcc
	v_ldexp_f32 v87, v87, v96
	v_log_f32_e32 v87, v87
	s_nop 0
	v_mul_f32_e32 v96, 0x3f317217, v87
	v_fma_f32 v96, v87, s1, -v96
	v_fmac_f32_e32 v96, 0x3377d1cf, v87
	v_fmac_f32_e32 v96, 0x3f317217, v87
	v_cmp_lt_f32_e64 s[14:15], |v87|, s4
	s_nop 1
	v_cndmask_b32_e64 v87, v87, v96, s[14:15]
	v_cndmask_b32_e32 v96, 0, v232, vcc
	v_sub_f32_e32 v87, v87, v96
	v_max_f32_e32 v96, v110, v110
	v_med3_f32 v96, v96, s17, v231
	v_mul_f32_e32 v96, 0xbfb8aa3b, v96
	v_exp_f32_e32 v154, v96
	s_nop 0
	v_add_f32_e32 v96, 1.0, v154
	v_rcp_f32_e32 v152, v96
	v_max_f32_e32 v96, v111, v111
	v_med3_f32 v96, v96, s17, v231
	v_mul_f32_e32 v96, 0xbfb8aa3b, v96
	v_exp_f32_e32 v155, v96
	v_fma_f32 v80, v152, v156, v80
	v_cmp_gt_f32_e32 vcc, s16, v80
	v_add_f32_e32 v96, 1.0, v155
	v_rcp_f32_e32 v153, v96
	v_cndmask_b32_e64 v96, 0, 32, vcc
	v_ldexp_f32 v80, v80, v96
	v_log_f32_e32 v80, v80
	v_fma_f32 v81, v153, v157, v81
	v_pk_mul_f32 v[154:155], v[154:155], v[152:153]
	v_mul_f32_e32 v96, 0x3f317217, v80
	v_fma_f32 v96, v80, s1, -v96
	v_fmac_f32_e32 v96, 0x3377d1cf, v80
	v_fmac_f32_e32 v96, 0x3f317217, v80
	v_cmp_lt_f32_e64 s[14:15], |v80|, s4
	v_pk_mul_f32 v[154:155], v[154:155], v[156:157]
	s_nop 0
	v_cndmask_b32_e64 v80, v80, v96, s[14:15]
	v_cndmask_b32_e32 v96, 0, v232, vcc
	v_cmp_gt_f32_e32 vcc, s16, v81
	v_sub_f32_e32 v80, v80, v96
	s_nop 0
	v_cndmask_b32_e64 v96, 0, 32, vcc
	v_ldexp_f32 v81, v81, v96
	v_log_f32_e32 v81, v81
	s_nop 0
	v_mul_f32_e32 v96, 0x3f317217, v81
	v_fma_f32 v96, v81, s1, -v96
	v_fmac_f32_e32 v96, 0x3377d1cf, v81
	v_fmac_f32_e32 v96, 0x3f317217, v81
	v_cmp_lt_f32_e64 s[14:15], |v81|, s4
	s_nop 1
	v_cndmask_b32_e64 v81, v81, v96, s[14:15]
	v_cndmask_b32_e32 v96, 0, v232, vcc
	v_sub_f32_e32 v81, v81, v96
	v_max_f32_e32 v96, v112, v112
	v_med3_f32 v96, v96, s17, v231
	v_mul_f32_e32 v96, 0xbfb8aa3b, v96
	v_exp_f32_e32 v152, v96
	s_nop 0
	v_add_f32_e32 v96, 1.0, v152
	v_rcp_f32_e32 v156, v96
	v_max_f32_e32 v96, v113, v113
	v_med3_f32 v96, v96, s17, v231
	v_mul_f32_e32 v96, 0xbfb8aa3b, v96
	v_exp_f32_e32 v153, v96
	v_fma_f32 v82, v156, v158, v82
	v_cmp_gt_f32_e32 vcc, s16, v82
	v_add_f32_e32 v96, 1.0, v153
	v_rcp_f32_e32 v157, v96
	v_cndmask_b32_e64 v96, 0, 32, vcc
	v_ldexp_f32 v82, v82, v96
	v_log_f32_e32 v82, v82
	v_fmac_f32_e32 v83, v157, v159
	v_pk_mul_f32 v[152:153], v[152:153], v[156:157]
	v_mul_f32_e32 v96, 0x3f317217, v82
	v_fma_f32 v96, v82, s1, -v96
	v_fmac_f32_e32 v96, 0x3377d1cf, v82
	v_fmac_f32_e32 v96, 0x3f317217, v82
	v_cmp_lt_f32_e64 s[14:15], |v82|, s4
	v_pk_mul_f32 v[152:153], v[152:153], v[158:159]
	s_nop 0
	v_cndmask_b32_e64 v82, v82, v96, s[14:15]
	v_cndmask_b32_e32 v96, 0, v232, vcc
	v_cmp_gt_f32_e32 vcc, s16, v83
	v_sub_f32_e32 v82, v82, v96
	s_nop 0
	v_cndmask_b32_e64 v96, 0, 32, vcc
	v_ldexp_f32 v83, v83, v96
	v_log_f32_e32 v83, v83
	s_nop 0
	v_mul_f32_e32 v96, 0x3f317217, v83
	v_fma_f32 v96, v83, s1, -v96
	v_fmac_f32_e32 v96, 0x3377d1cf, v83
	v_fmac_f32_e32 v96, 0x3f317217, v83
	v_cmp_lt_f32_e64 s[14:15], |v83|, s4
	s_nop 1
	v_cndmask_b32_e64 v83, v83, v96, s[14:15]
	v_cndmask_b32_e32 v96, 0, v232, vcc
	v_sub_f32_e32 v83, v83, v96
	global_store_dwordx4 v[104:105], v[84:87], off
	global_store_dwordx4 v[104:105], v[80:83], off offset:16
	s_nop 0
	v_lshl_add_u64 v[84:85], v[114:115], 1, v[102:103]
	v_cvt_pk_bf16_f32 v80, v120, v121
	v_cvt_pk_bf16_f32 v81, v150, v151
	v_cvt_pk_bf16_f32 v82, v154, v155
	v_cvt_pk_bf16_f32 v83, v152, v153
	global_store_dwordx4 v[84:85], v[80:83], off
	s_mov_b64 s[14:15], 0
	s_branch .LBB0_737

.LBB0_721:
	s_andn2_b64 vcc, exec, s[14:15]
	s_cbranch_vccnz .LBB0_723
	v_mul_f32_e32 v80, 0xbfb8aa3b, v88
	v_mul_f32_e32 v81, 0xbfb8aa3b, v89
	v_mul_f32_e32 v82, 0xbfb8aa3b, v90
	v_mul_f32_e32 v83, 0xbfb8aa3b, v91
	v_mul_f32_e32 v84, 0xbfb8aa3b, v110
	v_mul_f32_e32 v85, 0xbfb8aa3b, v111
	v_exp_f32_e32 v80, v80
	v_exp_f32_e32 v81, v81
	v_exp_f32_e32 v82, v82
	v_exp_f32_e32 v83, v83
	v_exp_f32_e32 v84, v84
	v_exp_f32_e32 v85, v85
	v_mul_f32_e32 v86, 0xbfb8aa3b, v112
	v_mul_f32_e32 v87, 0xbfb8aa3b, v113
	v_exp_f32_e32 v86, v86
	v_exp_f32_e32 v87, v87
	v_add_f32_e32 v80, 1.0, v80
	v_add_f32_e32 v81, 1.0, v81
	v_add_f32_e32 v82, 1.0, v82
	v_add_f32_e32 v83, 1.0, v83
	v_add_f32_e32 v84, 1.0, v84
	v_add_f32_e32 v85, 1.0, v85
	v_rcp_f32_e32 v80, v80
	v_rcp_f32_e32 v81, v81
	v_rcp_f32_e32 v82, v82
	v_rcp_f32_e32 v83, v83
	v_rcp_f32_e32 v84, v84
	v_rcp_f32_e32 v85, v85
	v_add_f32_e32 v86, 1.0, v86
	v_add_f32_e32 v87, 1.0, v87
	v_rcp_f32_e32 v86, v86
	v_rcp_f32_e32 v87, v87
	v_pk_mul_f32 v[80:81], v[88:89], v[80:81]
	v_pk_mul_f32 v[82:83], v[90:91], v[82:83]
	v_pk_mul_f32 v[84:85], v[110:111], v[84:85]
	s_lshl_b32 s48, s95, 8
	v_cvt_pk_bf16_f32 v80, v80, v81
	v_cvt_pk_bf16_f32 v81, v82, v83
	v_cvt_pk_bf16_f32 v82, v84, v85
	v_lshl_add_u64 v[84:85], v[100:101], 0, s[48:49]
	v_lshl_add_u64 v[84:85], v[146:147], 1, v[84:85]
	v_pk_mul_f32 v[86:87], v[112:113], v[86:87]
	v_add_co_u32_e32 v84, vcc, 0x811f000, v84
	v_cvt_pk_bf16_f32 v83, v86, v87
	s_nop 0
	v_addc_co_u32_e32 v85, vcc, 0, v85, vcc
	global_store_dwordx4 v[84:85], v[80:83], off offset:2560
	s_mov_b64 s[14:15], 0
	s_branch .LBB0_737

.LBB0_737:
	v_add_f32_e32 v80, v204, v205
	v_fmamk_f32 v80, v80, 0x3a800000, v226
	v_rsq_f32_e32 v94, v80
	v_add_u32_e32 v80, 48, v148
	v_ashrrev_i32_e32 v81, 31, v80
	v_lshlrev_b64 v[84:85], 11, v[80:81]
	v_lshlrev_b64 v[88:89], 10, v[80:81]
	v_lshl_add_u64 v[98:99], s[50:51], 0, v[84:85]
	v_lshl_add_u64 v[82:83], s[72:73], 0, v[88:89]
	v_lshl_add_u64 v[86:87], s[52:53], 0, v[84:85]
	v_lshl_add_u64 v[84:85], s[96:97], 0, v[88:89]
	v_pk_mul_f32 v[92:93], v[76:77], v[94:95] op_sel_hi:[1,0]
	v_pk_mul_f32 v[102:103], v[78:79], v[94:95] op_sel_hi:[1,0]
	v_pk_mul_f32 v[104:105], v[72:73], v[94:95] op_sel_hi:[1,0]
	v_pk_mul_f32 v[106:107], v[74:75], v[94:95] op_sel_hi:[1,0]
	s_and_b64 vcc, exec, s[10:11]
	s_mov_b64 s[14:15], -1
	s_cbranch_vccnz .LBB0_759
	s_cmp_lt_u32 s94, 10
	s_cbranch_scc1 .LBB0_756
	s_cmp_lt_u32 s94, 14
	s_cbranch_scc1 .LBB0_753
	s_cmp_lt_u32 s94, 18
	s_cbranch_scc1 .LBB0_750
	s_cmp_lt_u32 s94, 22
	s_cbranch_scc1 .LBB0_747
	s_cmp_lt_u32 s94, 26
	s_cbranch_scc1 .LBB0_744
	v_mul_f32_e32 v73, 0xbfb8aa3b, v92
	v_mul_f32_e32 v74, 0xbfb8aa3b, v93
	v_mul_f32_e32 v75, 0xbfb8aa3b, v102
	v_mul_f32_e32 v77, 0xbfb8aa3b, v103
	v_exp_f32_e32 v73, v73
	v_exp_f32_e32 v74, v74
	v_exp_f32_e32 v75, v75
	v_exp_f32_e32 v77, v77
	v_mul_f32_e32 v78, 0xbfb8aa3b, v104
	v_mul_f32_e32 v79, 0xbfb8aa3b, v105
	v_mul_f32_e32 v88, 0xbfb8aa3b, v106
	v_mul_f32_e32 v89, 0xbfb8aa3b, v107
	v_exp_f32_e32 v78, v78
	v_exp_f32_e32 v79, v79
	v_exp_f32_e32 v88, v88
	v_exp_f32_e32 v89, v89
	v_add_f32_e32 v73, 1.0, v73
	v_add_f32_e32 v74, 1.0, v74
	v_add_f32_e32 v75, 1.0, v75
	v_add_f32_e32 v77, 1.0, v77
	v_rcp_f32_e32 v73, v73
	v_rcp_f32_e32 v74, v74
	v_rcp_f32_e32 v75, v75
	v_rcp_f32_e32 v77, v77
	v_lshl_add_u32 v72, s93, 8, v195
	v_add_f32_e32 v78, 1.0, v78
	v_add_f32_e32 v79, 1.0, v79
	v_add_f32_e32 v88, 1.0, v88
	v_add_f32_e32 v89, 1.0, v89
	v_ashrrev_i32_e32 v76, 10, v72
	v_rcp_f32_e32 v78, v78
	v_rcp_f32_e32 v79, v79
	v_rcp_f32_e32 v88, v88
	v_rcp_f32_e32 v89, v89
	v_and_b32_e32 v90, 0x3f8, v72
	v_cvt_pk_bf16_f32 v72, v73, v74
	v_cvt_pk_bf16_f32 v73, v75, v77
	v_ashrrev_i32_e32 v77, 31, v76
	v_lshlrev_b64 v[76:77], 25, v[76:77]
	v_lshl_add_u64 v[76:77], v[98:99], 0, v[76:77]
	v_lshlrev_b32_e32 v96, 1, v90
	v_cvt_pk_bf16_f32 v74, v78, v79
	v_cvt_pk_bf16_f32 v75, v88, v89
	v_lshl_add_u64 v[76:77], v[76:77], 0, v[96:97]
	s_mov_b64 s[14:15], 0
	global_store_dwordx4 v[76:77], v[72:75], off
	s_mov_b64 s[14:15], 0
	s_branch .LBB0_759
.LBB0_744:
	s_andn2_b64 vcc, exec, s[14:15]
	s_cbranch_vccnz .LBB0_746
	s_mov_b32 s14, 0x3e0293ee
	v_pk_mul_f32 v[72:73], v[92:93], s[14:15] op_sel_hi:[1,0]
	v_pk_mul_f32 v[74:75], v[102:103], s[14:15] op_sel_hi:[1,0]
	v_pk_mul_f32 v[76:77], v[104:105], s[14:15] op_sel_hi:[1,0]
	s_lshl_b32 s48, s93, 8
	v_cvt_pk_bf16_f32 v72, v72, v73
	v_cvt_pk_bf16_f32 v73, v74, v75
	v_cvt_pk_bf16_f32 v74, v76, v77
	v_lshl_add_u64 v[76:77], s[48:49], 1, v[82:83]
	v_lshl_add_u64 v[76:77], v[146:147], 1, v[76:77]
	v_pk_mul_f32 v[78:79], v[106:107], s[14:15] op_sel_hi:[1,0]
	v_add_co_u32_e32 v76, vcc, 0xe11e000, v76
	v_cvt_pk_bf16_f32 v75, v78, v79
	s_nop 0
	v_addc_co_u32_e32 v77, vcc, 0, v77, vcc
	global_store_dwordx4 v[76:77], v[72:75], off offset:2560
	s_mov_b64 s[14:15], 0
	s_branch .LBB0_759

.LBB0_747:
	s_andn2_b64 vcc, exec, s[14:15]
	s_cbranch_vccnz .LBB0_749
	v_mul_f32_e32 v72, 0xbfb8aa3b, v92
	v_mul_f32_e32 v73, 0xbfb8aa3b, v93
	v_mul_f32_e32 v74, 0xbfb8aa3b, v102
	v_mul_f32_e32 v75, 0xbfb8aa3b, v103
	v_mul_f32_e32 v76, 0xbfb8aa3b, v104
	v_mul_f32_e32 v77, 0xbfb8aa3b, v105
	v_exp_f32_e32 v72, v72
	v_exp_f32_e32 v73, v73
	v_exp_f32_e32 v74, v74
	v_exp_f32_e32 v75, v75
	v_exp_f32_e32 v76, v76
	v_exp_f32_e32 v77, v77
	v_mul_f32_e32 v78, 0xbfb8aa3b, v106
	v_mul_f32_e32 v79, 0xbfb8aa3b, v107
	v_exp_f32_e32 v78, v78
	v_exp_f32_e32 v79, v79
	v_add_f32_e32 v72, 1.0, v72
	v_add_f32_e32 v73, 1.0, v73
	v_add_f32_e32 v74, 1.0, v74
	v_add_f32_e32 v75, 1.0, v75
	v_add_f32_e32 v76, 1.0, v76
	v_add_f32_e32 v77, 1.0, v77
	v_rcp_f32_e32 v72, v72
	v_rcp_f32_e32 v73, v73
	v_rcp_f32_e32 v74, v74
	v_rcp_f32_e32 v75, v75
	v_rcp_f32_e32 v76, v76
	v_rcp_f32_e32 v77, v77
	v_add_f32_e32 v78, 1.0, v78
	v_add_f32_e32 v79, 1.0, v79
	v_rcp_f32_e32 v78, v78
	v_rcp_f32_e32 v79, v79
	v_pk_mul_f32 v[72:73], v[92:93], v[72:73]
	v_pk_mul_f32 v[74:75], v[102:103], v[74:75]
	v_pk_mul_f32 v[76:77], v[104:105], v[76:77]
	s_lshl_b32 s48, s93, 8
	v_cvt_pk_bf16_f32 v72, v72, v73
	v_cvt_pk_bf16_f32 v73, v74, v75
	v_cvt_pk_bf16_f32 v74, v76, v77
	v_lshl_add_u64 v[76:77], s[48:49], 1, v[82:83]
	v_lshl_add_u64 v[76:77], v[146:147], 1, v[76:77]
	v_pk_mul_f32 v[78:79], v[106:107], v[78:79]
	v_add_co_u32_e32 v76, vcc, 0xd11e000, v76
	v_cvt_pk_bf16_f32 v75, v78, v79
	s_nop 0
	v_addc_co_u32_e32 v77, vcc, 0, v77, vcc
	global_store_dwordx4 v[76:77], v[72:75], off offset:3584
	s_mov_b64 s[14:15], 0
	s_branch .LBB0_759

.LBB0_750:
	s_andn2_b64 vcc, exec, s[14:15]
	s_cbranch_vccnz .LBB0_752
	s_lshl_b32 s48, s93, 8
	v_lshl_add_u64 v[76:77], s[48:49], 1, v[82:83]
	v_lshl_add_u64 v[76:77], v[146:147], 1, v[76:77]
	v_add_co_u32_e32 v76, vcc, 0xc11f000, v76
	v_cvt_pk_bf16_f32 v72, v92, v93
	v_cvt_pk_bf16_f32 v73, v102, v103
	v_cvt_pk_bf16_f32 v74, v104, v105
	v_cvt_pk_bf16_f32 v75, v106, v107
	v_addc_co_u32_e32 v77, vcc, 0, v77, vcc
	global_store_dwordx4 v[76:77], v[72:75], off offset:512
	s_mov_b64 s[14:15], 0
	s_branch .LBB0_759

.LBB0_768:
	v_mov_b32_e32 v95, v94
	v_pk_mul_f32 v[72:73], v[68:69], v[94:95]
	v_pk_mul_f32 v[74:75], v[70:71], v[94:95]
	v_pk_mul_f32 v[92:93], v[64:65], v[94:95]
	v_pk_mul_f32 v[94:95], v[66:67], v[94:95]
	s_and_b64 vcc, exec, s[12:13]
	s_mov_b64 s[14:15], -1
	s_cbranch_vccnz .LBB0_795
	s_cmp_eq_u32 s93, 2
	s_cbranch_scc1 .LBB0_791
	s_cmp_lt_u32 s94, 10
	s_cbranch_scc1 .LBB0_788
	s_cmp_lt_u32 s94, 14
	s_cbranch_scc1 .LBB0_785
	s_cmp_lt_u32 s94, 18
	s_cbranch_scc1 .LBB0_782
	s_cmp_lt_u32 s94, 22
	s_cbranch_scc1 .LBB0_779
	s_cmp_lt_u32 s94, 26
	s_cbranch_scc1 .LBB0_776
	v_mul_f32_e32 v65, 0xbfb8aa3b, v72
	v_mul_f32_e32 v66, 0xbfb8aa3b, v73
	v_mul_f32_e32 v67, 0xbfb8aa3b, v74
	v_mul_f32_e32 v69, 0xbfb8aa3b, v75
	v_exp_f32_e32 v65, v65
	v_exp_f32_e32 v66, v66
	v_exp_f32_e32 v67, v67
	v_exp_f32_e32 v69, v69
	v_mul_f32_e32 v81, 0xbfb8aa3b, v94
	v_mul_f32_e32 v96, 0xbfb8aa3b, v95
	v_mul_f32_e32 v70, 0xbfb8aa3b, v92
	v_mul_f32_e32 v71, 0xbfb8aa3b, v93
	v_exp_f32_e32 v81, v81
	v_exp_f32_e32 v96, v96
	v_exp_f32_e32 v70, v70
	v_exp_f32_e32 v71, v71
	v_add_f32_e32 v65, 1.0, v65
	v_add_f32_e32 v66, 1.0, v66
	v_add_f32_e32 v67, 1.0, v67
	v_add_f32_e32 v69, 1.0, v69
	v_rcp_f32_e32 v65, v65
	v_rcp_f32_e32 v66, v66
	v_rcp_f32_e32 v67, v67
	v_rcp_f32_e32 v69, v69
	v_add_f32_e32 v81, 1.0, v81
	v_add_f32_e32 v96, 1.0, v96
	v_lshl_add_u32 v64, s95, 7, v195
	v_add_f32_e32 v70, 1.0, v70
	v_add_f32_e32 v71, 1.0, v71
	v_rcp_f32_e32 v81, v81
	v_rcp_f32_e32 v96, v96
	v_ashrrev_i32_e32 v68, 10, v64
	v_rcp_f32_e32 v70, v70
	v_rcp_f32_e32 v71, v71
	v_and_b32_e32 v102, 0x3f8, v64
	v_cvt_pk_bf16_f32 v64, v65, v66
	v_cvt_pk_bf16_f32 v65, v67, v69
	v_ashrrev_i32_e32 v69, 31, v68
	v_lshlrev_b64 v[68:69], 25, v[68:69]
	v_cvt_pk_bf16_f32 v67, v81, v96
	v_lshl_add_u64 v[68:69], v[98:99], 0, v[68:69]
	v_lshlrev_b32_e32 v96, 1, v102
	v_cvt_pk_bf16_f32 v66, v70, v71
	v_lshl_add_u64 v[68:69], v[68:69], 0, v[96:97]
	s_mov_b64 s[14:15], 0
	global_store_dwordx4 v[68:69], v[64:67], off
	s_mov_b64 s[14:15], 0
	s_branch .LBB0_804
.LBB0_776:
	s_andn2_b64 vcc, exec, s[14:15]
	s_cbranch_vccnz .LBB0_778
	s_mov_b32 s14, 0x3e0293ee
	v_pk_mul_f32 v[64:65], v[72:73], s[14:15] op_sel_hi:[1,0]
	v_pk_mul_f32 v[66:67], v[74:75], s[14:15] op_sel_hi:[1,0]
	v_pk_mul_f32 v[68:69], v[92:93], s[14:15] op_sel_hi:[1,0]
	s_lshl_b32 s48, s95, 8
	v_cvt_pk_bf16_f32 v64, v64, v65
	v_cvt_pk_bf16_f32 v65, v66, v67
	v_cvt_pk_bf16_f32 v66, v68, v69
	v_lshl_add_u64 v[68:69], v[82:83], 0, s[48:49]
	v_lshl_add_u64 v[68:69], v[146:147], 1, v[68:69]
	v_pk_mul_f32 v[70:71], v[94:95], s[14:15] op_sel_hi:[1,0]
	v_add_co_u32_e32 v68, vcc, 0xe11e000, v68
	v_cvt_pk_bf16_f32 v67, v70, v71
	s_nop 0
	v_addc_co_u32_e32 v69, vcc, 0, v69, vcc
	global_store_dwordx4 v[68:69], v[64:67], off offset:2560
	s_mov_b64 s[14:15], 0
	s_branch .LBB0_804

.LBB0_779:
	s_andn2_b64 vcc, exec, s[14:15]
	s_cbranch_vccnz .LBB0_781
	v_mul_f32_e32 v64, 0xbfb8aa3b, v72
	v_mul_f32_e32 v65, 0xbfb8aa3b, v73
	v_mul_f32_e32 v66, 0xbfb8aa3b, v74
	v_mul_f32_e32 v67, 0xbfb8aa3b, v75
	v_mul_f32_e32 v68, 0xbfb8aa3b, v92
	v_mul_f32_e32 v69, 0xbfb8aa3b, v93
	v_exp_f32_e32 v64, v64
	v_exp_f32_e32 v65, v65
	v_exp_f32_e32 v66, v66
	v_exp_f32_e32 v67, v67
	v_exp_f32_e32 v68, v68
	v_exp_f32_e32 v69, v69
	v_mul_f32_e32 v70, 0xbfb8aa3b, v94
	v_mul_f32_e32 v71, 0xbfb8aa3b, v95
	v_exp_f32_e32 v70, v70
	v_exp_f32_e32 v71, v71
	v_add_f32_e32 v64, 1.0, v64
	v_add_f32_e32 v65, 1.0, v65
	v_add_f32_e32 v66, 1.0, v66
	v_add_f32_e32 v67, 1.0, v67
	v_add_f32_e32 v68, 1.0, v68
	v_add_f32_e32 v69, 1.0, v69
	v_rcp_f32_e32 v64, v64
	v_rcp_f32_e32 v65, v65
	v_rcp_f32_e32 v66, v66
	v_rcp_f32_e32 v67, v67
	v_rcp_f32_e32 v68, v68
	v_rcp_f32_e32 v69, v69
	v_add_f32_e32 v70, 1.0, v70
	v_add_f32_e32 v71, 1.0, v71
	v_rcp_f32_e32 v70, v70
	v_rcp_f32_e32 v71, v71
	v_pk_mul_f32 v[64:65], v[72:73], v[64:65]
	v_pk_mul_f32 v[66:67], v[74:75], v[66:67]
	v_pk_mul_f32 v[68:69], v[92:93], v[68:69]
	s_lshl_b32 s48, s95, 8
	v_cvt_pk_bf16_f32 v64, v64, v65
	v_cvt_pk_bf16_f32 v65, v66, v67
	v_cvt_pk_bf16_f32 v66, v68, v69
	v_lshl_add_u64 v[68:69], v[82:83], 0, s[48:49]
	v_lshl_add_u64 v[68:69], v[146:147], 1, v[68:69]
	v_pk_mul_f32 v[70:71], v[94:95], v[70:71]
	v_add_co_u32_e32 v68, vcc, 0xd11e000, v68
	v_cvt_pk_bf16_f32 v67, v70, v71
	s_nop 0
	v_addc_co_u32_e32 v69, vcc, 0, v69, vcc
	global_store_dwordx4 v[68:69], v[64:67], off offset:3584
	s_mov_b64 s[14:15], 0
	s_branch .LBB0_804

.LBB0_782:
	s_andn2_b64 vcc, exec, s[14:15]
	s_cbranch_vccnz .LBB0_784
	s_lshl_b32 s48, s95, 8
	v_lshl_add_u64 v[68:69], v[82:83], 0, s[48:49]
	v_lshl_add_u64 v[68:69], v[146:147], 1, v[68:69]
	v_add_co_u32_e32 v68, vcc, 0xc11f000, v68
	v_cvt_pk_bf16_f32 v64, v72, v73
	v_cvt_pk_bf16_f32 v65, v74, v75
	v_cvt_pk_bf16_f32 v66, v92, v93
	v_cvt_pk_bf16_f32 v67, v94, v95
	v_addc_co_u32_e32 v69, vcc, 0, v69, vcc
	global_store_dwordx4 v[68:69], v[64:67], off offset:512
	s_mov_b64 s[14:15], 0
	s_branch .LBB0_804

.LBB0_785:
	s_andn2_b64 vcc, exec, s[14:15]
	s_cbranch_vccnz .LBB0_787
	v_lshl_add_u32 v98, s95, 7, v194
	v_ashrrev_i32_e32 v99, 31, v98
	v_lshlrev_b64 v[102:103], 2, v[98:99]
	v_lshl_add_u64 v[68:69], s[80:81], 0, v[102:103]
	global_load_dwordx4 v[64:67], v[68:69], off offset:16
	s_nop 0
	global_load_dwordx4 v[68:71], v[68:69], off
	v_max_f32_e32 v81, v72, v72
	s_mov_b32 s17, 0xc2700000
	v_med3_f32 v81, v81, s17, v231
	v_mul_f32_e32 v81, 0xbfb8aa3b, v81
	v_exp_f32_e32 v104, v81
	s_mov_b32 s1, 0x3f317217
	v_lshl_add_u64 v[86:87], v[86:87], 0, v[102:103]
	v_add_f32_e32 v81, 1.0, v104
	v_rcp_f32_e32 v106, v81
	v_max_f32_e32 v81, v73, v73
	v_med3_f32 v81, v81, s17, v231
	v_mul_f32_e32 v81, 0xbfb8aa3b, v81
	v_exp_f32_e32 v105, v81
	s_waitcnt vmcnt(0)
	v_pk_add_f32 v[112:113], v[64:65], 1.0 op_sel_hi:[1,0] neg_lo:[1,0] neg_hi:[1,0]
	v_pk_add_f32 v[108:109], v[68:69], 1.0 op_sel_hi:[1,0] neg_lo:[1,0] neg_hi:[1,0]
	v_add_f32_e32 v81, 1.0, v105
	v_fma_f32 v68, v106, v108, v68
	v_cmp_gt_f32_e32 vcc, s16, v68
	v_rcp_f32_e32 v107, v81
	v_pk_add_f32 v[110:111], v[70:71], 1.0 op_sel_hi:[1,0] neg_lo:[1,0] neg_hi:[1,0]
	v_cndmask_b32_e64 v81, 0, 32, vcc
	v_ldexp_f32 v68, v68, v81
	v_log_f32_e32 v68, v68
	v_fma_f32 v69, v107, v109, v69
	v_pk_mul_f32 v[104:105], v[104:105], v[106:107]
	v_pk_add_f32 v[114:115], v[66:67], 1.0 op_sel_hi:[1,0] neg_lo:[1,0] neg_hi:[1,0]
	v_mul_f32_e32 v81, 0x3f317217, v68
	v_fma_f32 v81, v68, s1, -v81
	v_fmac_f32_e32 v81, 0x3377d1cf, v68
	v_fmac_f32_e32 v81, 0x3f317217, v68
	v_cmp_lt_f32_e64 s[14:15], |v68|, s4
	v_pk_mul_f32 v[104:105], v[104:105], v[108:109]
	s_nop 0
	v_cndmask_b32_e64 v68, v68, v81, s[14:15]
	v_cndmask_b32_e32 v81, 0, v232, vcc
	v_cmp_gt_f32_e32 vcc, s16, v69
	v_sub_f32_e32 v68, v68, v81
	s_nop 0
	v_cndmask_b32_e64 v81, 0, 32, vcc
	v_ldexp_f32 v69, v69, v81
	v_log_f32_e32 v69, v69
	s_nop 0
	v_mul_f32_e32 v81, 0x3f317217, v69
	v_fma_f32 v81, v69, s1, -v81
	v_fmac_f32_e32 v81, 0x3377d1cf, v69
	v_fmac_f32_e32 v81, 0x3f317217, v69
	v_cmp_lt_f32_e64 s[14:15], |v69|, s4
	s_nop 1
	v_cndmask_b32_e64 v69, v69, v81, s[14:15]
	v_cndmask_b32_e32 v81, 0, v232, vcc
	v_sub_f32_e32 v69, v69, v81
	v_max_f32_e32 v81, v74, v74
	v_med3_f32 v81, v81, s17, v231
	v_mul_f32_e32 v81, 0xbfb8aa3b, v81
	v_exp_f32_e32 v106, v81
	s_nop 0
	v_add_f32_e32 v81, 1.0, v106
	v_rcp_f32_e32 v108, v81
	v_max_f32_e32 v81, v75, v75
	v_med3_f32 v81, v81, s17, v231
	v_mul_f32_e32 v81, 0xbfb8aa3b, v81
	v_exp_f32_e32 v107, v81
	v_fma_f32 v70, v108, v110, v70
	v_cmp_gt_f32_e32 vcc, s16, v70
	v_add_f32_e32 v81, 1.0, v107
	v_rcp_f32_e32 v109, v81
	v_cndmask_b32_e64 v81, 0, 32, vcc
	v_ldexp_f32 v70, v70, v81
	v_log_f32_e32 v70, v70
	v_fmac_f32_e32 v71, v109, v111
	v_pk_mul_f32 v[106:107], v[106:107], v[108:109]
	v_mul_f32_e32 v81, 0x3f317217, v70
	v_fma_f32 v81, v70, s1, -v81
	v_fmac_f32_e32 v81, 0x3377d1cf, v70
	v_fmac_f32_e32 v81, 0x3f317217, v70
	v_cmp_lt_f32_e64 s[14:15], |v70|, s4
	v_pk_mul_f32 v[106:107], v[106:107], v[110:111]
	s_nop 0
	v_cndmask_b32_e64 v70, v70, v81, s[14:15]
	v_cndmask_b32_e32 v81, 0, v232, vcc
	v_cmp_gt_f32_e32 vcc, s16, v71
	v_sub_f32_e32 v70, v70, v81
	s_nop 0
	v_cndmask_b32_e64 v81, 0, 32, vcc
	v_ldexp_f32 v71, v71, v81
	v_log_f32_e32 v71, v71
	s_nop 0
	v_mul_f32_e32 v81, 0x3f317217, v71
	v_fma_f32 v81, v71, s1, -v81
	v_fmac_f32_e32 v81, 0x3377d1cf, v71
	v_fmac_f32_e32 v81, 0x3f317217, v71
	v_cmp_lt_f32_e64 s[14:15], |v71|, s4
	s_nop 1
	v_cndmask_b32_e64 v71, v71, v81, s[14:15]
	v_cndmask_b32_e32 v81, 0, v232, vcc
	v_sub_f32_e32 v71, v71, v81
	v_max_f32_e32 v81, v92, v92
	v_med3_f32 v81, v81, s17, v231
	v_mul_f32_e32 v81, 0xbfb8aa3b, v81
	v_exp_f32_e32 v110, v81
	s_nop 0
	v_add_f32_e32 v81, 1.0, v110
	v_rcp_f32_e32 v108, v81
	v_max_f32_e32 v81, v93, v93
	v_med3_f32 v81, v81, s17, v231
	v_mul_f32_e32 v81, 0xbfb8aa3b, v81
	v_exp_f32_e32 v111, v81
	v_fma_f32 v64, v108, v112, v64
	v_cmp_gt_f32_e32 vcc, s16, v64
	v_add_f32_e32 v81, 1.0, v111
	v_rcp_f32_e32 v109, v81
	v_cndmask_b32_e64 v81, 0, 32, vcc
	v_ldexp_f32 v64, v64, v81
	v_log_f32_e32 v64, v64
	v_fma_f32 v65, v109, v113, v65
	v_pk_mul_f32 v[110:111], v[110:111], v[108:109]
	v_mul_f32_e32 v81, 0x3f317217, v64
	v_fma_f32 v81, v64, s1, -v81
	v_fmac_f32_e32 v81, 0x3377d1cf, v64
	v_fmac_f32_e32 v81, 0x3f317217, v64
	v_cmp_lt_f32_e64 s[14:15], |v64|, s4
	v_pk_mul_f32 v[110:111], v[110:111], v[112:113]
	s_nop 0
	v_cndmask_b32_e64 v64, v64, v81, s[14:15]
	v_cndmask_b32_e32 v81, 0, v232, vcc
	v_cmp_gt_f32_e32 vcc, s16, v65
	v_sub_f32_e32 v64, v64, v81
	s_nop 0
	v_cndmask_b32_e64 v81, 0, 32, vcc
	v_ldexp_f32 v65, v65, v81
	v_log_f32_e32 v65, v65
	s_nop 0
	v_mul_f32_e32 v81, 0x3f317217, v65
	v_fma_f32 v81, v65, s1, -v81
	v_fmac_f32_e32 v81, 0x3377d1cf, v65
	v_fmac_f32_e32 v81, 0x3f317217, v65
	v_cmp_lt_f32_e64 s[14:15], |v65|, s4
	s_nop 1
	v_cndmask_b32_e64 v65, v65, v81, s[14:15]
	v_cndmask_b32_e32 v81, 0, v232, vcc
	v_sub_f32_e32 v65, v65, v81
	v_max_f32_e32 v81, v94, v94
	v_med3_f32 v81, v81, s17, v231
	v_mul_f32_e32 v81, 0xbfb8aa3b, v81
	v_exp_f32_e32 v108, v81
	s_nop 0
	v_add_f32_e32 v81, 1.0, v108
	v_rcp_f32_e32 v112, v81
	v_max_f32_e32 v81, v95, v95
	v_med3_f32 v81, v81, s17, v231
	v_mul_f32_e32 v81, 0xbfb8aa3b, v81
	v_exp_f32_e32 v109, v81
	v_fma_f32 v66, v112, v114, v66
	v_cmp_gt_f32_e32 vcc, s16, v66
	v_add_f32_e32 v81, 1.0, v109
	v_rcp_f32_e32 v113, v81
	v_cndmask_b32_e64 v81, 0, 32, vcc
	v_ldexp_f32 v66, v66, v81
	v_log_f32_e32 v66, v66
	v_fmac_f32_e32 v67, v113, v115
	v_pk_mul_f32 v[108:109], v[108:109], v[112:113]
	v_mul_f32_e32 v81, 0x3f317217, v66
	v_fma_f32 v81, v66, s1, -v81
	v_fmac_f32_e32 v81, 0x3377d1cf, v66
	v_fmac_f32_e32 v81, 0x3f317217, v66
	v_cmp_lt_f32_e64 s[14:15], |v66|, s4
	v_pk_mul_f32 v[108:109], v[108:109], v[114:115]
	s_nop 0
	v_cndmask_b32_e64 v66, v66, v81, s[14:15]
	v_cndmask_b32_e32 v81, 0, v232, vcc
	v_cmp_gt_f32_e32 vcc, s16, v67
	v_sub_f32_e32 v66, v66, v81
	s_nop 0
	v_cndmask_b32_e64 v81, 0, 32, vcc
	v_ldexp_f32 v67, v67, v81
	v_log_f32_e32 v67, v67
	s_nop 0
	v_mul_f32_e32 v81, 0x3f317217, v67
	v_fma_f32 v81, v67, s1, -v81
	v_fmac_f32_e32 v81, 0x3377d1cf, v67
	v_fmac_f32_e32 v81, 0x3f317217, v67
	v_cmp_lt_f32_e64 s[14:15], |v67|, s4
	s_nop 1
	v_cndmask_b32_e64 v67, v67, v81, s[14:15]
	v_cndmask_b32_e32 v81, 0, v232, vcc
	v_sub_f32_e32 v67, v67, v81
	global_store_dwordx4 v[86:87], v[68:71], off
	global_store_dwordx4 v[86:87], v[64:67], off offset:16
	s_nop 0
	v_lshl_add_u64 v[68:69], v[98:99], 1, v[84:85]
	v_cvt_pk_bf16_f32 v64, v104, v105
	v_cvt_pk_bf16_f32 v65, v106, v107
	v_cvt_pk_bf16_f32 v66, v110, v111
	v_cvt_pk_bf16_f32 v67, v108, v109
	global_store_dwordx4 v[68:69], v[64:67], off
	s_mov_b64 s[14:15], 0
	s_branch .LBB0_804

.LBB0_788:
	s_andn2_b64 vcc, exec, s[14:15]
	s_cbranch_vccnz .LBB0_790
	v_mul_f32_e32 v64, 0xbfb8aa3b, v72
	v_mul_f32_e32 v65, 0xbfb8aa3b, v73
	v_mul_f32_e32 v66, 0xbfb8aa3b, v74
	v_mul_f32_e32 v67, 0xbfb8aa3b, v75
	v_mul_f32_e32 v68, 0xbfb8aa3b, v92
	v_mul_f32_e32 v69, 0xbfb8aa3b, v93
	v_exp_f32_e32 v64, v64
	v_exp_f32_e32 v65, v65
	v_exp_f32_e32 v66, v66
	v_exp_f32_e32 v67, v67
	v_exp_f32_e32 v68, v68
	v_exp_f32_e32 v69, v69
	v_mul_f32_e32 v70, 0xbfb8aa3b, v94
	v_mul_f32_e32 v71, 0xbfb8aa3b, v95
	v_exp_f32_e32 v70, v70
	v_exp_f32_e32 v71, v71
	v_add_f32_e32 v64, 1.0, v64
	v_add_f32_e32 v65, 1.0, v65
	v_add_f32_e32 v66, 1.0, v66
	v_add_f32_e32 v67, 1.0, v67
	v_add_f32_e32 v68, 1.0, v68
	v_add_f32_e32 v69, 1.0, v69
	v_rcp_f32_e32 v64, v64
	v_rcp_f32_e32 v65, v65
	v_rcp_f32_e32 v66, v66
	v_rcp_f32_e32 v67, v67
	v_rcp_f32_e32 v68, v68
	v_rcp_f32_e32 v69, v69
	v_add_f32_e32 v70, 1.0, v70
	v_add_f32_e32 v71, 1.0, v71
	v_rcp_f32_e32 v70, v70
	v_rcp_f32_e32 v71, v71
	v_pk_mul_f32 v[64:65], v[72:73], v[64:65]
	v_pk_mul_f32 v[66:67], v[74:75], v[66:67]
	v_pk_mul_f32 v[68:69], v[92:93], v[68:69]
	s_lshl_b32 s48, s95, 8
	v_cvt_pk_bf16_f32 v64, v64, v65
	v_cvt_pk_bf16_f32 v65, v66, v67
	v_cvt_pk_bf16_f32 v66, v68, v69
	v_lshl_add_u64 v[68:69], v[82:83], 0, s[48:49]
	v_lshl_add_u64 v[68:69], v[146:147], 1, v[68:69]
	v_pk_mul_f32 v[70:71], v[94:95], v[70:71]
	v_add_co_u32_e32 v68, vcc, 0x811f000, v68
	v_cvt_pk_bf16_f32 v67, v70, v71
	s_nop 0
	v_addc_co_u32_e32 v69, vcc, 0, v69, vcc
	global_store_dwordx4 v[68:69], v[64:67], off offset:2560
	s_mov_b64 s[14:15], 0
	s_branch .LBB0_804

.LBB0_804:
	v_add_f32_e32 v64, v202, v203
	v_fmamk_f32 v64, v64, 0x3a800000, v226
	v_rsq_f32_e32 v78, v64
	v_add_u32_e32 v64, 0x80, v148
	v_ashrrev_i32_e32 v65, 31, v64
	v_lshlrev_b64 v[68:69], 11, v[64:65]
	v_lshlrev_b64 v[72:73], 10, v[64:65]
	v_lshl_add_u64 v[80:81], s[50:51], 0, v[68:69]
	v_lshl_add_u64 v[66:67], s[72:73], 0, v[72:73]
	v_lshl_add_u64 v[70:71], s[52:53], 0, v[68:69]
	v_lshl_add_u64 v[68:69], s[96:97], 0, v[72:73]
	v_pk_mul_f32 v[76:77], v[60:61], v[78:79] op_sel_hi:[1,0]
	v_pk_mul_f32 v[84:85], v[62:63], v[78:79] op_sel_hi:[1,0]
	v_pk_mul_f32 v[86:87], v[56:57], v[78:79] op_sel_hi:[1,0]
	v_pk_mul_f32 v[88:89], v[58:59], v[78:79] op_sel_hi:[1,0]
	s_and_b64 vcc, exec, s[10:11]
	s_mov_b64 s[14:15], -1
	s_cbranch_vccnz .LBB0_826
	s_cmp_lt_u32 s94, 10
	s_cbranch_scc1 .LBB0_823
	s_cmp_lt_u32 s94, 14
	s_cbranch_scc1 .LBB0_820
	s_cmp_lt_u32 s94, 18
	s_cbranch_scc1 .LBB0_817
	s_cmp_lt_u32 s94, 22
	s_cbranch_scc1 .LBB0_814
	s_cmp_lt_u32 s94, 26
	s_cbranch_scc1 .LBB0_811
	v_mul_f32_e32 v57, 0xbfb8aa3b, v76
	v_mul_f32_e32 v58, 0xbfb8aa3b, v77
	v_mul_f32_e32 v59, 0xbfb8aa3b, v84
	v_mul_f32_e32 v61, 0xbfb8aa3b, v85
	v_exp_f32_e32 v57, v57
	v_exp_f32_e32 v58, v58
	v_exp_f32_e32 v59, v59
	v_exp_f32_e32 v61, v61
	v_mul_f32_e32 v62, 0xbfb8aa3b, v86
	v_mul_f32_e32 v63, 0xbfb8aa3b, v87
	v_mul_f32_e32 v72, 0xbfb8aa3b, v88
	v_mul_f32_e32 v73, 0xbfb8aa3b, v89
	v_exp_f32_e32 v62, v62
	v_exp_f32_e32 v63, v63
	v_exp_f32_e32 v72, v72
	v_exp_f32_e32 v73, v73
	v_add_f32_e32 v57, 1.0, v57
	v_add_f32_e32 v58, 1.0, v58
	v_add_f32_e32 v59, 1.0, v59
	v_add_f32_e32 v61, 1.0, v61
	v_rcp_f32_e32 v57, v57
	v_rcp_f32_e32 v58, v58
	v_rcp_f32_e32 v59, v59
	v_rcp_f32_e32 v61, v61
	v_lshl_add_u32 v56, s93, 8, v195
	v_add_f32_e32 v62, 1.0, v62
	v_add_f32_e32 v63, 1.0, v63
	v_add_f32_e32 v72, 1.0, v72
	v_add_f32_e32 v73, 1.0, v73
	v_ashrrev_i32_e32 v60, 10, v56
	v_rcp_f32_e32 v62, v62
	v_rcp_f32_e32 v63, v63
	v_rcp_f32_e32 v72, v72
	v_rcp_f32_e32 v73, v73
	v_and_b32_e32 v74, 0x3f8, v56
	v_cvt_pk_bf16_f32 v56, v57, v58
	v_cvt_pk_bf16_f32 v57, v59, v61
	v_ashrrev_i32_e32 v61, 31, v60
	v_lshlrev_b64 v[60:61], 25, v[60:61]
	v_lshl_add_u64 v[60:61], v[80:81], 0, v[60:61]
	v_lshlrev_b32_e32 v96, 1, v74
	v_cvt_pk_bf16_f32 v58, v62, v63
	v_cvt_pk_bf16_f32 v59, v72, v73
	v_lshl_add_u64 v[60:61], v[60:61], 0, v[96:97]
	s_mov_b64 s[14:15], 0
	global_store_dwordx4 v[60:61], v[56:59], off
	s_mov_b64 s[14:15], 0
	s_branch .LBB0_826
.LBB0_811:
	s_andn2_b64 vcc, exec, s[14:15]
	s_cbranch_vccnz .LBB0_813
	s_mov_b32 s14, 0x3e0293ee
	v_pk_mul_f32 v[56:57], v[76:77], s[14:15] op_sel_hi:[1,0]
	v_pk_mul_f32 v[58:59], v[84:85], s[14:15] op_sel_hi:[1,0]
	v_pk_mul_f32 v[60:61], v[86:87], s[14:15] op_sel_hi:[1,0]
	s_lshl_b32 s48, s93, 8
	v_cvt_pk_bf16_f32 v56, v56, v57
	v_cvt_pk_bf16_f32 v57, v58, v59
	v_cvt_pk_bf16_f32 v58, v60, v61
	v_lshl_add_u64 v[60:61], s[48:49], 1, v[66:67]
	v_lshl_add_u64 v[60:61], v[146:147], 1, v[60:61]
	v_pk_mul_f32 v[62:63], v[88:89], s[14:15] op_sel_hi:[1,0]
	v_add_co_u32_e32 v60, vcc, 0xe11e000, v60
	v_cvt_pk_bf16_f32 v59, v62, v63
	s_nop 0
	v_addc_co_u32_e32 v61, vcc, 0, v61, vcc
	global_store_dwordx4 v[60:61], v[56:59], off offset:2560
	s_mov_b64 s[14:15], 0
	s_branch .LBB0_826

.LBB0_814:
	s_andn2_b64 vcc, exec, s[14:15]
	s_cbranch_vccnz .LBB0_816
	v_mul_f32_e32 v56, 0xbfb8aa3b, v76
	v_mul_f32_e32 v57, 0xbfb8aa3b, v77
	v_mul_f32_e32 v58, 0xbfb8aa3b, v84
	v_mul_f32_e32 v59, 0xbfb8aa3b, v85
	v_mul_f32_e32 v60, 0xbfb8aa3b, v86
	v_mul_f32_e32 v61, 0xbfb8aa3b, v87
	v_exp_f32_e32 v56, v56
	v_exp_f32_e32 v57, v57
	v_exp_f32_e32 v58, v58
	v_exp_f32_e32 v59, v59
	v_exp_f32_e32 v60, v60
	v_exp_f32_e32 v61, v61
	v_mul_f32_e32 v62, 0xbfb8aa3b, v88
	v_mul_f32_e32 v63, 0xbfb8aa3b, v89
	v_exp_f32_e32 v62, v62
	v_exp_f32_e32 v63, v63
	v_add_f32_e32 v56, 1.0, v56
	v_add_f32_e32 v57, 1.0, v57
	v_add_f32_e32 v58, 1.0, v58
	v_add_f32_e32 v59, 1.0, v59
	v_add_f32_e32 v60, 1.0, v60
	v_add_f32_e32 v61, 1.0, v61
	v_rcp_f32_e32 v56, v56
	v_rcp_f32_e32 v57, v57
	v_rcp_f32_e32 v58, v58
	v_rcp_f32_e32 v59, v59
	v_rcp_f32_e32 v60, v60
	v_rcp_f32_e32 v61, v61
	v_add_f32_e32 v62, 1.0, v62
	v_add_f32_e32 v63, 1.0, v63
	v_rcp_f32_e32 v62, v62
	v_rcp_f32_e32 v63, v63
	v_pk_mul_f32 v[56:57], v[76:77], v[56:57]
	v_pk_mul_f32 v[58:59], v[84:85], v[58:59]
	v_pk_mul_f32 v[60:61], v[86:87], v[60:61]
	s_lshl_b32 s48, s93, 8
	v_cvt_pk_bf16_f32 v56, v56, v57
	v_cvt_pk_bf16_f32 v57, v58, v59
	v_cvt_pk_bf16_f32 v58, v60, v61
	v_lshl_add_u64 v[60:61], s[48:49], 1, v[66:67]
	v_lshl_add_u64 v[60:61], v[146:147], 1, v[60:61]
	v_pk_mul_f32 v[62:63], v[88:89], v[62:63]
	v_add_co_u32_e32 v60, vcc, 0xd11e000, v60
	v_cvt_pk_bf16_f32 v59, v62, v63
	s_nop 0
	v_addc_co_u32_e32 v61, vcc, 0, v61, vcc
	global_store_dwordx4 v[60:61], v[56:59], off offset:3584
	s_mov_b64 s[14:15], 0
	s_branch .LBB0_826

.LBB0_817:
	s_andn2_b64 vcc, exec, s[14:15]
	s_cbranch_vccnz .LBB0_819
	s_lshl_b32 s48, s93, 8
	v_lshl_add_u64 v[60:61], s[48:49], 1, v[66:67]
	v_lshl_add_u64 v[60:61], v[146:147], 1, v[60:61]
	v_add_co_u32_e32 v60, vcc, 0xc11f000, v60
	v_cvt_pk_bf16_f32 v56, v76, v77
	v_cvt_pk_bf16_f32 v57, v84, v85
	v_cvt_pk_bf16_f32 v58, v86, v87
	v_cvt_pk_bf16_f32 v59, v88, v89
	v_addc_co_u32_e32 v61, vcc, 0, v61, vcc
	global_store_dwordx4 v[60:61], v[56:59], off offset:512
	s_mov_b64 s[14:15], 0
	s_branch .LBB0_826

.LBB0_835:
	v_mov_b32_e32 v79, v78
	v_pk_mul_f32 v[56:57], v[52:53], v[78:79]
	v_pk_mul_f32 v[58:59], v[54:55], v[78:79]
	v_pk_mul_f32 v[76:77], v[48:49], v[78:79]
	v_pk_mul_f32 v[78:79], v[50:51], v[78:79]
	s_and_b64 vcc, exec, s[12:13]
	s_mov_b64 s[14:15], -1
	s_cbranch_vccnz .LBB0_862
	s_cmp_eq_u32 s93, 2
	s_cbranch_scc1 .LBB0_858
	s_cmp_lt_u32 s94, 10
	s_cbranch_scc1 .LBB0_855
	s_cmp_lt_u32 s94, 14
	s_cbranch_scc1 .LBB0_852
	s_cmp_lt_u32 s94, 18
	s_cbranch_scc1 .LBB0_849
	s_cmp_lt_u32 s94, 22
	s_cbranch_scc1 .LBB0_846
	s_cmp_lt_u32 s94, 26
	s_cbranch_scc1 .LBB0_843
	v_mul_f32_e32 v49, 0xbfb8aa3b, v56
	v_mul_f32_e32 v50, 0xbfb8aa3b, v57
	v_mul_f32_e32 v51, 0xbfb8aa3b, v58
	v_mul_f32_e32 v53, 0xbfb8aa3b, v59
	v_exp_f32_e32 v49, v49
	v_exp_f32_e32 v50, v50
	v_exp_f32_e32 v51, v51
	v_exp_f32_e32 v53, v53
	v_mul_f32_e32 v54, 0xbfb8aa3b, v76
	v_mul_f32_e32 v55, 0xbfb8aa3b, v77
	v_mul_f32_e32 v65, 0xbfb8aa3b, v78
	v_mul_f32_e32 v84, 0xbfb8aa3b, v79
	v_exp_f32_e32 v54, v54
	v_exp_f32_e32 v55, v55
	v_exp_f32_e32 v65, v65
	v_exp_f32_e32 v84, v84
	v_add_f32_e32 v49, 1.0, v49
	v_add_f32_e32 v50, 1.0, v50
	v_add_f32_e32 v51, 1.0, v51
	v_add_f32_e32 v53, 1.0, v53
	v_rcp_f32_e32 v49, v49
	v_rcp_f32_e32 v50, v50
	v_rcp_f32_e32 v51, v51
	v_rcp_f32_e32 v53, v53
	v_lshl_add_u32 v48, s95, 7, v195
	v_add_f32_e32 v54, 1.0, v54
	v_add_f32_e32 v55, 1.0, v55
	v_add_f32_e32 v65, 1.0, v65
	v_add_f32_e32 v84, 1.0, v84
	v_ashrrev_i32_e32 v52, 10, v48
	v_rcp_f32_e32 v54, v54
	v_rcp_f32_e32 v55, v55
	v_rcp_f32_e32 v65, v65
	v_rcp_f32_e32 v84, v84
	v_and_b32_e32 v85, 0x3f8, v48
	v_cvt_pk_bf16_f32 v48, v49, v50
	v_cvt_pk_bf16_f32 v49, v51, v53
	v_ashrrev_i32_e32 v53, 31, v52
	v_lshlrev_b64 v[52:53], 25, v[52:53]
	v_lshl_add_u64 v[52:53], v[80:81], 0, v[52:53]
	v_lshlrev_b32_e32 v96, 1, v85
	v_cvt_pk_bf16_f32 v50, v54, v55
	v_cvt_pk_bf16_f32 v51, v65, v84
	v_lshl_add_u64 v[52:53], v[52:53], 0, v[96:97]
	s_mov_b64 s[14:15], 0
	global_store_dwordx4 v[52:53], v[48:51], off
	s_mov_b64 s[14:15], 0
	s_branch .LBB0_871
.LBB0_843:
	s_andn2_b64 vcc, exec, s[14:15]
	s_cbranch_vccnz .LBB0_845
	s_mov_b32 s14, 0x3e0293ee
	v_pk_mul_f32 v[48:49], v[56:57], s[14:15] op_sel_hi:[1,0]
	v_pk_mul_f32 v[50:51], v[58:59], s[14:15] op_sel_hi:[1,0]
	v_pk_mul_f32 v[52:53], v[76:77], s[14:15] op_sel_hi:[1,0]
	s_lshl_b32 s48, s95, 8
	v_cvt_pk_bf16_f32 v48, v48, v49
	v_cvt_pk_bf16_f32 v49, v50, v51
	v_cvt_pk_bf16_f32 v50, v52, v53
	v_lshl_add_u64 v[52:53], v[66:67], 0, s[48:49]
	v_lshl_add_u64 v[52:53], v[146:147], 1, v[52:53]
	v_pk_mul_f32 v[54:55], v[78:79], s[14:15] op_sel_hi:[1,0]
	v_add_co_u32_e32 v52, vcc, 0xe11e000, v52
	v_cvt_pk_bf16_f32 v51, v54, v55
	s_nop 0
	v_addc_co_u32_e32 v53, vcc, 0, v53, vcc
	global_store_dwordx4 v[52:53], v[48:51], off offset:2560
	s_mov_b64 s[14:15], 0
	s_branch .LBB0_871

.LBB0_846:
	s_andn2_b64 vcc, exec, s[14:15]
	s_cbranch_vccnz .LBB0_848
	v_mul_f32_e32 v48, 0xbfb8aa3b, v56
	v_mul_f32_e32 v49, 0xbfb8aa3b, v57
	v_mul_f32_e32 v50, 0xbfb8aa3b, v58
	v_mul_f32_e32 v51, 0xbfb8aa3b, v59
	v_mul_f32_e32 v52, 0xbfb8aa3b, v76
	v_mul_f32_e32 v53, 0xbfb8aa3b, v77
	v_exp_f32_e32 v48, v48
	v_exp_f32_e32 v49, v49
	v_exp_f32_e32 v50, v50
	v_exp_f32_e32 v51, v51
	v_exp_f32_e32 v52, v52
	v_exp_f32_e32 v53, v53
	v_mul_f32_e32 v54, 0xbfb8aa3b, v78
	v_mul_f32_e32 v55, 0xbfb8aa3b, v79
	v_exp_f32_e32 v54, v54
	v_exp_f32_e32 v55, v55
	v_add_f32_e32 v48, 1.0, v48
	v_add_f32_e32 v49, 1.0, v49
	v_add_f32_e32 v50, 1.0, v50
	v_add_f32_e32 v51, 1.0, v51
	v_add_f32_e32 v52, 1.0, v52
	v_add_f32_e32 v53, 1.0, v53
	v_rcp_f32_e32 v48, v48
	v_rcp_f32_e32 v49, v49
	v_rcp_f32_e32 v50, v50
	v_rcp_f32_e32 v51, v51
	v_rcp_f32_e32 v52, v52
	v_rcp_f32_e32 v53, v53
	v_add_f32_e32 v54, 1.0, v54
	v_add_f32_e32 v55, 1.0, v55
	v_rcp_f32_e32 v54, v54
	v_rcp_f32_e32 v55, v55
	v_pk_mul_f32 v[48:49], v[56:57], v[48:49]
	v_pk_mul_f32 v[50:51], v[58:59], v[50:51]
	v_pk_mul_f32 v[52:53], v[76:77], v[52:53]
	s_lshl_b32 s48, s95, 8
	v_cvt_pk_bf16_f32 v48, v48, v49
	v_cvt_pk_bf16_f32 v49, v50, v51
	v_cvt_pk_bf16_f32 v50, v52, v53
	v_lshl_add_u64 v[52:53], v[66:67], 0, s[48:49]
	v_lshl_add_u64 v[52:53], v[146:147], 1, v[52:53]
	v_pk_mul_f32 v[54:55], v[78:79], v[54:55]
	v_add_co_u32_e32 v52, vcc, 0xd11e000, v52
	v_cvt_pk_bf16_f32 v51, v54, v55
	s_nop 0
	v_addc_co_u32_e32 v53, vcc, 0, v53, vcc
	global_store_dwordx4 v[52:53], v[48:51], off offset:3584
	s_mov_b64 s[14:15], 0
	s_branch .LBB0_871

.LBB0_849:
	s_andn2_b64 vcc, exec, s[14:15]
	s_cbranch_vccnz .LBB0_851
	s_lshl_b32 s48, s95, 8
	v_lshl_add_u64 v[52:53], v[66:67], 0, s[48:49]
	v_lshl_add_u64 v[52:53], v[146:147], 1, v[52:53]
	v_add_co_u32_e32 v52, vcc, 0xc11f000, v52
	v_cvt_pk_bf16_f32 v48, v56, v57
	v_cvt_pk_bf16_f32 v49, v58, v59
	v_cvt_pk_bf16_f32 v50, v76, v77
	v_cvt_pk_bf16_f32 v51, v78, v79
	v_addc_co_u32_e32 v53, vcc, 0, v53, vcc
	global_store_dwordx4 v[52:53], v[48:51], off offset:512
	s_mov_b64 s[14:15], 0
	s_branch .LBB0_871

.LBB0_852:
	s_andn2_b64 vcc, exec, s[14:15]
	s_cbranch_vccnz .LBB0_854
	v_lshl_add_u32 v80, s95, 7, v194
	v_ashrrev_i32_e32 v81, 31, v80
	v_lshlrev_b64 v[84:85], 2, v[80:81]
	v_lshl_add_u64 v[52:53], s[80:81], 0, v[84:85]
	global_load_dwordx4 v[48:51], v[52:53], off offset:16
	s_nop 0
	global_load_dwordx4 v[52:55], v[52:53], off
	v_max_f32_e32 v65, v56, v56
	s_mov_b32 s17, 0xc2700000
	v_med3_f32 v65, v65, s17, v231
	v_mul_f32_e32 v65, 0xbfb8aa3b, v65
	v_exp_f32_e32 v86, v65
	s_mov_b32 s1, 0x3f317217
	v_lshl_add_u64 v[70:71], v[70:71], 0, v[84:85]
	v_add_f32_e32 v65, 1.0, v86
	v_rcp_f32_e32 v88, v65
	v_max_f32_e32 v65, v57, v57
	v_med3_f32 v65, v65, s17, v231
	v_mul_f32_e32 v65, 0xbfb8aa3b, v65
	v_exp_f32_e32 v87, v65
	s_waitcnt vmcnt(0)
	v_pk_add_f32 v[94:95], v[48:49], 1.0 op_sel_hi:[1,0] neg_lo:[1,0] neg_hi:[1,0]
	v_pk_add_f32 v[90:91], v[52:53], 1.0 op_sel_hi:[1,0] neg_lo:[1,0] neg_hi:[1,0]
	v_add_f32_e32 v65, 1.0, v87
	v_fma_f32 v52, v88, v90, v52
	v_cmp_gt_f32_e32 vcc, s16, v52
	v_rcp_f32_e32 v89, v65
	v_pk_add_f32 v[92:93], v[54:55], 1.0 op_sel_hi:[1,0] neg_lo:[1,0] neg_hi:[1,0]
	v_cndmask_b32_e64 v65, 0, 32, vcc
	v_ldexp_f32 v52, v52, v65
	v_log_f32_e32 v52, v52
	v_fma_f32 v53, v89, v91, v53
	v_pk_mul_f32 v[86:87], v[86:87], v[88:89]
	v_pk_add_f32 v[98:99], v[50:51], 1.0 op_sel_hi:[1,0] neg_lo:[1,0] neg_hi:[1,0]
	v_mul_f32_e32 v65, 0x3f317217, v52
	v_fma_f32 v65, v52, s1, -v65
	v_fmac_f32_e32 v65, 0x3377d1cf, v52
	v_fmac_f32_e32 v65, 0x3f317217, v52
	v_cmp_lt_f32_e64 s[14:15], |v52|, s4
	v_pk_mul_f32 v[86:87], v[86:87], v[90:91]
	s_nop 0
	v_cndmask_b32_e64 v52, v52, v65, s[14:15]
	v_cndmask_b32_e32 v65, 0, v232, vcc
	v_cmp_gt_f32_e32 vcc, s16, v53
	v_sub_f32_e32 v52, v52, v65
	s_nop 0
	v_cndmask_b32_e64 v65, 0, 32, vcc
	v_ldexp_f32 v53, v53, v65
	v_log_f32_e32 v53, v53
	s_nop 0
	v_mul_f32_e32 v65, 0x3f317217, v53
	v_fma_f32 v65, v53, s1, -v65
	v_fmac_f32_e32 v65, 0x3377d1cf, v53
	v_fmac_f32_e32 v65, 0x3f317217, v53
	v_cmp_lt_f32_e64 s[14:15], |v53|, s4
	s_nop 1
	v_cndmask_b32_e64 v53, v53, v65, s[14:15]
	v_cndmask_b32_e32 v65, 0, v232, vcc
	v_sub_f32_e32 v53, v53, v65
	v_max_f32_e32 v65, v58, v58
	v_med3_f32 v65, v65, s17, v231
	v_mul_f32_e32 v65, 0xbfb8aa3b, v65
	v_exp_f32_e32 v88, v65
	s_nop 0
	v_add_f32_e32 v65, 1.0, v88
	v_rcp_f32_e32 v90, v65
	v_max_f32_e32 v65, v59, v59
	v_med3_f32 v65, v65, s17, v231
	v_mul_f32_e32 v65, 0xbfb8aa3b, v65
	v_exp_f32_e32 v89, v65
	v_fma_f32 v54, v90, v92, v54
	v_cmp_gt_f32_e32 vcc, s16, v54
	v_add_f32_e32 v65, 1.0, v89
	v_rcp_f32_e32 v91, v65
	v_cndmask_b32_e64 v65, 0, 32, vcc
	v_ldexp_f32 v54, v54, v65
	v_log_f32_e32 v54, v54
	v_fmac_f32_e32 v55, v91, v93
	v_pk_mul_f32 v[88:89], v[88:89], v[90:91]
	v_mul_f32_e32 v65, 0x3f317217, v54
	v_fma_f32 v65, v54, s1, -v65
	v_fmac_f32_e32 v65, 0x3377d1cf, v54
	v_fmac_f32_e32 v65, 0x3f317217, v54
	v_cmp_lt_f32_e64 s[14:15], |v54|, s4
	v_pk_mul_f32 v[88:89], v[88:89], v[92:93]
	s_nop 0
	v_cndmask_b32_e64 v54, v54, v65, s[14:15]
	v_cndmask_b32_e32 v65, 0, v232, vcc
	v_cmp_gt_f32_e32 vcc, s16, v55
	v_sub_f32_e32 v54, v54, v65
	s_nop 0
	v_cndmask_b32_e64 v65, 0, 32, vcc
	v_ldexp_f32 v55, v55, v65
	v_log_f32_e32 v55, v55
	s_nop 0
	v_mul_f32_e32 v65, 0x3f317217, v55
	v_fma_f32 v65, v55, s1, -v65
	v_fmac_f32_e32 v65, 0x3377d1cf, v55
	v_fmac_f32_e32 v65, 0x3f317217, v55
	v_cmp_lt_f32_e64 s[14:15], |v55|, s4
	s_nop 1
	v_cndmask_b32_e64 v55, v55, v65, s[14:15]
	v_cndmask_b32_e32 v65, 0, v232, vcc
	v_sub_f32_e32 v55, v55, v65
	v_max_f32_e32 v65, v76, v76
	v_med3_f32 v65, v65, s17, v231
	v_mul_f32_e32 v65, 0xbfb8aa3b, v65
	v_exp_f32_e32 v92, v65
	s_nop 0
	v_add_f32_e32 v65, 1.0, v92
	v_rcp_f32_e32 v90, v65
	v_max_f32_e32 v65, v77, v77
	v_med3_f32 v65, v65, s17, v231
	v_mul_f32_e32 v65, 0xbfb8aa3b, v65
	v_exp_f32_e32 v93, v65
	v_fma_f32 v48, v90, v94, v48
	v_cmp_gt_f32_e32 vcc, s16, v48
	v_add_f32_e32 v65, 1.0, v93
	v_rcp_f32_e32 v91, v65
	v_cndmask_b32_e64 v65, 0, 32, vcc
	v_ldexp_f32 v48, v48, v65
	v_log_f32_e32 v48, v48
	v_fma_f32 v49, v91, v95, v49
	v_pk_mul_f32 v[92:93], v[92:93], v[90:91]
	v_mul_f32_e32 v65, 0x3f317217, v48
	v_fma_f32 v65, v48, s1, -v65
	v_fmac_f32_e32 v65, 0x3377d1cf, v48
	v_fmac_f32_e32 v65, 0x3f317217, v48
	v_cmp_lt_f32_e64 s[14:15], |v48|, s4
	v_pk_mul_f32 v[92:93], v[92:93], v[94:95]
	s_nop 0
	v_cndmask_b32_e64 v48, v48, v65, s[14:15]
	v_cndmask_b32_e32 v65, 0, v232, vcc
	v_cmp_gt_f32_e32 vcc, s16, v49
	v_sub_f32_e32 v48, v48, v65
	s_nop 0
	v_cndmask_b32_e64 v65, 0, 32, vcc
	v_ldexp_f32 v49, v49, v65
	v_log_f32_e32 v49, v49
	s_nop 0
	v_mul_f32_e32 v65, 0x3f317217, v49
	v_fma_f32 v65, v49, s1, -v65
	v_fmac_f32_e32 v65, 0x3377d1cf, v49
	v_fmac_f32_e32 v65, 0x3f317217, v49
	v_cmp_lt_f32_e64 s[14:15], |v49|, s4
	s_nop 1
	v_cndmask_b32_e64 v49, v49, v65, s[14:15]
	v_cndmask_b32_e32 v65, 0, v232, vcc
	v_sub_f32_e32 v49, v49, v65
	v_max_f32_e32 v65, v78, v78
	v_med3_f32 v65, v65, s17, v231
	v_mul_f32_e32 v65, 0xbfb8aa3b, v65
	v_exp_f32_e32 v90, v65
	s_nop 0
	v_add_f32_e32 v65, 1.0, v90
	v_rcp_f32_e32 v94, v65
	v_max_f32_e32 v65, v79, v79
	v_med3_f32 v65, v65, s17, v231
	v_mul_f32_e32 v65, 0xbfb8aa3b, v65
	v_exp_f32_e32 v91, v65
	v_fma_f32 v50, v94, v98, v50
	v_cmp_gt_f32_e32 vcc, s16, v50
	v_add_f32_e32 v65, 1.0, v91
	v_rcp_f32_e32 v95, v65
	v_cndmask_b32_e64 v65, 0, 32, vcc
	v_ldexp_f32 v50, v50, v65
	v_log_f32_e32 v50, v50
	v_fmac_f32_e32 v51, v95, v99
	v_pk_mul_f32 v[90:91], v[90:91], v[94:95]
	v_mul_f32_e32 v65, 0x3f317217, v50
	v_fma_f32 v65, v50, s1, -v65
	v_fmac_f32_e32 v65, 0x3377d1cf, v50
	v_fmac_f32_e32 v65, 0x3f317217, v50
	v_cmp_lt_f32_e64 s[14:15], |v50|, s4
	v_pk_mul_f32 v[90:91], v[90:91], v[98:99]
	s_nop 0
	v_cndmask_b32_e64 v50, v50, v65, s[14:15]
	v_cndmask_b32_e32 v65, 0, v232, vcc
	v_cmp_gt_f32_e32 vcc, s16, v51
	v_sub_f32_e32 v50, v50, v65
	s_nop 0
	v_cndmask_b32_e64 v65, 0, 32, vcc
	v_ldexp_f32 v51, v51, v65
	v_log_f32_e32 v51, v51
	s_nop 0
	v_mul_f32_e32 v65, 0x3f317217, v51
	v_fma_f32 v65, v51, s1, -v65
	v_fmac_f32_e32 v65, 0x3377d1cf, v51
	v_fmac_f32_e32 v65, 0x3f317217, v51
	v_cmp_lt_f32_e64 s[14:15], |v51|, s4
	s_nop 1
	v_cndmask_b32_e64 v51, v51, v65, s[14:15]
	v_cndmask_b32_e32 v65, 0, v232, vcc
	v_sub_f32_e32 v51, v51, v65
	global_store_dwordx4 v[70:71], v[52:55], off
	global_store_dwordx4 v[70:71], v[48:51], off offset:16
	s_nop 0
	v_lshl_add_u64 v[52:53], v[80:81], 1, v[68:69]
	v_cvt_pk_bf16_f32 v48, v86, v87
	v_cvt_pk_bf16_f32 v49, v88, v89
	v_cvt_pk_bf16_f32 v50, v92, v93
	v_cvt_pk_bf16_f32 v51, v90, v91
	global_store_dwordx4 v[52:53], v[48:51], off
	s_mov_b64 s[14:15], 0
	s_branch .LBB0_871

.LBB0_855:
	s_andn2_b64 vcc, exec, s[14:15]
	s_cbranch_vccnz .LBB0_857
	v_mul_f32_e32 v48, 0xbfb8aa3b, v56
	v_mul_f32_e32 v49, 0xbfb8aa3b, v57
	v_mul_f32_e32 v50, 0xbfb8aa3b, v58
	v_mul_f32_e32 v51, 0xbfb8aa3b, v59
	v_mul_f32_e32 v52, 0xbfb8aa3b, v76
	v_mul_f32_e32 v53, 0xbfb8aa3b, v77
	v_exp_f32_e32 v48, v48
	v_exp_f32_e32 v49, v49
	v_exp_f32_e32 v50, v50
	v_exp_f32_e32 v51, v51
	v_exp_f32_e32 v52, v52
	v_exp_f32_e32 v53, v53
	v_mul_f32_e32 v54, 0xbfb8aa3b, v78
	v_mul_f32_e32 v55, 0xbfb8aa3b, v79
	v_exp_f32_e32 v54, v54
	v_exp_f32_e32 v55, v55
	v_add_f32_e32 v48, 1.0, v48
	v_add_f32_e32 v49, 1.0, v49
	v_add_f32_e32 v50, 1.0, v50
	v_add_f32_e32 v51, 1.0, v51
	v_add_f32_e32 v52, 1.0, v52
	v_add_f32_e32 v53, 1.0, v53
	v_rcp_f32_e32 v48, v48
	v_rcp_f32_e32 v49, v49
	v_rcp_f32_e32 v50, v50
	v_rcp_f32_e32 v51, v51
	v_rcp_f32_e32 v52, v52
	v_rcp_f32_e32 v53, v53
	v_add_f32_e32 v54, 1.0, v54
	v_add_f32_e32 v55, 1.0, v55
	v_rcp_f32_e32 v54, v54
	v_rcp_f32_e32 v55, v55
	v_pk_mul_f32 v[48:49], v[56:57], v[48:49]
	v_pk_mul_f32 v[50:51], v[58:59], v[50:51]
	v_pk_mul_f32 v[52:53], v[76:77], v[52:53]
	s_lshl_b32 s48, s95, 8
	v_cvt_pk_bf16_f32 v48, v48, v49
	v_cvt_pk_bf16_f32 v49, v50, v51
	v_cvt_pk_bf16_f32 v50, v52, v53
	v_lshl_add_u64 v[52:53], v[66:67], 0, s[48:49]
	v_lshl_add_u64 v[52:53], v[146:147], 1, v[52:53]
	v_pk_mul_f32 v[54:55], v[78:79], v[54:55]
	v_add_co_u32_e32 v52, vcc, 0x811f000, v52
	v_cvt_pk_bf16_f32 v51, v54, v55
	s_nop 0
	v_addc_co_u32_e32 v53, vcc, 0, v53, vcc
	global_store_dwordx4 v[52:53], v[48:51], off offset:2560
	s_mov_b64 s[14:15], 0
	s_branch .LBB0_871

.LBB0_871:
	v_add_f32_e32 v48, v200, v201
	v_fmamk_f32 v48, v48, 0x3a800000, v226
	v_rsq_f32_e32 v62, v48
	v_add_u32_e32 v48, 0x90, v148
	v_ashrrev_i32_e32 v49, 31, v48
	v_lshlrev_b64 v[52:53], 11, v[48:49]
	v_lshlrev_b64 v[56:57], 10, v[48:49]
	v_lshl_add_u64 v[64:65], s[50:51], 0, v[52:53]
	v_lshl_add_u64 v[50:51], s[72:73], 0, v[56:57]
	v_lshl_add_u64 v[54:55], s[52:53], 0, v[52:53]
	v_lshl_add_u64 v[52:53], s[96:97], 0, v[56:57]
	v_pk_mul_f32 v[60:61], v[44:45], v[62:63] op_sel_hi:[1,0]
	v_pk_mul_f32 v[68:69], v[46:47], v[62:63] op_sel_hi:[1,0]
	v_pk_mul_f32 v[70:71], v[40:41], v[62:63] op_sel_hi:[1,0]
	v_pk_mul_f32 v[72:73], v[42:43], v[62:63] op_sel_hi:[1,0]
	s_and_b64 vcc, exec, s[10:11]
	s_mov_b64 s[14:15], -1
	s_cbranch_vccnz .LBB0_893
	s_cmp_lt_u32 s94, 10
	s_cbranch_scc1 .LBB0_890
	s_cmp_lt_u32 s94, 14
	s_cbranch_scc1 .LBB0_887
	s_cmp_lt_u32 s94, 18
	s_cbranch_scc1 .LBB0_884
	s_cmp_lt_u32 s94, 22
	s_cbranch_scc1 .LBB0_881
	s_cmp_lt_u32 s94, 26
	s_cbranch_scc1 .LBB0_878
	v_mul_f32_e32 v41, 0xbfb8aa3b, v60
	v_mul_f32_e32 v42, 0xbfb8aa3b, v61
	v_mul_f32_e32 v43, 0xbfb8aa3b, v68
	v_mul_f32_e32 v45, 0xbfb8aa3b, v69
	v_exp_f32_e32 v41, v41
	v_exp_f32_e32 v42, v42
	v_exp_f32_e32 v43, v43
	v_exp_f32_e32 v45, v45
	v_mul_f32_e32 v46, 0xbfb8aa3b, v70
	v_mul_f32_e32 v47, 0xbfb8aa3b, v71
	v_mul_f32_e32 v56, 0xbfb8aa3b, v72
	v_mul_f32_e32 v57, 0xbfb8aa3b, v73
	v_exp_f32_e32 v46, v46
	v_exp_f32_e32 v47, v47
	v_exp_f32_e32 v56, v56
	v_exp_f32_e32 v57, v57
	v_add_f32_e32 v41, 1.0, v41
	v_add_f32_e32 v42, 1.0, v42
	v_add_f32_e32 v43, 1.0, v43
	v_add_f32_e32 v45, 1.0, v45
	v_rcp_f32_e32 v41, v41
	v_rcp_f32_e32 v42, v42
	v_rcp_f32_e32 v43, v43
	v_rcp_f32_e32 v45, v45
	v_lshl_add_u32 v40, s93, 8, v195
	v_add_f32_e32 v46, 1.0, v46
	v_add_f32_e32 v47, 1.0, v47
	v_add_f32_e32 v56, 1.0, v56
	v_add_f32_e32 v57, 1.0, v57
	v_ashrrev_i32_e32 v44, 10, v40
	v_rcp_f32_e32 v46, v46
	v_rcp_f32_e32 v47, v47
	v_rcp_f32_e32 v56, v56
	v_rcp_f32_e32 v57, v57
	v_and_b32_e32 v58, 0x3f8, v40
	v_cvt_pk_bf16_f32 v40, v41, v42
	v_cvt_pk_bf16_f32 v41, v43, v45
	v_ashrrev_i32_e32 v45, 31, v44
	v_lshlrev_b64 v[44:45], 25, v[44:45]
	v_lshl_add_u64 v[44:45], v[64:65], 0, v[44:45]
	v_lshlrev_b32_e32 v96, 1, v58
	v_cvt_pk_bf16_f32 v42, v46, v47
	v_cvt_pk_bf16_f32 v43, v56, v57
	v_lshl_add_u64 v[44:45], v[44:45], 0, v[96:97]
	s_mov_b64 s[14:15], 0
	global_store_dwordx4 v[44:45], v[40:43], off
	s_mov_b64 s[14:15], 0
	s_branch .LBB0_893
.LBB0_878:
	s_andn2_b64 vcc, exec, s[14:15]
	s_cbranch_vccnz .LBB0_880
	s_mov_b32 s14, 0x3e0293ee
	v_pk_mul_f32 v[40:41], v[60:61], s[14:15] op_sel_hi:[1,0]
	v_pk_mul_f32 v[42:43], v[68:69], s[14:15] op_sel_hi:[1,0]
	v_pk_mul_f32 v[44:45], v[70:71], s[14:15] op_sel_hi:[1,0]
	s_lshl_b32 s48, s93, 8
	v_cvt_pk_bf16_f32 v40, v40, v41
	v_cvt_pk_bf16_f32 v41, v42, v43
	v_cvt_pk_bf16_f32 v42, v44, v45
	v_lshl_add_u64 v[44:45], s[48:49], 1, v[50:51]
	v_lshl_add_u64 v[44:45], v[146:147], 1, v[44:45]
	v_pk_mul_f32 v[46:47], v[72:73], s[14:15] op_sel_hi:[1,0]
	v_add_co_u32_e32 v44, vcc, 0xe11e000, v44
	v_cvt_pk_bf16_f32 v43, v46, v47
	s_nop 0
	v_addc_co_u32_e32 v45, vcc, 0, v45, vcc
	global_store_dwordx4 v[44:45], v[40:43], off offset:2560
	s_mov_b64 s[14:15], 0
	s_branch .LBB0_893

.LBB0_881:
	s_andn2_b64 vcc, exec, s[14:15]
	s_cbranch_vccnz .LBB0_883
	v_mul_f32_e32 v40, 0xbfb8aa3b, v60
	v_mul_f32_e32 v41, 0xbfb8aa3b, v61
	v_mul_f32_e32 v42, 0xbfb8aa3b, v68
	v_mul_f32_e32 v43, 0xbfb8aa3b, v69
	v_mul_f32_e32 v44, 0xbfb8aa3b, v70
	v_mul_f32_e32 v45, 0xbfb8aa3b, v71
	v_exp_f32_e32 v40, v40
	v_exp_f32_e32 v41, v41
	v_exp_f32_e32 v42, v42
	v_exp_f32_e32 v43, v43
	v_exp_f32_e32 v44, v44
	v_exp_f32_e32 v45, v45
	v_mul_f32_e32 v46, 0xbfb8aa3b, v72
	v_mul_f32_e32 v47, 0xbfb8aa3b, v73
	v_exp_f32_e32 v46, v46
	v_exp_f32_e32 v47, v47
	v_add_f32_e32 v40, 1.0, v40
	v_add_f32_e32 v41, 1.0, v41
	v_add_f32_e32 v42, 1.0, v42
	v_add_f32_e32 v43, 1.0, v43
	v_add_f32_e32 v44, 1.0, v44
	v_add_f32_e32 v45, 1.0, v45
	v_rcp_f32_e32 v40, v40
	v_rcp_f32_e32 v41, v41
	v_rcp_f32_e32 v42, v42
	v_rcp_f32_e32 v43, v43
	v_rcp_f32_e32 v44, v44
	v_rcp_f32_e32 v45, v45
	v_add_f32_e32 v46, 1.0, v46
	v_add_f32_e32 v47, 1.0, v47
	v_rcp_f32_e32 v46, v46
	v_rcp_f32_e32 v47, v47
	v_pk_mul_f32 v[40:41], v[60:61], v[40:41]
	v_pk_mul_f32 v[42:43], v[68:69], v[42:43]
	v_pk_mul_f32 v[44:45], v[70:71], v[44:45]
	s_lshl_b32 s48, s93, 8
	v_cvt_pk_bf16_f32 v40, v40, v41
	v_cvt_pk_bf16_f32 v41, v42, v43
	v_cvt_pk_bf16_f32 v42, v44, v45
	v_lshl_add_u64 v[44:45], s[48:49], 1, v[50:51]
	v_lshl_add_u64 v[44:45], v[146:147], 1, v[44:45]
	v_pk_mul_f32 v[46:47], v[72:73], v[46:47]
	v_add_co_u32_e32 v44, vcc, 0xd11e000, v44
	v_cvt_pk_bf16_f32 v43, v46, v47
	s_nop 0
	v_addc_co_u32_e32 v45, vcc, 0, v45, vcc
	global_store_dwordx4 v[44:45], v[40:43], off offset:3584
	s_mov_b64 s[14:15], 0
	s_branch .LBB0_893

.LBB0_884:
	s_andn2_b64 vcc, exec, s[14:15]
	s_cbranch_vccnz .LBB0_886
	s_lshl_b32 s48, s93, 8
	v_lshl_add_u64 v[44:45], s[48:49], 1, v[50:51]
	v_lshl_add_u64 v[44:45], v[146:147], 1, v[44:45]
	v_add_co_u32_e32 v44, vcc, 0xc11f000, v44
	v_cvt_pk_bf16_f32 v40, v60, v61
	v_cvt_pk_bf16_f32 v41, v68, v69
	v_cvt_pk_bf16_f32 v42, v70, v71
	v_cvt_pk_bf16_f32 v43, v72, v73
	v_addc_co_u32_e32 v45, vcc, 0, v45, vcc
	global_store_dwordx4 v[44:45], v[40:43], off offset:512
	s_mov_b64 s[14:15], 0
	s_branch .LBB0_893

.LBB0_902:
	v_mov_b32_e32 v63, v62
	v_pk_mul_f32 v[40:41], v[36:37], v[62:63]
	v_pk_mul_f32 v[42:43], v[38:39], v[62:63]
	v_pk_mul_f32 v[60:61], v[32:33], v[62:63]
	v_pk_mul_f32 v[62:63], v[34:35], v[62:63]
	s_and_b64 vcc, exec, s[12:13]
	s_mov_b64 s[14:15], -1
	s_cbranch_vccnz .LBB0_929
	s_cmp_eq_u32 s93, 2
	s_cbranch_scc1 .LBB0_925
	s_cmp_lt_u32 s94, 10
	s_cbranch_scc1 .LBB0_922
	s_cmp_lt_u32 s94, 14
	s_cbranch_scc1 .LBB0_919
	s_cmp_lt_u32 s94, 18
	s_cbranch_scc1 .LBB0_916
	s_cmp_lt_u32 s94, 22
	s_cbranch_scc1 .LBB0_913
	s_cmp_lt_u32 s94, 26
	s_cbranch_scc1 .LBB0_910
	v_mul_f32_e32 v33, 0xbfb8aa3b, v40
	v_mul_f32_e32 v34, 0xbfb8aa3b, v41
	v_mul_f32_e32 v35, 0xbfb8aa3b, v42
	v_mul_f32_e32 v37, 0xbfb8aa3b, v43
	v_exp_f32_e32 v33, v33
	v_exp_f32_e32 v34, v34
	v_exp_f32_e32 v35, v35
	v_exp_f32_e32 v37, v37
	v_mul_f32_e32 v38, 0xbfb8aa3b, v60
	v_mul_f32_e32 v39, 0xbfb8aa3b, v61
	v_mul_f32_e32 v49, 0xbfb8aa3b, v62
	v_mul_f32_e32 v68, 0xbfb8aa3b, v63
	v_exp_f32_e32 v38, v38
	v_exp_f32_e32 v39, v39
	v_exp_f32_e32 v49, v49
	v_exp_f32_e32 v68, v68
	v_add_f32_e32 v33, 1.0, v33
	v_add_f32_e32 v34, 1.0, v34
	v_add_f32_e32 v35, 1.0, v35
	v_add_f32_e32 v37, 1.0, v37
	v_rcp_f32_e32 v33, v33
	v_rcp_f32_e32 v34, v34
	v_rcp_f32_e32 v35, v35
	v_rcp_f32_e32 v37, v37
	v_lshl_add_u32 v32, s95, 7, v195
	v_add_f32_e32 v38, 1.0, v38
	v_add_f32_e32 v39, 1.0, v39
	v_add_f32_e32 v49, 1.0, v49
	v_add_f32_e32 v68, 1.0, v68
	v_ashrrev_i32_e32 v36, 10, v32
	v_rcp_f32_e32 v38, v38
	v_rcp_f32_e32 v39, v39
	v_rcp_f32_e32 v49, v49
	v_rcp_f32_e32 v68, v68
	v_and_b32_e32 v69, 0x3f8, v32
	v_cvt_pk_bf16_f32 v32, v33, v34
	v_cvt_pk_bf16_f32 v33, v35, v37
	v_ashrrev_i32_e32 v37, 31, v36
	v_lshlrev_b64 v[36:37], 25, v[36:37]
	v_lshl_add_u64 v[36:37], v[64:65], 0, v[36:37]
	v_lshlrev_b32_e32 v96, 1, v69
	v_cvt_pk_bf16_f32 v34, v38, v39
	v_cvt_pk_bf16_f32 v35, v49, v68
	v_lshl_add_u64 v[36:37], v[36:37], 0, v[96:97]
	s_mov_b64 s[14:15], 0
	global_store_dwordx4 v[36:37], v[32:35], off
	s_mov_b64 s[14:15], 0
	s_branch .LBB0_938
.LBB0_910:
	s_andn2_b64 vcc, exec, s[14:15]
	s_cbranch_vccnz .LBB0_912
	s_mov_b32 s14, 0x3e0293ee
	v_pk_mul_f32 v[32:33], v[40:41], s[14:15] op_sel_hi:[1,0]
	v_pk_mul_f32 v[34:35], v[42:43], s[14:15] op_sel_hi:[1,0]
	v_pk_mul_f32 v[36:37], v[60:61], s[14:15] op_sel_hi:[1,0]
	s_lshl_b32 s48, s95, 8
	v_cvt_pk_bf16_f32 v32, v32, v33
	v_cvt_pk_bf16_f32 v33, v34, v35
	v_cvt_pk_bf16_f32 v34, v36, v37
	v_lshl_add_u64 v[36:37], v[50:51], 0, s[48:49]
	v_lshl_add_u64 v[36:37], v[146:147], 1, v[36:37]
	v_pk_mul_f32 v[38:39], v[62:63], s[14:15] op_sel_hi:[1,0]
	v_add_co_u32_e32 v36, vcc, 0xe11e000, v36
	v_cvt_pk_bf16_f32 v35, v38, v39
	s_nop 0
	v_addc_co_u32_e32 v37, vcc, 0, v37, vcc
	global_store_dwordx4 v[36:37], v[32:35], off offset:2560
	s_mov_b64 s[14:15], 0
	s_branch .LBB0_938

.LBB0_913:
	s_andn2_b64 vcc, exec, s[14:15]
	s_cbranch_vccnz .LBB0_915
	v_mul_f32_e32 v32, 0xbfb8aa3b, v40
	v_mul_f32_e32 v33, 0xbfb8aa3b, v41
	v_mul_f32_e32 v34, 0xbfb8aa3b, v42
	v_mul_f32_e32 v35, 0xbfb8aa3b, v43
	v_mul_f32_e32 v36, 0xbfb8aa3b, v60
	v_mul_f32_e32 v37, 0xbfb8aa3b, v61
	v_exp_f32_e32 v32, v32
	v_exp_f32_e32 v33, v33
	v_exp_f32_e32 v34, v34
	v_exp_f32_e32 v35, v35
	v_exp_f32_e32 v36, v36
	v_exp_f32_e32 v37, v37
	v_mul_f32_e32 v38, 0xbfb8aa3b, v62
	v_mul_f32_e32 v39, 0xbfb8aa3b, v63
	v_exp_f32_e32 v38, v38
	v_exp_f32_e32 v39, v39
	v_add_f32_e32 v32, 1.0, v32
	v_add_f32_e32 v33, 1.0, v33
	v_add_f32_e32 v34, 1.0, v34
	v_add_f32_e32 v35, 1.0, v35
	v_add_f32_e32 v36, 1.0, v36
	v_add_f32_e32 v37, 1.0, v37
	v_rcp_f32_e32 v32, v32
	v_rcp_f32_e32 v33, v33
	v_rcp_f32_e32 v34, v34
	v_rcp_f32_e32 v35, v35
	v_rcp_f32_e32 v36, v36
	v_rcp_f32_e32 v37, v37
	v_add_f32_e32 v38, 1.0, v38
	v_add_f32_e32 v39, 1.0, v39
	v_rcp_f32_e32 v38, v38
	v_rcp_f32_e32 v39, v39
	v_pk_mul_f32 v[32:33], v[40:41], v[32:33]
	v_pk_mul_f32 v[34:35], v[42:43], v[34:35]
	v_pk_mul_f32 v[36:37], v[60:61], v[36:37]
	s_lshl_b32 s48, s95, 8
	v_cvt_pk_bf16_f32 v32, v32, v33
	v_cvt_pk_bf16_f32 v33, v34, v35
	v_cvt_pk_bf16_f32 v34, v36, v37
	v_lshl_add_u64 v[36:37], v[50:51], 0, s[48:49]
	v_lshl_add_u64 v[36:37], v[146:147], 1, v[36:37]
	v_pk_mul_f32 v[38:39], v[62:63], v[38:39]
	v_add_co_u32_e32 v36, vcc, 0xd11e000, v36
	v_cvt_pk_bf16_f32 v35, v38, v39
	s_nop 0
	v_addc_co_u32_e32 v37, vcc, 0, v37, vcc
	global_store_dwordx4 v[36:37], v[32:35], off offset:3584
	s_mov_b64 s[14:15], 0
	s_branch .LBB0_938

.LBB0_916:
	s_andn2_b64 vcc, exec, s[14:15]
	s_cbranch_vccnz .LBB0_918
	s_lshl_b32 s48, s95, 8
	v_lshl_add_u64 v[36:37], v[50:51], 0, s[48:49]
	v_lshl_add_u64 v[36:37], v[146:147], 1, v[36:37]
	v_add_co_u32_e32 v36, vcc, 0xc11f000, v36
	v_cvt_pk_bf16_f32 v32, v40, v41
	v_cvt_pk_bf16_f32 v33, v42, v43
	v_cvt_pk_bf16_f32 v34, v60, v61
	v_cvt_pk_bf16_f32 v35, v62, v63
	v_addc_co_u32_e32 v37, vcc, 0, v37, vcc
	global_store_dwordx4 v[36:37], v[32:35], off offset:512
	s_mov_b64 s[14:15], 0
	s_branch .LBB0_938

.LBB0_919:
	s_andn2_b64 vcc, exec, s[14:15]
	s_cbranch_vccnz .LBB0_921
	v_lshl_add_u32 v64, s95, 7, v194
	v_ashrrev_i32_e32 v65, 31, v64
	v_lshlrev_b64 v[68:69], 2, v[64:65]
	v_lshl_add_u64 v[36:37], s[80:81], 0, v[68:69]
	global_load_dwordx4 v[32:35], v[36:37], off offset:16
	s_nop 0
	global_load_dwordx4 v[36:39], v[36:37], off
	v_max_f32_e32 v49, v40, v40
	s_mov_b32 s17, 0xc2700000
	v_med3_f32 v49, v49, s17, v231
	v_mul_f32_e32 v49, 0xbfb8aa3b, v49
	v_exp_f32_e32 v70, v49
	s_mov_b32 s1, 0x3f317217
	v_lshl_add_u64 v[54:55], v[54:55], 0, v[68:69]
	v_add_f32_e32 v49, 1.0, v70
	v_rcp_f32_e32 v72, v49
	v_max_f32_e32 v49, v41, v41
	v_med3_f32 v49, v49, s17, v231
	v_mul_f32_e32 v49, 0xbfb8aa3b, v49
	v_exp_f32_e32 v71, v49
	s_waitcnt vmcnt(0)
	v_pk_add_f32 v[78:79], v[32:33], 1.0 op_sel_hi:[1,0] neg_lo:[1,0] neg_hi:[1,0]
	v_pk_add_f32 v[74:75], v[36:37], 1.0 op_sel_hi:[1,0] neg_lo:[1,0] neg_hi:[1,0]
	v_add_f32_e32 v49, 1.0, v71
	v_fma_f32 v36, v72, v74, v36
	v_cmp_gt_f32_e32 vcc, s16, v36
	v_rcp_f32_e32 v73, v49
	v_pk_add_f32 v[76:77], v[38:39], 1.0 op_sel_hi:[1,0] neg_lo:[1,0] neg_hi:[1,0]
	v_cndmask_b32_e64 v49, 0, 32, vcc
	v_ldexp_f32 v36, v36, v49
	v_log_f32_e32 v36, v36
	v_fma_f32 v37, v73, v75, v37
	v_pk_mul_f32 v[70:71], v[70:71], v[72:73]
	v_pk_add_f32 v[80:81], v[34:35], 1.0 op_sel_hi:[1,0] neg_lo:[1,0] neg_hi:[1,0]
	v_mul_f32_e32 v49, 0x3f317217, v36
	v_fma_f32 v49, v36, s1, -v49
	v_fmac_f32_e32 v49, 0x3377d1cf, v36
	v_fmac_f32_e32 v49, 0x3f317217, v36
	v_cmp_lt_f32_e64 s[14:15], |v36|, s4
	v_pk_mul_f32 v[70:71], v[70:71], v[74:75]
	s_nop 0
	v_cndmask_b32_e64 v36, v36, v49, s[14:15]
	v_cndmask_b32_e32 v49, 0, v232, vcc
	v_cmp_gt_f32_e32 vcc, s16, v37
	v_sub_f32_e32 v36, v36, v49
	s_nop 0
	v_cndmask_b32_e64 v49, 0, 32, vcc
	v_ldexp_f32 v37, v37, v49
	v_log_f32_e32 v37, v37
	s_nop 0
	v_mul_f32_e32 v49, 0x3f317217, v37
	v_fma_f32 v49, v37, s1, -v49
	v_fmac_f32_e32 v49, 0x3377d1cf, v37
	v_fmac_f32_e32 v49, 0x3f317217, v37
	v_cmp_lt_f32_e64 s[14:15], |v37|, s4
	s_nop 1
	v_cndmask_b32_e64 v37, v37, v49, s[14:15]
	v_cndmask_b32_e32 v49, 0, v232, vcc
	v_sub_f32_e32 v37, v37, v49
	v_max_f32_e32 v49, v42, v42
	v_med3_f32 v49, v49, s17, v231
	v_mul_f32_e32 v49, 0xbfb8aa3b, v49
	v_exp_f32_e32 v72, v49
	s_nop 0
	v_add_f32_e32 v49, 1.0, v72
	v_rcp_f32_e32 v74, v49
	v_max_f32_e32 v49, v43, v43
	v_med3_f32 v49, v49, s17, v231
	v_mul_f32_e32 v49, 0xbfb8aa3b, v49
	v_exp_f32_e32 v73, v49
	v_fma_f32 v38, v74, v76, v38
	v_cmp_gt_f32_e32 vcc, s16, v38
	v_add_f32_e32 v49, 1.0, v73
	v_rcp_f32_e32 v75, v49
	v_cndmask_b32_e64 v49, 0, 32, vcc
	v_ldexp_f32 v38, v38, v49
	v_log_f32_e32 v38, v38
	v_fmac_f32_e32 v39, v75, v77
	v_pk_mul_f32 v[72:73], v[72:73], v[74:75]
	v_mul_f32_e32 v49, 0x3f317217, v38
	v_fma_f32 v49, v38, s1, -v49
	v_fmac_f32_e32 v49, 0x3377d1cf, v38
	v_fmac_f32_e32 v49, 0x3f317217, v38
	v_cmp_lt_f32_e64 s[14:15], |v38|, s4
	v_pk_mul_f32 v[72:73], v[72:73], v[76:77]
	s_nop 0
	v_cndmask_b32_e64 v38, v38, v49, s[14:15]
	v_cndmask_b32_e32 v49, 0, v232, vcc
	v_cmp_gt_f32_e32 vcc, s16, v39
	v_sub_f32_e32 v38, v38, v49
	s_nop 0
	v_cndmask_b32_e64 v49, 0, 32, vcc
	v_ldexp_f32 v39, v39, v49
	v_log_f32_e32 v39, v39
	s_nop 0
	v_mul_f32_e32 v49, 0x3f317217, v39
	v_fma_f32 v49, v39, s1, -v49
	v_fmac_f32_e32 v49, 0x3377d1cf, v39
	v_fmac_f32_e32 v49, 0x3f317217, v39
	v_cmp_lt_f32_e64 s[14:15], |v39|, s4
	s_nop 1
	v_cndmask_b32_e64 v39, v39, v49, s[14:15]
	v_cndmask_b32_e32 v49, 0, v232, vcc
	v_sub_f32_e32 v39, v39, v49
	v_max_f32_e32 v49, v60, v60
	v_med3_f32 v49, v49, s17, v231
	v_mul_f32_e32 v49, 0xbfb8aa3b, v49
	v_exp_f32_e32 v76, v49
	s_nop 0
	v_add_f32_e32 v49, 1.0, v76
	v_rcp_f32_e32 v74, v49
	v_max_f32_e32 v49, v61, v61
	v_med3_f32 v49, v49, s17, v231
	v_mul_f32_e32 v49, 0xbfb8aa3b, v49
	v_exp_f32_e32 v77, v49
	v_fma_f32 v32, v74, v78, v32
	v_cmp_gt_f32_e32 vcc, s16, v32
	v_add_f32_e32 v49, 1.0, v77
	v_rcp_f32_e32 v75, v49
	v_cndmask_b32_e64 v49, 0, 32, vcc
	v_ldexp_f32 v32, v32, v49
	v_log_f32_e32 v32, v32
	v_fma_f32 v33, v75, v79, v33
	v_pk_mul_f32 v[76:77], v[76:77], v[74:75]
	v_mul_f32_e32 v49, 0x3f317217, v32
	v_fma_f32 v49, v32, s1, -v49
	v_fmac_f32_e32 v49, 0x3377d1cf, v32
	v_fmac_f32_e32 v49, 0x3f317217, v32
	v_cmp_lt_f32_e64 s[14:15], |v32|, s4
	v_pk_mul_f32 v[76:77], v[76:77], v[78:79]
	s_nop 0
	v_cndmask_b32_e64 v32, v32, v49, s[14:15]
	v_cndmask_b32_e32 v49, 0, v232, vcc
	v_cmp_gt_f32_e32 vcc, s16, v33
	v_sub_f32_e32 v32, v32, v49
	s_nop 0
	v_cndmask_b32_e64 v49, 0, 32, vcc
	v_ldexp_f32 v33, v33, v49
	v_log_f32_e32 v33, v33
	s_nop 0
	v_mul_f32_e32 v49, 0x3f317217, v33
	v_fma_f32 v49, v33, s1, -v49
	v_fmac_f32_e32 v49, 0x3377d1cf, v33
	v_fmac_f32_e32 v49, 0x3f317217, v33
	v_cmp_lt_f32_e64 s[14:15], |v33|, s4
	s_nop 1
	v_cndmask_b32_e64 v33, v33, v49, s[14:15]
	v_cndmask_b32_e32 v49, 0, v232, vcc
	v_sub_f32_e32 v33, v33, v49
	v_max_f32_e32 v49, v62, v62
	v_med3_f32 v49, v49, s17, v231
	v_mul_f32_e32 v49, 0xbfb8aa3b, v49
	v_exp_f32_e32 v74, v49
	s_nop 0
	v_add_f32_e32 v49, 1.0, v74
	v_rcp_f32_e32 v78, v49
	v_max_f32_e32 v49, v63, v63
	v_med3_f32 v49, v49, s17, v231
	v_mul_f32_e32 v49, 0xbfb8aa3b, v49
	v_exp_f32_e32 v75, v49
	v_fma_f32 v34, v78, v80, v34
	v_cmp_gt_f32_e32 vcc, s16, v34
	v_add_f32_e32 v49, 1.0, v75
	v_rcp_f32_e32 v79, v49
	v_cndmask_b32_e64 v49, 0, 32, vcc
	v_ldexp_f32 v34, v34, v49
	v_log_f32_e32 v34, v34
	v_fmac_f32_e32 v35, v79, v81
	v_pk_mul_f32 v[74:75], v[74:75], v[78:79]
	v_mul_f32_e32 v49, 0x3f317217, v34
	v_fma_f32 v49, v34, s1, -v49
	v_fmac_f32_e32 v49, 0x3377d1cf, v34
	v_fmac_f32_e32 v49, 0x3f317217, v34
	v_cmp_lt_f32_e64 s[14:15], |v34|, s4
	v_pk_mul_f32 v[74:75], v[74:75], v[80:81]
	s_nop 0
	v_cndmask_b32_e64 v34, v34, v49, s[14:15]
	v_cndmask_b32_e32 v49, 0, v232, vcc
	v_cmp_gt_f32_e32 vcc, s16, v35
	v_sub_f32_e32 v34, v34, v49
	s_nop 0
	v_cndmask_b32_e64 v49, 0, 32, vcc
	v_ldexp_f32 v35, v35, v49
	v_log_f32_e32 v35, v35
	s_nop 0
	v_mul_f32_e32 v49, 0x3f317217, v35
	v_fma_f32 v49, v35, s1, -v49
	v_fmac_f32_e32 v49, 0x3377d1cf, v35
	v_fmac_f32_e32 v49, 0x3f317217, v35
	v_cmp_lt_f32_e64 s[14:15], |v35|, s4
	s_nop 1
	v_cndmask_b32_e64 v35, v35, v49, s[14:15]
	v_cndmask_b32_e32 v49, 0, v232, vcc
	v_sub_f32_e32 v35, v35, v49
	global_store_dwordx4 v[54:55], v[36:39], off
	global_store_dwordx4 v[54:55], v[32:35], off offset:16
	s_nop 0
	v_lshl_add_u64 v[36:37], v[64:65], 1, v[52:53]
	v_cvt_pk_bf16_f32 v32, v70, v71
	v_cvt_pk_bf16_f32 v33, v72, v73
	v_cvt_pk_bf16_f32 v34, v76, v77
	v_cvt_pk_bf16_f32 v35, v74, v75
	global_store_dwordx4 v[36:37], v[32:35], off
	s_mov_b64 s[14:15], 0
	s_branch .LBB0_938

.LBB0_922:
	s_andn2_b64 vcc, exec, s[14:15]
	s_cbranch_vccnz .LBB0_924
	v_mul_f32_e32 v32, 0xbfb8aa3b, v40
	v_mul_f32_e32 v33, 0xbfb8aa3b, v41
	v_mul_f32_e32 v34, 0xbfb8aa3b, v42
	v_mul_f32_e32 v35, 0xbfb8aa3b, v43
	v_mul_f32_e32 v36, 0xbfb8aa3b, v60
	v_mul_f32_e32 v37, 0xbfb8aa3b, v61
	v_exp_f32_e32 v32, v32
	v_exp_f32_e32 v33, v33
	v_exp_f32_e32 v34, v34
	v_exp_f32_e32 v35, v35
	v_exp_f32_e32 v36, v36
	v_exp_f32_e32 v37, v37
	v_mul_f32_e32 v38, 0xbfb8aa3b, v62
	v_mul_f32_e32 v39, 0xbfb8aa3b, v63
	v_exp_f32_e32 v38, v38
	v_exp_f32_e32 v39, v39
	v_add_f32_e32 v32, 1.0, v32
	v_add_f32_e32 v33, 1.0, v33
	v_add_f32_e32 v34, 1.0, v34
	v_add_f32_e32 v35, 1.0, v35
	v_add_f32_e32 v36, 1.0, v36
	v_add_f32_e32 v37, 1.0, v37
	v_rcp_f32_e32 v32, v32
	v_rcp_f32_e32 v33, v33
	v_rcp_f32_e32 v34, v34
	v_rcp_f32_e32 v35, v35
	v_rcp_f32_e32 v36, v36
	v_rcp_f32_e32 v37, v37
	v_add_f32_e32 v38, 1.0, v38
	v_add_f32_e32 v39, 1.0, v39
	v_rcp_f32_e32 v38, v38
	v_rcp_f32_e32 v39, v39
	v_pk_mul_f32 v[32:33], v[40:41], v[32:33]
	v_pk_mul_f32 v[34:35], v[42:43], v[34:35]
	v_pk_mul_f32 v[36:37], v[60:61], v[36:37]
	s_lshl_b32 s48, s95, 8
	v_cvt_pk_bf16_f32 v32, v32, v33
	v_cvt_pk_bf16_f32 v33, v34, v35
	v_cvt_pk_bf16_f32 v34, v36, v37
	v_lshl_add_u64 v[36:37], v[50:51], 0, s[48:49]
	v_lshl_add_u64 v[36:37], v[146:147], 1, v[36:37]
	v_pk_mul_f32 v[38:39], v[62:63], v[38:39]
	v_add_co_u32_e32 v36, vcc, 0x811f000, v36
	v_cvt_pk_bf16_f32 v35, v38, v39
	s_nop 0
	v_addc_co_u32_e32 v37, vcc, 0, v37, vcc
	global_store_dwordx4 v[36:37], v[32:35], off offset:2560
	s_mov_b64 s[14:15], 0
	s_branch .LBB0_938

.LBB0_938:
	v_add_f32_e32 v32, v198, v199
	v_fmamk_f32 v32, v32, 0x3a800000, v226
	v_rsq_f32_e32 v46, v32
	v_add_u32_e32 v32, 0xa0, v148
	v_ashrrev_i32_e32 v33, 31, v32
	v_lshlrev_b64 v[36:37], 11, v[32:33]
	v_lshlrev_b64 v[40:41], 10, v[32:33]
	v_lshl_add_u64 v[48:49], s[50:51], 0, v[36:37]
	v_lshl_add_u64 v[34:35], s[72:73], 0, v[40:41]
	v_lshl_add_u64 v[38:39], s[52:53], 0, v[36:37]
	v_lshl_add_u64 v[36:37], s[96:97], 0, v[40:41]
	v_pk_mul_f32 v[44:45], v[28:29], v[46:47] op_sel_hi:[1,0]
	v_pk_mul_f32 v[52:53], v[30:31], v[46:47] op_sel_hi:[1,0]
	v_pk_mul_f32 v[54:55], v[24:25], v[46:47] op_sel_hi:[1,0]
	v_pk_mul_f32 v[56:57], v[26:27], v[46:47] op_sel_hi:[1,0]
	s_and_b64 vcc, exec, s[10:11]
	s_mov_b64 s[14:15], -1
	s_cbranch_vccnz .LBB0_960
	s_cmp_lt_u32 s94, 10
	s_cbranch_scc1 .LBB0_957
	s_cmp_lt_u32 s94, 14
	s_cbranch_scc1 .LBB0_954
	s_cmp_lt_u32 s94, 18
	s_cbranch_scc1 .LBB0_951
	s_cmp_lt_u32 s94, 22
	s_cbranch_scc1 .LBB0_948
	s_cmp_lt_u32 s94, 26
	s_cbranch_scc1 .LBB0_945
	v_mul_f32_e32 v25, 0xbfb8aa3b, v44
	v_mul_f32_e32 v26, 0xbfb8aa3b, v45
	v_mul_f32_e32 v27, 0xbfb8aa3b, v52
	v_mul_f32_e32 v29, 0xbfb8aa3b, v53
	v_exp_f32_e32 v25, v25
	v_exp_f32_e32 v26, v26
	v_exp_f32_e32 v27, v27
	v_exp_f32_e32 v29, v29
	v_mul_f32_e32 v30, 0xbfb8aa3b, v54
	v_mul_f32_e32 v31, 0xbfb8aa3b, v55
	v_mul_f32_e32 v40, 0xbfb8aa3b, v56
	v_mul_f32_e32 v41, 0xbfb8aa3b, v57
	v_exp_f32_e32 v30, v30
	v_exp_f32_e32 v31, v31
	v_exp_f32_e32 v40, v40
	v_exp_f32_e32 v41, v41
	v_add_f32_e32 v25, 1.0, v25
	v_add_f32_e32 v26, 1.0, v26
	v_add_f32_e32 v27, 1.0, v27
	v_add_f32_e32 v29, 1.0, v29
	v_rcp_f32_e32 v25, v25
	v_rcp_f32_e32 v26, v26
	v_rcp_f32_e32 v27, v27
	v_rcp_f32_e32 v29, v29
	v_lshl_add_u32 v24, s93, 8, v195
	v_add_f32_e32 v30, 1.0, v30
	v_add_f32_e32 v31, 1.0, v31
	v_add_f32_e32 v40, 1.0, v40
	v_add_f32_e32 v41, 1.0, v41
	v_ashrrev_i32_e32 v28, 10, v24
	v_rcp_f32_e32 v30, v30
	v_rcp_f32_e32 v31, v31
	v_rcp_f32_e32 v40, v40
	v_rcp_f32_e32 v41, v41
	v_and_b32_e32 v42, 0x3f8, v24
	v_cvt_pk_bf16_f32 v24, v25, v26
	v_cvt_pk_bf16_f32 v25, v27, v29
	v_ashrrev_i32_e32 v29, 31, v28
	v_lshlrev_b64 v[28:29], 25, v[28:29]
	v_lshl_add_u64 v[28:29], v[48:49], 0, v[28:29]
	v_lshlrev_b32_e32 v96, 1, v42
	v_cvt_pk_bf16_f32 v26, v30, v31
	v_cvt_pk_bf16_f32 v27, v40, v41
	v_lshl_add_u64 v[28:29], v[28:29], 0, v[96:97]
	s_mov_b64 s[14:15], 0
	global_store_dwordx4 v[28:29], v[24:27], off
	s_mov_b64 s[14:15], 0
	s_branch .LBB0_960
.LBB0_945:
	s_andn2_b64 vcc, exec, s[14:15]
	s_cbranch_vccnz .LBB0_947
	s_mov_b32 s14, 0x3e0293ee
	v_pk_mul_f32 v[24:25], v[44:45], s[14:15] op_sel_hi:[1,0]
	v_pk_mul_f32 v[26:27], v[52:53], s[14:15] op_sel_hi:[1,0]
	v_pk_mul_f32 v[28:29], v[54:55], s[14:15] op_sel_hi:[1,0]
	s_lshl_b32 s48, s93, 8
	v_cvt_pk_bf16_f32 v24, v24, v25
	v_cvt_pk_bf16_f32 v25, v26, v27
	v_cvt_pk_bf16_f32 v26, v28, v29
	v_lshl_add_u64 v[28:29], s[48:49], 1, v[34:35]
	v_lshl_add_u64 v[28:29], v[146:147], 1, v[28:29]
	v_pk_mul_f32 v[30:31], v[56:57], s[14:15] op_sel_hi:[1,0]
	v_add_co_u32_e32 v28, vcc, 0xe11e000, v28
	v_cvt_pk_bf16_f32 v27, v30, v31
	s_nop 0
	v_addc_co_u32_e32 v29, vcc, 0, v29, vcc
	global_store_dwordx4 v[28:29], v[24:27], off offset:2560
	s_mov_b64 s[14:15], 0
	s_branch .LBB0_960

.LBB0_948:
	s_andn2_b64 vcc, exec, s[14:15]
	s_cbranch_vccnz .LBB0_950
	v_mul_f32_e32 v24, 0xbfb8aa3b, v44
	v_mul_f32_e32 v25, 0xbfb8aa3b, v45
	v_mul_f32_e32 v26, 0xbfb8aa3b, v52
	v_mul_f32_e32 v27, 0xbfb8aa3b, v53
	v_mul_f32_e32 v28, 0xbfb8aa3b, v54
	v_mul_f32_e32 v29, 0xbfb8aa3b, v55
	v_exp_f32_e32 v24, v24
	v_exp_f32_e32 v25, v25
	v_exp_f32_e32 v26, v26
	v_exp_f32_e32 v27, v27
	v_exp_f32_e32 v28, v28
	v_exp_f32_e32 v29, v29
	v_mul_f32_e32 v30, 0xbfb8aa3b, v56
	v_mul_f32_e32 v31, 0xbfb8aa3b, v57
	v_exp_f32_e32 v30, v30
	v_exp_f32_e32 v31, v31
	v_add_f32_e32 v24, 1.0, v24
	v_add_f32_e32 v25, 1.0, v25
	v_add_f32_e32 v26, 1.0, v26
	v_add_f32_e32 v27, 1.0, v27
	v_add_f32_e32 v28, 1.0, v28
	v_add_f32_e32 v29, 1.0, v29
	v_rcp_f32_e32 v24, v24
	v_rcp_f32_e32 v25, v25
	v_rcp_f32_e32 v26, v26
	v_rcp_f32_e32 v27, v27
	v_rcp_f32_e32 v28, v28
	v_rcp_f32_e32 v29, v29
	v_add_f32_e32 v30, 1.0, v30
	v_add_f32_e32 v31, 1.0, v31
	v_rcp_f32_e32 v30, v30
	v_rcp_f32_e32 v31, v31
	v_pk_mul_f32 v[24:25], v[44:45], v[24:25]
	v_pk_mul_f32 v[26:27], v[52:53], v[26:27]
	v_pk_mul_f32 v[28:29], v[54:55], v[28:29]
	s_lshl_b32 s48, s93, 8
	v_cvt_pk_bf16_f32 v24, v24, v25
	v_cvt_pk_bf16_f32 v25, v26, v27
	v_cvt_pk_bf16_f32 v26, v28, v29
	v_lshl_add_u64 v[28:29], s[48:49], 1, v[34:35]
	v_lshl_add_u64 v[28:29], v[146:147], 1, v[28:29]
	v_pk_mul_f32 v[30:31], v[56:57], v[30:31]
	v_add_co_u32_e32 v28, vcc, 0xd11e000, v28
	v_cvt_pk_bf16_f32 v27, v30, v31
	s_nop 0
	v_addc_co_u32_e32 v29, vcc, 0, v29, vcc
	global_store_dwordx4 v[28:29], v[24:27], off offset:3584
	s_mov_b64 s[14:15], 0
	s_branch .LBB0_960

.LBB0_951:
	s_andn2_b64 vcc, exec, s[14:15]
	s_cbranch_vccnz .LBB0_953
	s_lshl_b32 s48, s93, 8
	v_lshl_add_u64 v[28:29], s[48:49], 1, v[34:35]
	v_lshl_add_u64 v[28:29], v[146:147], 1, v[28:29]
	v_add_co_u32_e32 v28, vcc, 0xc11f000, v28
	v_cvt_pk_bf16_f32 v24, v44, v45
	v_cvt_pk_bf16_f32 v25, v52, v53
	v_cvt_pk_bf16_f32 v26, v54, v55
	v_cvt_pk_bf16_f32 v27, v56, v57
	v_addc_co_u32_e32 v29, vcc, 0, v29, vcc
	global_store_dwordx4 v[28:29], v[24:27], off offset:512
	s_mov_b64 s[14:15], 0
	s_branch .LBB0_960

.LBB0_969:
	v_mov_b32_e32 v47, v46
	v_pk_mul_f32 v[24:25], v[20:21], v[46:47]
	v_pk_mul_f32 v[26:27], v[22:23], v[46:47]
	v_pk_mul_f32 v[44:45], v[16:17], v[46:47]
	v_pk_mul_f32 v[46:47], v[18:19], v[46:47]
	s_and_b64 vcc, exec, s[12:13]
	s_mov_b64 s[14:15], -1
	s_cbranch_vccnz .LBB0_996
	s_cmp_eq_u32 s93, 2
	s_cbranch_scc1 .LBB0_992
	s_cmp_lt_u32 s94, 10
	s_cbranch_scc1 .LBB0_989
	s_cmp_lt_u32 s94, 14
	s_cbranch_scc1 .LBB0_986
	s_cmp_lt_u32 s94, 18
	s_cbranch_scc1 .LBB0_983
	s_cmp_lt_u32 s94, 22
	s_cbranch_scc1 .LBB0_980
	s_cmp_lt_u32 s94, 26
	s_cbranch_scc1 .LBB0_977
	v_mul_f32_e32 v17, 0xbfb8aa3b, v24
	v_mul_f32_e32 v18, 0xbfb8aa3b, v25
	v_mul_f32_e32 v19, 0xbfb8aa3b, v26
	v_mul_f32_e32 v21, 0xbfb8aa3b, v27
	v_exp_f32_e32 v17, v17
	v_exp_f32_e32 v18, v18
	v_exp_f32_e32 v19, v19
	v_exp_f32_e32 v21, v21
	v_mul_f32_e32 v22, 0xbfb8aa3b, v44
	v_mul_f32_e32 v23, 0xbfb8aa3b, v45
	v_mul_f32_e32 v33, 0xbfb8aa3b, v46
	v_mul_f32_e32 v52, 0xbfb8aa3b, v47
	v_exp_f32_e32 v22, v22
	v_exp_f32_e32 v23, v23
	v_exp_f32_e32 v33, v33
	v_exp_f32_e32 v52, v52
	v_add_f32_e32 v17, 1.0, v17
	v_add_f32_e32 v18, 1.0, v18
	v_add_f32_e32 v19, 1.0, v19
	v_add_f32_e32 v21, 1.0, v21
	v_rcp_f32_e32 v17, v17
	v_rcp_f32_e32 v18, v18
	v_rcp_f32_e32 v19, v19
	v_rcp_f32_e32 v21, v21
	v_lshl_add_u32 v16, s95, 7, v195
	v_add_f32_e32 v22, 1.0, v22
	v_add_f32_e32 v23, 1.0, v23
	v_add_f32_e32 v33, 1.0, v33
	v_add_f32_e32 v52, 1.0, v52
	v_ashrrev_i32_e32 v20, 10, v16
	v_rcp_f32_e32 v22, v22
	v_rcp_f32_e32 v23, v23
	v_rcp_f32_e32 v33, v33
	v_rcp_f32_e32 v52, v52
	v_and_b32_e32 v53, 0x3f8, v16
	v_cvt_pk_bf16_f32 v16, v17, v18
	v_cvt_pk_bf16_f32 v17, v19, v21
	v_ashrrev_i32_e32 v21, 31, v20
	v_lshlrev_b64 v[20:21], 25, v[20:21]
	v_lshl_add_u64 v[20:21], v[48:49], 0, v[20:21]
	v_lshlrev_b32_e32 v96, 1, v53
	v_cvt_pk_bf16_f32 v18, v22, v23
	v_cvt_pk_bf16_f32 v19, v33, v52
	v_lshl_add_u64 v[20:21], v[20:21], 0, v[96:97]
	s_mov_b64 s[14:15], 0
	global_store_dwordx4 v[20:21], v[16:19], off
	s_mov_b64 s[14:15], 0
	s_branch .LBB0_1005
.LBB0_977:
	s_andn2_b64 vcc, exec, s[14:15]
	s_cbranch_vccnz .LBB0_979
	s_mov_b32 s14, 0x3e0293ee
	v_pk_mul_f32 v[16:17], v[24:25], s[14:15] op_sel_hi:[1,0]
	v_pk_mul_f32 v[18:19], v[26:27], s[14:15] op_sel_hi:[1,0]
	v_pk_mul_f32 v[20:21], v[44:45], s[14:15] op_sel_hi:[1,0]
	s_lshl_b32 s48, s95, 8
	v_cvt_pk_bf16_f32 v16, v16, v17
	v_cvt_pk_bf16_f32 v17, v18, v19
	v_cvt_pk_bf16_f32 v18, v20, v21
	v_lshl_add_u64 v[20:21], v[34:35], 0, s[48:49]
	v_lshl_add_u64 v[20:21], v[146:147], 1, v[20:21]
	v_pk_mul_f32 v[22:23], v[46:47], s[14:15] op_sel_hi:[1,0]
	v_add_co_u32_e32 v20, vcc, 0xe11e000, v20
	v_cvt_pk_bf16_f32 v19, v22, v23
	s_nop 0
	v_addc_co_u32_e32 v21, vcc, 0, v21, vcc
	global_store_dwordx4 v[20:21], v[16:19], off offset:2560
	s_mov_b64 s[14:15], 0
	s_branch .LBB0_1005

.LBB0_980:
	s_andn2_b64 vcc, exec, s[14:15]
	s_cbranch_vccnz .LBB0_982
	v_mul_f32_e32 v16, 0xbfb8aa3b, v24
	v_mul_f32_e32 v17, 0xbfb8aa3b, v25
	v_mul_f32_e32 v18, 0xbfb8aa3b, v26
	v_mul_f32_e32 v19, 0xbfb8aa3b, v27
	v_mul_f32_e32 v20, 0xbfb8aa3b, v44
	v_mul_f32_e32 v21, 0xbfb8aa3b, v45
	v_exp_f32_e32 v16, v16
	v_exp_f32_e32 v17, v17
	v_exp_f32_e32 v18, v18
	v_exp_f32_e32 v19, v19
	v_exp_f32_e32 v20, v20
	v_exp_f32_e32 v21, v21
	v_mul_f32_e32 v22, 0xbfb8aa3b, v46
	v_mul_f32_e32 v23, 0xbfb8aa3b, v47
	v_exp_f32_e32 v22, v22
	v_exp_f32_e32 v23, v23
	v_add_f32_e32 v16, 1.0, v16
	v_add_f32_e32 v17, 1.0, v17
	v_add_f32_e32 v18, 1.0, v18
	v_add_f32_e32 v19, 1.0, v19
	v_add_f32_e32 v20, 1.0, v20
	v_add_f32_e32 v21, 1.0, v21
	v_rcp_f32_e32 v16, v16
	v_rcp_f32_e32 v17, v17
	v_rcp_f32_e32 v18, v18
	v_rcp_f32_e32 v19, v19
	v_rcp_f32_e32 v20, v20
	v_rcp_f32_e32 v21, v21
	v_add_f32_e32 v22, 1.0, v22
	v_add_f32_e32 v23, 1.0, v23
	v_rcp_f32_e32 v22, v22
	v_rcp_f32_e32 v23, v23
	v_pk_mul_f32 v[16:17], v[24:25], v[16:17]
	v_pk_mul_f32 v[18:19], v[26:27], v[18:19]
	v_pk_mul_f32 v[20:21], v[44:45], v[20:21]
	s_lshl_b32 s48, s95, 8
	v_cvt_pk_bf16_f32 v16, v16, v17
	v_cvt_pk_bf16_f32 v17, v18, v19
	v_cvt_pk_bf16_f32 v18, v20, v21
	v_lshl_add_u64 v[20:21], v[34:35], 0, s[48:49]
	v_lshl_add_u64 v[20:21], v[146:147], 1, v[20:21]
	v_pk_mul_f32 v[22:23], v[46:47], v[22:23]
	v_add_co_u32_e32 v20, vcc, 0xd11e000, v20
	v_cvt_pk_bf16_f32 v19, v22, v23
	s_nop 0
	v_addc_co_u32_e32 v21, vcc, 0, v21, vcc
	global_store_dwordx4 v[20:21], v[16:19], off offset:3584
	s_mov_b64 s[14:15], 0
	s_branch .LBB0_1005

.LBB0_983:
	s_andn2_b64 vcc, exec, s[14:15]
	s_cbranch_vccnz .LBB0_985
	s_lshl_b32 s48, s95, 8
	v_lshl_add_u64 v[20:21], v[34:35], 0, s[48:49]
	v_lshl_add_u64 v[20:21], v[146:147], 1, v[20:21]
	v_add_co_u32_e32 v20, vcc, 0xc11f000, v20
	v_cvt_pk_bf16_f32 v16, v24, v25
	v_cvt_pk_bf16_f32 v17, v26, v27
	v_cvt_pk_bf16_f32 v18, v44, v45
	v_cvt_pk_bf16_f32 v19, v46, v47
	v_addc_co_u32_e32 v21, vcc, 0, v21, vcc
	global_store_dwordx4 v[20:21], v[16:19], off offset:512
	s_mov_b64 s[14:15], 0
	s_branch .LBB0_1005

.LBB0_986:
	s_andn2_b64 vcc, exec, s[14:15]
	s_cbranch_vccnz .LBB0_988
	v_lshl_add_u32 v48, s95, 7, v194
	v_ashrrev_i32_e32 v49, 31, v48
	v_lshlrev_b64 v[52:53], 2, v[48:49]
	v_lshl_add_u64 v[20:21], s[80:81], 0, v[52:53]
	global_load_dwordx4 v[16:19], v[20:21], off offset:16
	s_nop 0
	global_load_dwordx4 v[20:23], v[20:21], off
	v_max_f32_e32 v33, v24, v24
	s_mov_b32 s17, 0xc2700000
	v_med3_f32 v33, v33, s17, v231
	v_mul_f32_e32 v33, 0xbfb8aa3b, v33
	v_exp_f32_e32 v54, v33
	s_mov_b32 s1, 0x3f317217
	v_lshl_add_u64 v[38:39], v[38:39], 0, v[52:53]
	v_add_f32_e32 v33, 1.0, v54
	v_rcp_f32_e32 v56, v33
	v_max_f32_e32 v33, v25, v25
	v_med3_f32 v33, v33, s17, v231
	v_mul_f32_e32 v33, 0xbfb8aa3b, v33
	v_exp_f32_e32 v55, v33
	s_waitcnt vmcnt(0)
	v_pk_add_f32 v[62:63], v[16:17], 1.0 op_sel_hi:[1,0] neg_lo:[1,0] neg_hi:[1,0]
	v_pk_add_f32 v[58:59], v[20:21], 1.0 op_sel_hi:[1,0] neg_lo:[1,0] neg_hi:[1,0]
	v_add_f32_e32 v33, 1.0, v55
	v_fma_f32 v20, v56, v58, v20
	v_cmp_gt_f32_e32 vcc, s16, v20
	v_rcp_f32_e32 v57, v33
	v_pk_add_f32 v[60:61], v[22:23], 1.0 op_sel_hi:[1,0] neg_lo:[1,0] neg_hi:[1,0]
	v_cndmask_b32_e64 v33, 0, 32, vcc
	v_ldexp_f32 v20, v20, v33
	v_log_f32_e32 v20, v20
	v_fma_f32 v21, v57, v59, v21
	v_pk_mul_f32 v[54:55], v[54:55], v[56:57]
	v_pk_add_f32 v[64:65], v[18:19], 1.0 op_sel_hi:[1,0] neg_lo:[1,0] neg_hi:[1,0]
	v_mul_f32_e32 v33, 0x3f317217, v20
	v_fma_f32 v33, v20, s1, -v33
	v_fmac_f32_e32 v33, 0x3377d1cf, v20
	v_fmac_f32_e32 v33, 0x3f317217, v20
	v_cmp_lt_f32_e64 s[14:15], |v20|, s4
	v_pk_mul_f32 v[54:55], v[54:55], v[58:59]
	s_nop 0
	v_cndmask_b32_e64 v20, v20, v33, s[14:15]
	v_cndmask_b32_e32 v33, 0, v232, vcc
	v_cmp_gt_f32_e32 vcc, s16, v21
	v_sub_f32_e32 v20, v20, v33
	s_nop 0
	v_cndmask_b32_e64 v33, 0, 32, vcc
	v_ldexp_f32 v21, v21, v33
	v_log_f32_e32 v21, v21
	s_nop 0
	v_mul_f32_e32 v33, 0x3f317217, v21
	v_fma_f32 v33, v21, s1, -v33
	v_fmac_f32_e32 v33, 0x3377d1cf, v21
	v_fmac_f32_e32 v33, 0x3f317217, v21
	v_cmp_lt_f32_e64 s[14:15], |v21|, s4
	s_nop 1
	v_cndmask_b32_e64 v21, v21, v33, s[14:15]
	v_cndmask_b32_e32 v33, 0, v232, vcc
	v_sub_f32_e32 v21, v21, v33
	v_max_f32_e32 v33, v26, v26
	v_med3_f32 v33, v33, s17, v231
	v_mul_f32_e32 v33, 0xbfb8aa3b, v33
	v_exp_f32_e32 v56, v33
	s_nop 0
	v_add_f32_e32 v33, 1.0, v56
	v_rcp_f32_e32 v58, v33
	v_max_f32_e32 v33, v27, v27
	v_med3_f32 v33, v33, s17, v231
	v_mul_f32_e32 v33, 0xbfb8aa3b, v33
	v_exp_f32_e32 v57, v33
	v_fma_f32 v22, v58, v60, v22
	v_cmp_gt_f32_e32 vcc, s16, v22
	v_add_f32_e32 v33, 1.0, v57
	v_rcp_f32_e32 v59, v33
	v_cndmask_b32_e64 v33, 0, 32, vcc
	v_ldexp_f32 v22, v22, v33
	v_log_f32_e32 v22, v22
	v_fmac_f32_e32 v23, v59, v61
	v_pk_mul_f32 v[56:57], v[56:57], v[58:59]
	v_mul_f32_e32 v33, 0x3f317217, v22
	v_fma_f32 v33, v22, s1, -v33
	v_fmac_f32_e32 v33, 0x3377d1cf, v22
	v_fmac_f32_e32 v33, 0x3f317217, v22
	v_cmp_lt_f32_e64 s[14:15], |v22|, s4
	v_pk_mul_f32 v[56:57], v[56:57], v[60:61]
	s_nop 0
	v_cndmask_b32_e64 v22, v22, v33, s[14:15]
	v_cndmask_b32_e32 v33, 0, v232, vcc
	v_cmp_gt_f32_e32 vcc, s16, v23
	v_sub_f32_e32 v22, v22, v33
	s_nop 0
	v_cndmask_b32_e64 v33, 0, 32, vcc
	v_ldexp_f32 v23, v23, v33
	v_log_f32_e32 v23, v23
	s_nop 0
	v_mul_f32_e32 v33, 0x3f317217, v23
	v_fma_f32 v33, v23, s1, -v33
	v_fmac_f32_e32 v33, 0x3377d1cf, v23
	v_fmac_f32_e32 v33, 0x3f317217, v23
	v_cmp_lt_f32_e64 s[14:15], |v23|, s4
	s_nop 1
	v_cndmask_b32_e64 v23, v23, v33, s[14:15]
	v_cndmask_b32_e32 v33, 0, v232, vcc
	v_sub_f32_e32 v23, v23, v33
	v_max_f32_e32 v33, v44, v44
	v_med3_f32 v33, v33, s17, v231
	v_mul_f32_e32 v33, 0xbfb8aa3b, v33
	v_exp_f32_e32 v60, v33
	s_nop 0
	v_add_f32_e32 v33, 1.0, v60
	v_rcp_f32_e32 v58, v33
	v_max_f32_e32 v33, v45, v45
	v_med3_f32 v33, v33, s17, v231
	v_mul_f32_e32 v33, 0xbfb8aa3b, v33
	v_exp_f32_e32 v61, v33
	v_fma_f32 v16, v58, v62, v16
	v_cmp_gt_f32_e32 vcc, s16, v16
	v_add_f32_e32 v33, 1.0, v61
	v_rcp_f32_e32 v59, v33
	v_cndmask_b32_e64 v33, 0, 32, vcc
	v_ldexp_f32 v16, v16, v33
	v_log_f32_e32 v16, v16
	v_fma_f32 v17, v59, v63, v17
	v_pk_mul_f32 v[60:61], v[60:61], v[58:59]
	v_mul_f32_e32 v33, 0x3f317217, v16
	v_fma_f32 v33, v16, s1, -v33
	v_fmac_f32_e32 v33, 0x3377d1cf, v16
	v_fmac_f32_e32 v33, 0x3f317217, v16
	v_cmp_lt_f32_e64 s[14:15], |v16|, s4
	v_pk_mul_f32 v[60:61], v[60:61], v[62:63]
	s_nop 0
	v_cndmask_b32_e64 v16, v16, v33, s[14:15]
	v_cndmask_b32_e32 v33, 0, v232, vcc
	v_cmp_gt_f32_e32 vcc, s16, v17
	v_sub_f32_e32 v16, v16, v33
	s_nop 0
	v_cndmask_b32_e64 v33, 0, 32, vcc
	v_ldexp_f32 v17, v17, v33
	v_log_f32_e32 v17, v17
	s_nop 0
	v_mul_f32_e32 v33, 0x3f317217, v17
	v_fma_f32 v33, v17, s1, -v33
	v_fmac_f32_e32 v33, 0x3377d1cf, v17
	v_fmac_f32_e32 v33, 0x3f317217, v17
	v_cmp_lt_f32_e64 s[14:15], |v17|, s4
	s_nop 1
	v_cndmask_b32_e64 v17, v17, v33, s[14:15]
	v_cndmask_b32_e32 v33, 0, v232, vcc
	v_sub_f32_e32 v17, v17, v33
	v_max_f32_e32 v33, v46, v46
	v_med3_f32 v33, v33, s17, v231
	v_mul_f32_e32 v33, 0xbfb8aa3b, v33
	v_exp_f32_e32 v58, v33
	s_nop 0
	v_add_f32_e32 v33, 1.0, v58
	v_rcp_f32_e32 v62, v33
	v_max_f32_e32 v33, v47, v47
	v_med3_f32 v33, v33, s17, v231
	v_mul_f32_e32 v33, 0xbfb8aa3b, v33
	v_exp_f32_e32 v59, v33
	v_fma_f32 v18, v62, v64, v18
	v_cmp_gt_f32_e32 vcc, s16, v18
	v_add_f32_e32 v33, 1.0, v59
	v_rcp_f32_e32 v63, v33
	v_cndmask_b32_e64 v33, 0, 32, vcc
	v_ldexp_f32 v18, v18, v33
	v_log_f32_e32 v18, v18
	v_fmac_f32_e32 v19, v63, v65
	v_pk_mul_f32 v[58:59], v[58:59], v[62:63]
	v_mul_f32_e32 v33, 0x3f317217, v18
	v_fma_f32 v33, v18, s1, -v33
	v_fmac_f32_e32 v33, 0x3377d1cf, v18
	v_fmac_f32_e32 v33, 0x3f317217, v18
	v_cmp_lt_f32_e64 s[14:15], |v18|, s4
	v_pk_mul_f32 v[58:59], v[58:59], v[64:65]
	s_nop 0
	v_cndmask_b32_e64 v18, v18, v33, s[14:15]
	v_cndmask_b32_e32 v33, 0, v232, vcc
	v_cmp_gt_f32_e32 vcc, s16, v19
	v_sub_f32_e32 v18, v18, v33
	s_nop 0
	v_cndmask_b32_e64 v33, 0, 32, vcc
	v_ldexp_f32 v19, v19, v33
	v_log_f32_e32 v19, v19
	s_nop 0
	v_mul_f32_e32 v33, 0x3f317217, v19
	v_fma_f32 v33, v19, s1, -v33
	v_fmac_f32_e32 v33, 0x3377d1cf, v19
	v_fmac_f32_e32 v33, 0x3f317217, v19
	v_cmp_lt_f32_e64 s[14:15], |v19|, s4
	s_nop 1
	v_cndmask_b32_e64 v19, v19, v33, s[14:15]
	v_cndmask_b32_e32 v33, 0, v232, vcc
	v_sub_f32_e32 v19, v19, v33
	global_store_dwordx4 v[38:39], v[20:23], off
	global_store_dwordx4 v[38:39], v[16:19], off offset:16
	s_nop 0
	v_lshl_add_u64 v[20:21], v[48:49], 1, v[36:37]
	v_cvt_pk_bf16_f32 v16, v54, v55
	v_cvt_pk_bf16_f32 v17, v56, v57
	v_cvt_pk_bf16_f32 v18, v60, v61
	v_cvt_pk_bf16_f32 v19, v58, v59
	global_store_dwordx4 v[20:21], v[16:19], off
	s_mov_b64 s[14:15], 0
	s_branch .LBB0_1005

.LBB0_989:
	s_andn2_b64 vcc, exec, s[14:15]
	s_cbranch_vccnz .LBB0_991
	v_mul_f32_e32 v16, 0xbfb8aa3b, v24
	v_mul_f32_e32 v17, 0xbfb8aa3b, v25
	v_mul_f32_e32 v18, 0xbfb8aa3b, v26
	v_mul_f32_e32 v19, 0xbfb8aa3b, v27
	v_mul_f32_e32 v20, 0xbfb8aa3b, v44
	v_mul_f32_e32 v21, 0xbfb8aa3b, v45
	v_exp_f32_e32 v16, v16
	v_exp_f32_e32 v17, v17
	v_exp_f32_e32 v18, v18
	v_exp_f32_e32 v19, v19
	v_exp_f32_e32 v20, v20
	v_exp_f32_e32 v21, v21
	v_mul_f32_e32 v22, 0xbfb8aa3b, v46
	v_mul_f32_e32 v23, 0xbfb8aa3b, v47
	v_exp_f32_e32 v22, v22
	v_exp_f32_e32 v23, v23
	v_add_f32_e32 v16, 1.0, v16
	v_add_f32_e32 v17, 1.0, v17
	v_add_f32_e32 v18, 1.0, v18
	v_add_f32_e32 v19, 1.0, v19
	v_add_f32_e32 v20, 1.0, v20
	v_add_f32_e32 v21, 1.0, v21
	v_rcp_f32_e32 v16, v16
	v_rcp_f32_e32 v17, v17
	v_rcp_f32_e32 v18, v18
	v_rcp_f32_e32 v19, v19
	v_rcp_f32_e32 v20, v20
	v_rcp_f32_e32 v21, v21
	v_add_f32_e32 v22, 1.0, v22
	v_add_f32_e32 v23, 1.0, v23
	v_rcp_f32_e32 v22, v22
	v_rcp_f32_e32 v23, v23
	v_pk_mul_f32 v[16:17], v[24:25], v[16:17]
	v_pk_mul_f32 v[18:19], v[26:27], v[18:19]
	v_pk_mul_f32 v[20:21], v[44:45], v[20:21]
	s_lshl_b32 s48, s95, 8
	v_cvt_pk_bf16_f32 v16, v16, v17
	v_cvt_pk_bf16_f32 v17, v18, v19
	v_cvt_pk_bf16_f32 v18, v20, v21
	v_lshl_add_u64 v[20:21], v[34:35], 0, s[48:49]
	v_lshl_add_u64 v[20:21], v[146:147], 1, v[20:21]
	v_pk_mul_f32 v[22:23], v[46:47], v[22:23]
	v_add_co_u32_e32 v20, vcc, 0x811f000, v20
	v_cvt_pk_bf16_f32 v19, v22, v23
	s_nop 0
	v_addc_co_u32_e32 v21, vcc, 0, v21, vcc
	global_store_dwordx4 v[20:21], v[16:19], off offset:2560
	s_mov_b64 s[14:15], 0
	s_branch .LBB0_1005

.LBB0_1005:
	v_add_f32_e32 v16, v196, v197
	v_fmamk_f32 v16, v16, 0x3a800000, v226
	v_rsq_f32_e32 v30, v16
	v_add_u32_e32 v16, 0xb0, v148
	v_ashrrev_i32_e32 v17, 31, v16
	v_lshlrev_b64 v[20:21], 11, v[16:17]
	v_lshlrev_b64 v[24:25], 10, v[16:17]
	v_lshl_add_u64 v[32:33], s[50:51], 0, v[20:21]
	v_lshl_add_u64 v[18:19], s[72:73], 0, v[24:25]
	v_lshl_add_u64 v[22:23], s[52:53], 0, v[20:21]
	v_lshl_add_u64 v[20:21], s[96:97], 0, v[24:25]
	v_pk_mul_f32 v[28:29], v[12:13], v[30:31] op_sel_hi:[1,0]
	v_pk_mul_f32 v[36:37], v[14:15], v[30:31] op_sel_hi:[1,0]
	v_pk_mul_f32 v[38:39], v[8:9], v[30:31] op_sel_hi:[1,0]
	v_pk_mul_f32 v[40:41], v[10:11], v[30:31] op_sel_hi:[1,0]
	s_and_b64 vcc, exec, s[10:11]
	s_mov_b64 s[10:11], -1
	s_cbranch_vccnz .LBB0_1027
	s_cmp_lt_u32 s94, 10
	s_cbranch_scc1 .LBB0_1024
	s_cmp_lt_u32 s94, 14
	s_cbranch_scc1 .LBB0_1021
	s_cmp_lt_u32 s94, 18
	s_cbranch_scc1 .LBB0_1018
	s_cmp_lt_u32 s94, 22
	s_cbranch_scc1 .LBB0_1015
	s_cmp_lt_u32 s94, 26
	s_cbranch_scc1 .LBB0_1012
	v_mul_f32_e32 v9, 0xbfb8aa3b, v28
	v_mul_f32_e32 v10, 0xbfb8aa3b, v29
	v_mul_f32_e32 v11, 0xbfb8aa3b, v36
	v_mul_f32_e32 v13, 0xbfb8aa3b, v37
	v_exp_f32_e32 v9, v9
	v_exp_f32_e32 v10, v10
	v_exp_f32_e32 v11, v11
	v_exp_f32_e32 v13, v13
	v_mul_f32_e32 v14, 0xbfb8aa3b, v38
	v_mul_f32_e32 v15, 0xbfb8aa3b, v39
	v_mul_f32_e32 v24, 0xbfb8aa3b, v40
	v_mul_f32_e32 v25, 0xbfb8aa3b, v41
	v_exp_f32_e32 v14, v14
	v_exp_f32_e32 v15, v15
	v_exp_f32_e32 v24, v24
	v_exp_f32_e32 v25, v25
	v_add_f32_e32 v9, 1.0, v9
	v_add_f32_e32 v10, 1.0, v10
	v_add_f32_e32 v11, 1.0, v11
	v_add_f32_e32 v13, 1.0, v13
	v_rcp_f32_e32 v9, v9
	v_rcp_f32_e32 v10, v10
	v_rcp_f32_e32 v11, v11
	v_rcp_f32_e32 v13, v13
	v_lshl_add_u32 v8, s93, 8, v195
	v_add_f32_e32 v14, 1.0, v14
	v_add_f32_e32 v15, 1.0, v15
	v_add_f32_e32 v24, 1.0, v24
	v_add_f32_e32 v25, 1.0, v25
	v_ashrrev_i32_e32 v12, 10, v8
	v_rcp_f32_e32 v14, v14
	v_rcp_f32_e32 v15, v15
	v_rcp_f32_e32 v24, v24
	v_rcp_f32_e32 v25, v25
	v_and_b32_e32 v26, 0x3f8, v8
	v_cvt_pk_bf16_f32 v8, v9, v10
	v_cvt_pk_bf16_f32 v9, v11, v13
	v_ashrrev_i32_e32 v13, 31, v12
	v_lshlrev_b64 v[12:13], 25, v[12:13]
	v_lshl_add_u64 v[12:13], v[32:33], 0, v[12:13]
	v_lshlrev_b32_e32 v96, 1, v26
	v_cvt_pk_bf16_f32 v10, v14, v15
	v_cvt_pk_bf16_f32 v11, v24, v25
	v_lshl_add_u64 v[12:13], v[12:13], 0, v[96:97]
	s_mov_b64 s[10:11], 0
	global_store_dwordx4 v[12:13], v[8:11], off
	s_mov_b64 s[10:11], 0
	s_branch .LBB0_1027
.LBB0_1012:
	s_andn2_b64 vcc, exec, s[10:11]
	s_cbranch_vccnz .LBB0_1014
	s_mov_b32 s10, 0x3e0293ee
	v_pk_mul_f32 v[8:9], v[28:29], s[10:11] op_sel_hi:[1,0]
	v_pk_mul_f32 v[10:11], v[36:37], s[10:11] op_sel_hi:[1,0]
	v_pk_mul_f32 v[12:13], v[38:39], s[10:11] op_sel_hi:[1,0]
	s_lshl_b32 s48, s93, 8
	v_cvt_pk_bf16_f32 v8, v8, v9
	v_cvt_pk_bf16_f32 v9, v10, v11
	v_cvt_pk_bf16_f32 v10, v12, v13
	v_lshl_add_u64 v[12:13], s[48:49], 1, v[18:19]
	v_lshl_add_u64 v[12:13], v[146:147], 1, v[12:13]
	v_pk_mul_f32 v[14:15], v[40:41], s[10:11] op_sel_hi:[1,0]
	v_add_co_u32_e32 v12, vcc, 0xe11e000, v12
	v_cvt_pk_bf16_f32 v11, v14, v15
	s_nop 0
	v_addc_co_u32_e32 v13, vcc, 0, v13, vcc
	global_store_dwordx4 v[12:13], v[8:11], off offset:2560
	s_mov_b64 s[10:11], 0
	s_branch .LBB0_1027

.LBB0_1015:
	s_andn2_b64 vcc, exec, s[10:11]
	s_cbranch_vccnz .LBB0_1017
	v_mul_f32_e32 v8, 0xbfb8aa3b, v28
	v_mul_f32_e32 v9, 0xbfb8aa3b, v29
	v_mul_f32_e32 v10, 0xbfb8aa3b, v36
	v_mul_f32_e32 v11, 0xbfb8aa3b, v37
	v_mul_f32_e32 v12, 0xbfb8aa3b, v38
	v_mul_f32_e32 v13, 0xbfb8aa3b, v39
	v_exp_f32_e32 v8, v8
	v_exp_f32_e32 v9, v9
	v_exp_f32_e32 v10, v10
	v_exp_f32_e32 v11, v11
	v_exp_f32_e32 v12, v12
	v_exp_f32_e32 v13, v13
	v_mul_f32_e32 v14, 0xbfb8aa3b, v40
	v_mul_f32_e32 v15, 0xbfb8aa3b, v41
	v_exp_f32_e32 v14, v14
	v_exp_f32_e32 v15, v15
	v_add_f32_e32 v8, 1.0, v8
	v_add_f32_e32 v9, 1.0, v9
	v_add_f32_e32 v10, 1.0, v10
	v_add_f32_e32 v11, 1.0, v11
	v_add_f32_e32 v12, 1.0, v12
	v_add_f32_e32 v13, 1.0, v13
	v_rcp_f32_e32 v8, v8
	v_rcp_f32_e32 v9, v9
	v_rcp_f32_e32 v10, v10
	v_rcp_f32_e32 v11, v11
	v_rcp_f32_e32 v12, v12
	v_rcp_f32_e32 v13, v13
	v_add_f32_e32 v14, 1.0, v14
	v_add_f32_e32 v15, 1.0, v15
	v_rcp_f32_e32 v14, v14
	v_rcp_f32_e32 v15, v15
	v_pk_mul_f32 v[8:9], v[28:29], v[8:9]
	v_pk_mul_f32 v[10:11], v[36:37], v[10:11]
	v_pk_mul_f32 v[12:13], v[38:39], v[12:13]
	s_lshl_b32 s48, s93, 8
	v_cvt_pk_bf16_f32 v8, v8, v9
	v_cvt_pk_bf16_f32 v9, v10, v11
	v_cvt_pk_bf16_f32 v10, v12, v13
	v_lshl_add_u64 v[12:13], s[48:49], 1, v[18:19]
	v_lshl_add_u64 v[12:13], v[146:147], 1, v[12:13]
	v_pk_mul_f32 v[14:15], v[40:41], v[14:15]
	v_add_co_u32_e32 v12, vcc, 0xd11e000, v12
	v_cvt_pk_bf16_f32 v11, v14, v15
	s_nop 0
	v_addc_co_u32_e32 v13, vcc, 0, v13, vcc
	global_store_dwordx4 v[12:13], v[8:11], off offset:3584
	s_mov_b64 s[10:11], 0
	s_branch .LBB0_1027

.LBB0_1018:
	s_andn2_b64 vcc, exec, s[10:11]
	s_cbranch_vccnz .LBB0_1020
	s_lshl_b32 s48, s93, 8
	v_lshl_add_u64 v[12:13], s[48:49], 1, v[18:19]
	v_lshl_add_u64 v[12:13], v[146:147], 1, v[12:13]
	v_add_co_u32_e32 v12, vcc, 0xc11f000, v12
	v_cvt_pk_bf16_f32 v8, v28, v29
	v_cvt_pk_bf16_f32 v9, v36, v37
	v_cvt_pk_bf16_f32 v10, v38, v39
	v_cvt_pk_bf16_f32 v11, v40, v41
	v_addc_co_u32_e32 v13, vcc, 0, v13, vcc
	global_store_dwordx4 v[12:13], v[8:11], off offset:512
	s_mov_b64 s[10:11], 0
	s_branch .LBB0_1027

.LBB0_1036:
	v_mov_b32_e32 v31, v30
	v_pk_mul_f32 v[8:9], v[4:5], v[30:31]
	v_pk_mul_f32 v[10:11], v[6:7], v[30:31]
	v_pk_mul_f32 v[28:29], v[0:1], v[30:31]
	v_pk_mul_f32 v[30:31], v[2:3], v[30:31]
	s_and_b64 vcc, exec, s[12:13]
	s_mov_b64 s[10:11], -1
	s_cbranch_vccnz .LBB0_1063
	s_cmp_eq_u32 s93, 2
	s_cbranch_scc1 .LBB0_1059
	s_cmp_lt_u32 s94, 10
	s_cbranch_scc1 .LBB0_1056
	s_cmp_lt_u32 s94, 14
	s_cbranch_scc1 .LBB0_1053
	s_cmp_lt_u32 s94, 18
	s_cbranch_scc1 .LBB0_1050
	s_cmp_lt_u32 s94, 22
	s_cbranch_scc1 .LBB0_1047
	s_cmp_lt_u32 s94, 26
	s_cbranch_scc1 .LBB0_1044
	v_mul_f32_e32 v1, 0xbfb8aa3b, v8
	v_mul_f32_e32 v2, 0xbfb8aa3b, v9
	v_mul_f32_e32 v3, 0xbfb8aa3b, v10
	v_mul_f32_e32 v5, 0xbfb8aa3b, v11
	v_exp_f32_e32 v1, v1
	v_exp_f32_e32 v2, v2
	v_exp_f32_e32 v3, v3
	v_exp_f32_e32 v5, v5
	v_mul_f32_e32 v6, 0xbfb8aa3b, v28
	v_mul_f32_e32 v7, 0xbfb8aa3b, v29
	v_mul_f32_e32 v17, 0xbfb8aa3b, v30
	v_mul_f32_e32 v36, 0xbfb8aa3b, v31
	v_exp_f32_e32 v6, v6
	v_exp_f32_e32 v7, v7
	v_exp_f32_e32 v17, v17
	v_exp_f32_e32 v36, v36
	v_add_f32_e32 v1, 1.0, v1
	v_add_f32_e32 v2, 1.0, v2
	v_add_f32_e32 v3, 1.0, v3
	v_add_f32_e32 v5, 1.0, v5
	v_rcp_f32_e32 v1, v1
	v_rcp_f32_e32 v2, v2
	v_rcp_f32_e32 v3, v3
	v_rcp_f32_e32 v5, v5
	v_lshl_add_u32 v0, s95, 7, v195
	v_add_f32_e32 v6, 1.0, v6
	v_add_f32_e32 v7, 1.0, v7
	v_add_f32_e32 v17, 1.0, v17
	v_add_f32_e32 v36, 1.0, v36
	v_ashrrev_i32_e32 v4, 10, v0
	v_rcp_f32_e32 v6, v6
	v_rcp_f32_e32 v7, v7
	v_rcp_f32_e32 v17, v17
	v_rcp_f32_e32 v36, v36
	v_and_b32_e32 v37, 0x3f8, v0
	v_cvt_pk_bf16_f32 v0, v1, v2
	v_cvt_pk_bf16_f32 v1, v3, v5
	v_ashrrev_i32_e32 v5, 31, v4
	v_lshlrev_b64 v[4:5], 25, v[4:5]
	v_lshl_add_u64 v[4:5], v[32:33], 0, v[4:5]
	v_lshlrev_b32_e32 v96, 1, v37
	v_cvt_pk_bf16_f32 v2, v6, v7
	v_cvt_pk_bf16_f32 v3, v17, v36
	v_lshl_add_u64 v[4:5], v[4:5], 0, v[96:97]
	s_mov_b64 s[10:11], 0
	global_store_dwordx4 v[4:5], v[0:3], off
	s_mov_b64 s[10:11], 0
	s_branch .LBB0_1072
.LBB0_1044:
	s_andn2_b64 vcc, exec, s[10:11]
	s_cbranch_vccnz .LBB0_1046
	s_mov_b32 s10, 0x3e0293ee
	v_pk_mul_f32 v[0:1], v[8:9], s[10:11] op_sel_hi:[1,0]
	v_pk_mul_f32 v[2:3], v[10:11], s[10:11] op_sel_hi:[1,0]
	v_pk_mul_f32 v[4:5], v[28:29], s[10:11] op_sel_hi:[1,0]
	s_lshl_b32 s48, s95, 8
	v_cvt_pk_bf16_f32 v0, v0, v1
	v_cvt_pk_bf16_f32 v1, v2, v3
	v_cvt_pk_bf16_f32 v2, v4, v5
	v_lshl_add_u64 v[4:5], v[18:19], 0, s[48:49]
	v_lshl_add_u64 v[4:5], v[146:147], 1, v[4:5]
	v_pk_mul_f32 v[6:7], v[30:31], s[10:11] op_sel_hi:[1,0]
	v_add_co_u32_e32 v4, vcc, 0xe11e000, v4
	v_cvt_pk_bf16_f32 v3, v6, v7
	s_nop 0
	v_addc_co_u32_e32 v5, vcc, 0, v5, vcc
	global_store_dwordx4 v[4:5], v[0:3], off offset:2560
	s_mov_b64 s[10:11], 0
	s_branch .LBB0_1072

.LBB0_1047:
	s_andn2_b64 vcc, exec, s[10:11]
	s_cbranch_vccnz .LBB0_1049
	v_mul_f32_e32 v0, 0xbfb8aa3b, v8
	v_mul_f32_e32 v1, 0xbfb8aa3b, v9
	v_mul_f32_e32 v2, 0xbfb8aa3b, v10
	v_mul_f32_e32 v3, 0xbfb8aa3b, v11
	v_mul_f32_e32 v4, 0xbfb8aa3b, v28
	v_mul_f32_e32 v5, 0xbfb8aa3b, v29
	v_exp_f32_e32 v0, v0
	v_exp_f32_e32 v1, v1
	v_exp_f32_e32 v2, v2
	v_exp_f32_e32 v3, v3
	v_exp_f32_e32 v4, v4
	v_exp_f32_e32 v5, v5
	v_mul_f32_e32 v6, 0xbfb8aa3b, v30
	v_mul_f32_e32 v7, 0xbfb8aa3b, v31
	v_exp_f32_e32 v6, v6
	v_exp_f32_e32 v7, v7
	v_add_f32_e32 v0, 1.0, v0
	v_add_f32_e32 v1, 1.0, v1
	v_add_f32_e32 v2, 1.0, v2
	v_add_f32_e32 v3, 1.0, v3
	v_add_f32_e32 v4, 1.0, v4
	v_add_f32_e32 v5, 1.0, v5
	v_rcp_f32_e32 v0, v0
	v_rcp_f32_e32 v1, v1
	v_rcp_f32_e32 v2, v2
	v_rcp_f32_e32 v3, v3
	v_rcp_f32_e32 v4, v4
	v_rcp_f32_e32 v5, v5
	v_add_f32_e32 v6, 1.0, v6
	v_add_f32_e32 v7, 1.0, v7
	v_rcp_f32_e32 v6, v6
	v_rcp_f32_e32 v7, v7
	v_pk_mul_f32 v[0:1], v[8:9], v[0:1]
	v_pk_mul_f32 v[2:3], v[10:11], v[2:3]
	v_pk_mul_f32 v[4:5], v[28:29], v[4:5]
	s_lshl_b32 s48, s95, 8
	v_cvt_pk_bf16_f32 v0, v0, v1
	v_cvt_pk_bf16_f32 v1, v2, v3
	v_cvt_pk_bf16_f32 v2, v4, v5
	v_lshl_add_u64 v[4:5], v[18:19], 0, s[48:49]
	v_lshl_add_u64 v[4:5], v[146:147], 1, v[4:5]
	v_pk_mul_f32 v[6:7], v[30:31], v[6:7]
	v_add_co_u32_e32 v4, vcc, 0xd11e000, v4
	v_cvt_pk_bf16_f32 v3, v6, v7
	s_nop 0
	v_addc_co_u32_e32 v5, vcc, 0, v5, vcc
	global_store_dwordx4 v[4:5], v[0:3], off offset:3584
	s_mov_b64 s[10:11], 0
	s_branch .LBB0_1072

.LBB0_1050:
	s_andn2_b64 vcc, exec, s[10:11]
	s_cbranch_vccnz .LBB0_1052
	s_lshl_b32 s48, s95, 8
	v_lshl_add_u64 v[4:5], v[18:19], 0, s[48:49]
	v_lshl_add_u64 v[4:5], v[146:147], 1, v[4:5]
	v_add_co_u32_e32 v4, vcc, 0xc11f000, v4
	v_cvt_pk_bf16_f32 v0, v8, v9
	v_cvt_pk_bf16_f32 v1, v10, v11
	v_cvt_pk_bf16_f32 v2, v28, v29
	v_cvt_pk_bf16_f32 v3, v30, v31
	v_addc_co_u32_e32 v5, vcc, 0, v5, vcc
	global_store_dwordx4 v[4:5], v[0:3], off offset:512
	s_mov_b64 s[10:11], 0
	s_branch .LBB0_1072

.LBB0_1053:
	s_andn2_b64 vcc, exec, s[10:11]
	s_cbranch_vccnz .LBB0_1055
	v_lshl_add_u32 v32, s95, 7, v194
	v_ashrrev_i32_e32 v33, 31, v32
	v_lshlrev_b64 v[36:37], 2, v[32:33]
	v_lshl_add_u64 v[4:5], s[80:81], 0, v[36:37]
	global_load_dwordx4 v[0:3], v[4:5], off offset:16
	s_nop 0
	global_load_dwordx4 v[4:7], v[4:5], off
	v_max_f32_e32 v17, v8, v8
	s_mov_b32 s12, 0xc2700000
	v_med3_f32 v17, v17, s12, v231
	v_mul_f32_e32 v17, 0xbfb8aa3b, v17
	v_exp_f32_e32 v38, v17
	s_mov_b32 s1, 0x3f317217
	v_lshl_add_u64 v[22:23], v[22:23], 0, v[36:37]
	v_add_f32_e32 v17, 1.0, v38
	v_rcp_f32_e32 v40, v17
	v_max_f32_e32 v17, v9, v9
	v_med3_f32 v17, v17, s12, v231
	v_mul_f32_e32 v17, 0xbfb8aa3b, v17
	v_exp_f32_e32 v39, v17
	s_waitcnt vmcnt(0)
	v_pk_add_f32 v[46:47], v[0:1], 1.0 op_sel_hi:[1,0] neg_lo:[1,0] neg_hi:[1,0]
	v_pk_add_f32 v[42:43], v[4:5], 1.0 op_sel_hi:[1,0] neg_lo:[1,0] neg_hi:[1,0]
	v_add_f32_e32 v17, 1.0, v39
	v_fma_f32 v4, v40, v42, v4
	v_cmp_gt_f32_e32 vcc, s16, v4
	v_rcp_f32_e32 v41, v17
	v_pk_add_f32 v[44:45], v[6:7], 1.0 op_sel_hi:[1,0] neg_lo:[1,0] neg_hi:[1,0]
	v_cndmask_b32_e64 v17, 0, 32, vcc
	v_ldexp_f32 v4, v4, v17
	v_log_f32_e32 v4, v4
	v_fma_f32 v5, v41, v43, v5
	v_pk_mul_f32 v[38:39], v[38:39], v[40:41]
	v_pk_add_f32 v[48:49], v[2:3], 1.0 op_sel_hi:[1,0] neg_lo:[1,0] neg_hi:[1,0]
	v_mul_f32_e32 v17, 0x3f317217, v4
	v_fma_f32 v17, v4, s1, -v17
	v_fmac_f32_e32 v17, 0x3377d1cf, v4
	v_fmac_f32_e32 v17, 0x3f317217, v4
	v_cmp_lt_f32_e64 s[10:11], |v4|, s4
	v_pk_mul_f32 v[38:39], v[38:39], v[42:43]
	s_nop 0
	v_cndmask_b32_e64 v4, v4, v17, s[10:11]
	v_cndmask_b32_e32 v17, 0, v232, vcc
	v_cmp_gt_f32_e32 vcc, s16, v5
	v_sub_f32_e32 v4, v4, v17
	s_nop 0
	v_cndmask_b32_e64 v17, 0, 32, vcc
	v_ldexp_f32 v5, v5, v17
	v_log_f32_e32 v5, v5
	s_nop 0
	v_mul_f32_e32 v17, 0x3f317217, v5
	v_fma_f32 v17, v5, s1, -v17
	v_fmac_f32_e32 v17, 0x3377d1cf, v5
	v_fmac_f32_e32 v17, 0x3f317217, v5
	v_cmp_lt_f32_e64 s[10:11], |v5|, s4
	s_nop 1
	v_cndmask_b32_e64 v5, v5, v17, s[10:11]
	v_cndmask_b32_e32 v17, 0, v232, vcc
	v_sub_f32_e32 v5, v5, v17
	v_max_f32_e32 v17, v10, v10
	v_med3_f32 v17, v17, s12, v231
	v_mul_f32_e32 v17, 0xbfb8aa3b, v17
	v_exp_f32_e32 v40, v17
	s_nop 0
	v_add_f32_e32 v17, 1.0, v40
	v_rcp_f32_e32 v42, v17
	v_max_f32_e32 v17, v11, v11
	v_med3_f32 v17, v17, s12, v231
	v_mul_f32_e32 v17, 0xbfb8aa3b, v17
	v_exp_f32_e32 v41, v17
	v_fma_f32 v6, v42, v44, v6
	v_cmp_gt_f32_e32 vcc, s16, v6
	v_add_f32_e32 v17, 1.0, v41
	v_rcp_f32_e32 v43, v17
	v_cndmask_b32_e64 v17, 0, 32, vcc
	v_ldexp_f32 v6, v6, v17
	v_log_f32_e32 v6, v6
	v_fmac_f32_e32 v7, v43, v45
	v_pk_mul_f32 v[40:41], v[40:41], v[42:43]
	v_mul_f32_e32 v17, 0x3f317217, v6
	v_fma_f32 v17, v6, s1, -v17
	v_fmac_f32_e32 v17, 0x3377d1cf, v6
	v_fmac_f32_e32 v17, 0x3f317217, v6
	v_cmp_lt_f32_e64 s[10:11], |v6|, s4
	v_pk_mul_f32 v[40:41], v[40:41], v[44:45]
	s_nop 0
	v_cndmask_b32_e64 v6, v6, v17, s[10:11]
	v_cndmask_b32_e32 v17, 0, v232, vcc
	v_cmp_gt_f32_e32 vcc, s16, v7
	v_sub_f32_e32 v6, v6, v17
	s_nop 0
	v_cndmask_b32_e64 v17, 0, 32, vcc
	v_ldexp_f32 v7, v7, v17
	v_log_f32_e32 v7, v7
	s_nop 0
	v_mul_f32_e32 v17, 0x3f317217, v7
	v_fma_f32 v17, v7, s1, -v17
	v_fmac_f32_e32 v17, 0x3377d1cf, v7
	v_fmac_f32_e32 v17, 0x3f317217, v7
	v_cmp_lt_f32_e64 s[10:11], |v7|, s4
	s_nop 1
	v_cndmask_b32_e64 v7, v7, v17, s[10:11]
	v_cndmask_b32_e32 v17, 0, v232, vcc
	v_sub_f32_e32 v7, v7, v17
	v_max_f32_e32 v17, v28, v28
	v_med3_f32 v17, v17, s12, v231
	v_mul_f32_e32 v17, 0xbfb8aa3b, v17
	v_exp_f32_e32 v44, v17
	s_nop 0
	v_add_f32_e32 v17, 1.0, v44
	v_rcp_f32_e32 v42, v17
	v_max_f32_e32 v17, v29, v29
	v_med3_f32 v17, v17, s12, v231
	v_mul_f32_e32 v17, 0xbfb8aa3b, v17
	v_exp_f32_e32 v45, v17
	v_fma_f32 v0, v42, v46, v0
	v_cmp_gt_f32_e32 vcc, s16, v0
	v_add_f32_e32 v17, 1.0, v45
	v_rcp_f32_e32 v43, v17
	v_cndmask_b32_e64 v17, 0, 32, vcc
	v_ldexp_f32 v0, v0, v17
	v_log_f32_e32 v0, v0
	v_fma_f32 v1, v43, v47, v1
	v_pk_mul_f32 v[44:45], v[44:45], v[42:43]
	v_mul_f32_e32 v17, 0x3f317217, v0
	v_fma_f32 v17, v0, s1, -v17
	v_fmac_f32_e32 v17, 0x3377d1cf, v0
	v_fmac_f32_e32 v17, 0x3f317217, v0
	v_cmp_lt_f32_e64 s[10:11], |v0|, s4
	v_pk_mul_f32 v[44:45], v[44:45], v[46:47]
	s_nop 0
	v_cndmask_b32_e64 v0, v0, v17, s[10:11]
	v_cndmask_b32_e32 v17, 0, v232, vcc
	v_cmp_gt_f32_e32 vcc, s16, v1
	v_sub_f32_e32 v0, v0, v17
	s_nop 0
	v_cndmask_b32_e64 v17, 0, 32, vcc
	v_ldexp_f32 v1, v1, v17
	v_log_f32_e32 v1, v1
	s_nop 0
	v_mul_f32_e32 v17, 0x3f317217, v1
	v_fma_f32 v17, v1, s1, -v17
	v_fmac_f32_e32 v17, 0x3377d1cf, v1
	v_fmac_f32_e32 v17, 0x3f317217, v1
	v_cmp_lt_f32_e64 s[10:11], |v1|, s4
	s_nop 1
	v_cndmask_b32_e64 v1, v1, v17, s[10:11]
	v_cndmask_b32_e32 v17, 0, v232, vcc
	v_sub_f32_e32 v1, v1, v17
	v_max_f32_e32 v17, v30, v30
	v_med3_f32 v17, v17, s12, v231
	v_mul_f32_e32 v17, 0xbfb8aa3b, v17
	v_exp_f32_e32 v42, v17
	s_nop 0
	v_add_f32_e32 v17, 1.0, v42
	v_rcp_f32_e32 v46, v17
	v_max_f32_e32 v17, v31, v31
	v_med3_f32 v17, v17, s12, v231
	v_mul_f32_e32 v17, 0xbfb8aa3b, v17
	v_exp_f32_e32 v43, v17
	v_fma_f32 v2, v46, v48, v2
	v_cmp_gt_f32_e32 vcc, s16, v2
	v_add_f32_e32 v17, 1.0, v43
	v_rcp_f32_e32 v47, v17
	v_cndmask_b32_e64 v17, 0, 32, vcc
	v_ldexp_f32 v2, v2, v17
	v_log_f32_e32 v2, v2
	v_fmac_f32_e32 v3, v47, v49
	v_pk_mul_f32 v[42:43], v[42:43], v[46:47]
	v_mul_f32_e32 v17, 0x3f317217, v2
	v_fma_f32 v17, v2, s1, -v17
	v_fmac_f32_e32 v17, 0x3377d1cf, v2
	v_fmac_f32_e32 v17, 0x3f317217, v2
	v_cmp_lt_f32_e64 s[10:11], |v2|, s4
	v_pk_mul_f32 v[42:43], v[42:43], v[48:49]
	s_nop 0
	v_cndmask_b32_e64 v2, v2, v17, s[10:11]
	v_cndmask_b32_e32 v17, 0, v232, vcc
	v_cmp_gt_f32_e32 vcc, s16, v3
	v_sub_f32_e32 v2, v2, v17
	s_nop 0
	v_cndmask_b32_e64 v17, 0, 32, vcc
	v_ldexp_f32 v3, v3, v17
	v_log_f32_e32 v3, v3
	s_nop 0
	v_mul_f32_e32 v17, 0x3f317217, v3
	v_fma_f32 v17, v3, s1, -v17
	v_fmac_f32_e32 v17, 0x3377d1cf, v3
	v_fmac_f32_e32 v17, 0x3f317217, v3
	v_cmp_lt_f32_e64 s[10:11], |v3|, s4
	s_nop 1
	v_cndmask_b32_e64 v3, v3, v17, s[10:11]
	v_cndmask_b32_e32 v17, 0, v232, vcc
	v_sub_f32_e32 v3, v3, v17
	global_store_dwordx4 v[22:23], v[4:7], off
	global_store_dwordx4 v[22:23], v[0:3], off offset:16
	s_nop 0
	v_lshl_add_u64 v[4:5], v[32:33], 1, v[20:21]
	v_cvt_pk_bf16_f32 v0, v38, v39
	v_cvt_pk_bf16_f32 v1, v40, v41
	v_cvt_pk_bf16_f32 v2, v44, v45
	v_cvt_pk_bf16_f32 v3, v42, v43
	global_store_dwordx4 v[4:5], v[0:3], off
	s_mov_b64 s[10:11], 0
	s_branch .LBB0_1072

.LBB0_1056:
	s_andn2_b64 vcc, exec, s[10:11]
	s_cbranch_vccnz .LBB0_1058
	v_mul_f32_e32 v0, 0xbfb8aa3b, v8
	v_mul_f32_e32 v1, 0xbfb8aa3b, v9
	v_mul_f32_e32 v2, 0xbfb8aa3b, v10
	v_mul_f32_e32 v3, 0xbfb8aa3b, v11
	v_mul_f32_e32 v4, 0xbfb8aa3b, v28
	v_mul_f32_e32 v5, 0xbfb8aa3b, v29
	v_exp_f32_e32 v0, v0
	v_exp_f32_e32 v1, v1
	v_exp_f32_e32 v2, v2
	v_exp_f32_e32 v3, v3
	v_exp_f32_e32 v4, v4
	v_exp_f32_e32 v5, v5
	v_mul_f32_e32 v6, 0xbfb8aa3b, v30
	v_mul_f32_e32 v7, 0xbfb8aa3b, v31
	v_exp_f32_e32 v6, v6
	v_exp_f32_e32 v7, v7
	v_add_f32_e32 v0, 1.0, v0
	v_add_f32_e32 v1, 1.0, v1
	v_add_f32_e32 v2, 1.0, v2
	v_add_f32_e32 v3, 1.0, v3
	v_add_f32_e32 v4, 1.0, v4
	v_add_f32_e32 v5, 1.0, v5
	v_rcp_f32_e32 v0, v0
	v_rcp_f32_e32 v1, v1
	v_rcp_f32_e32 v2, v2
	v_rcp_f32_e32 v3, v3
	v_rcp_f32_e32 v4, v4
	v_rcp_f32_e32 v5, v5
	v_add_f32_e32 v6, 1.0, v6
	v_add_f32_e32 v7, 1.0, v7
	v_rcp_f32_e32 v6, v6
	v_rcp_f32_e32 v7, v7
	v_pk_mul_f32 v[0:1], v[8:9], v[0:1]
	v_pk_mul_f32 v[2:3], v[10:11], v[2:3]
	v_pk_mul_f32 v[4:5], v[28:29], v[4:5]
	s_lshl_b32 s48, s95, 8
	v_cvt_pk_bf16_f32 v0, v0, v1
	v_cvt_pk_bf16_f32 v1, v2, v3
	v_cvt_pk_bf16_f32 v2, v4, v5
	v_lshl_add_u64 v[4:5], v[18:19], 0, s[48:49]
	v_lshl_add_u64 v[4:5], v[146:147], 1, v[4:5]
	v_pk_mul_f32 v[6:7], v[30:31], v[6:7]
	v_add_co_u32_e32 v4, vcc, 0x811f000, v4
	v_cvt_pk_bf16_f32 v3, v6, v7
	s_nop 0
	v_addc_co_u32_e32 v5, vcc, 0, v5, vcc
	global_store_dwordx4 v[4:5], v[0:3], off offset:2560
	s_mov_b64 s[10:11], 0
	s_branch .LBB0_1072
